# Q/K stored key-fragment-major by a hand-written rope epilogue; attention K/Q loads re-addressed (16 keys of a quarter-wave in 4 lines instead of 16)
# speedup vs baseline: 1.0411x; 1.0119x over previous
;   __device__ __forceinline__ void operator()(f32x4 (&acc)[2][2][4][2], int brow, int bcol, int wr, int wc, int fr, int fq) const {
;     ...
;     if (nt < 4) {
;       u16* dst = (u16*)(outb + (nt < 2 ? OUT_QD : OUT_KD));
;       float sc = nt < 2 ? 0.125f * 1.4426950408889634f : 1.f;
;       int cbase = (nt & 1) * 256;
;       const float2* rope = (const float2*)(p.ws + OFF_ROPE);
;       int posmask = brow < NT_P ? 4095 : 8191;
;       bool rot = (wc & 1) == 0;
;       float2 csc[4], csn[4];
; #pragma unroll
;       for (int j = 0; j < 4; ++j) csc[j] = rope[((brow + wr * 64 + fq * 4 + j) & posmask) * 8 + (fr & 7)];
; #pragma unroll
;       for (int ch = 0; ch < 8; ++ch) {
;         const int ai = ch >> 2, m = ch & 3;
;         int row0 = brow + ai * 128 + wr * 64 + m * 16 + fq * 4;
;         if (ch + 1 < 8) {
;           int rown = brow + ((ch + 1) >> 2) * 128 + wr * 64 + ((ch + 1) & 3) * 16 + fq * 4;
; #pragma unroll
;           for (int j = 0; j < 4; ++j) csn[j] = rope[((rown + j) & posmask) * 8 + (fr & 7)];
;         }
;         __builtin_amdgcn_sched_barrier(0);
;         float4 r4 = rsq[ai][m];
;         float rr[4] = {r4.x * sc, r4.y * sc, r4.z * sc, r4.w * sc};
;         float va[2][4], vb[2][4];
; #pragma unroll
;         for (int j = 0; j < 4; ++j) {
;           float2 cs = csc[j];
; #pragma unroll
;           for (int bj = 0; bj < 2; ++bj) {
;             float v = acc[ai][bj][m][0][j];
;             float pr = dpp_f<0x128>(v);
;             float sg = (fr < 8) ? -pr : pr;
;             float vr = v * cs.x + sg * cs.y;
;             v = rot ? vr : v;
;             va[bj][j] = v * rr[j];
;             vb[bj][j] = acc[ai][bj][m][1][j] * rr[j];
;           }
;         }
; #pragma unroll
;         for (int bj = 0; bj < 2; ++bj) {
;           int c = cbase + bj * 128 + wc * 32 + fr;
;           store_rm4(dst, 512, row0, c, va[bj][0], va[bj][1], va[bj][2], va[bj][3], fr & 1);
;           store_rm4(dst, 512, row0, c + 16, vb[bj][0], vb[bj][1], vb[bj][2], vb[bj][3], fr & 1);
;         }
.LBB0_168:
	s_andn2_b64 vcc, exec, s[0:1]
	s_cbranch_vccnz .LBB0_130
	s_cmp_lt_i32 s47, 2
	s_cselect_b32 s4, s88, 0xc000000
	v_mov_b32_e32 v164, 1.0
	s_cbranch_scc0 .Lmy_rope_sc_done
	v_mov_b32_e32 v164, v254
.Lmy_rope_sc_done:
	s_cmp_lt_i32 s60, 0x8000
	s_cselect_b32 s8, s97, 0x1fff
	s_add_u32 s0, s50, s4
	s_addc_u32 s1, s51, 0
	v_add_u32_e32 v186, s60, v166
	v_add_u32_e32 v186, v186, v232
	v_and_b32_e32 v188, 7, v230
	v_lshlrev_b32_e32 v188, 3, v188
	v_and_b32_e32 v217, 1, v230
	v_mov_b32_e32 v190, 0x05040100
	v_mov_b32_e32 v218, 0x03020706
	v_cmp_eq_u32_e32 vcc, 1, v217
	v_and_b32_e32 v184, 14, v230
	s_lshl_b32 s5, s60, 10
	s_add_u32 s0, s0, s5
	s_addc_u32 s1, s1, 0
	v_lshlrev_b32_e32 v184, 1, v184
	v_add_u32_e32 v217, v232, v217
	v_lshl_or_b32 v184, v217, 11, v184
	v_lshl_or_b32 v184, v166, 3, v184
	v_and_b32_e32 v217, 1, v233
	v_lshl_or_b32 v184, v217, 8, v184
	v_lshrrev_b32_e32 v217, 1, v233
	v_lshl_or_b32 v184, v217, 15, v184
	s_and_b32 s5, s47, 1
	s_lshl_b32 s5, s5, 17
	v_or_b32_e32 v184, s5, v184
	s_add_u32 s4, s0, 0x1000
	s_addc_u32 s5, s1, 0
	s_add_u32 s6, s0, 0x10000
	s_addc_u32 s7, s1, 0
	s_add_u32 s98, s4, 0x10000
	s_addc_u32 s99, s5, 0
	v_cndmask_b32_e32 v190, v190, v218, vcc
	v_cmp_gt_u32_e64 s[100:101], 8, v230
	s_bitcmp0_b32 s33, 6
	s_cbranch_scc0 .Lmy_rope_norot
	v_and_b32_e32 v217, s8, v186
	v_lshl_or_b32 v217, v217, 6, v188
	global_load_dwordx2 v[168:169], v217, s[42:43]
	v_add_u32_e32 v217, 1, v186
	v_and_b32_e32 v217, s8, v217
	v_lshl_or_b32 v217, v217, 6, v188
	global_load_dwordx2 v[170:171], v217, s[42:43]
	v_add_u32_e32 v217, 2, v186
	v_and_b32_e32 v217, s8, v217
	v_lshl_or_b32 v217, v217, 6, v188
	global_load_dwordx2 v[172:173], v217, s[42:43]
	v_add_u32_e32 v217, 3, v186
	v_and_b32_e32 v217, s8, v217
	v_lshl_or_b32 v217, v217, 6, v188
	global_load_dwordx2 v[174:175], v217, s[42:43]
	v_add_u32_e32 v217, 16, v186
	v_and_b32_e32 v217, s8, v217
	v_lshl_or_b32 v217, v217, 6, v188
	global_load_dwordx2 v[176:177], v217, s[42:43]
	v_add_u32_e32 v217, 17, v186
	v_and_b32_e32 v217, s8, v217
	v_lshl_or_b32 v217, v217, 6, v188
	global_load_dwordx2 v[178:179], v217, s[42:43]
	v_add_u32_e32 v217, 18, v186
	v_and_b32_e32 v217, s8, v217
	v_lshl_or_b32 v217, v217, 6, v188
	global_load_dwordx2 v[180:181], v217, s[42:43]
	v_add_u32_e32 v217, 19, v186
	v_and_b32_e32 v217, s8, v217
	v_lshl_or_b32 v217, v217, 6, v188
	global_load_dwordx2 v[182:183], v217, s[42:43]
	s_waitcnt vmcnt(8)
	v_mul_f32_e32 v160, v156, v164
	v_mul_f32_e32 v161, v157, v164
	v_mul_f32_e32 v162, v158, v164
	v_mul_f32_e32 v163, v159, v164
	s_waitcnt vmcnt(4)
	v_mov_b32_dpp v167, v136 row_ror:8 row_mask:0xf bank_mask:0xf bound_ctrl:1
	v_mov_b32_dpp v193, v144 row_ror:8 row_mask:0xf bank_mask:0xf bound_ctrl:1
	v_mov_b32_dpp v194, v137 row_ror:8 row_mask:0xf bank_mask:0xf bound_ctrl:1
	v_mov_b32_dpp v195, v145 row_ror:8 row_mask:0xf bank_mask:0xf bound_ctrl:1
	v_mov_b32_dpp v196, v138 row_ror:8 row_mask:0xf bank_mask:0xf bound_ctrl:1
	v_mov_b32_dpp v197, v146 row_ror:8 row_mask:0xf bank_mask:0xf bound_ctrl:1
	v_mov_b32_dpp v198, v139 row_ror:8 row_mask:0xf bank_mask:0xf bound_ctrl:1
	v_mov_b32_dpp v199, v147 row_ror:8 row_mask:0xf bank_mask:0xf bound_ctrl:1
	v_cndmask_b32_e64 v167, v167, -v167, s[100:101]
	v_cndmask_b32_e64 v193, v193, -v193, s[100:101]
	v_cndmask_b32_e64 v194, v194, -v194, s[100:101]
	v_cndmask_b32_e64 v195, v195, -v195, s[100:101]
	v_cndmask_b32_e64 v196, v196, -v196, s[100:101]
	v_cndmask_b32_e64 v197, v197, -v197, s[100:101]
	v_cndmask_b32_e64 v198, v198, -v198, s[100:101]
	v_cndmask_b32_e64 v199, v199, -v199, s[100:101]
	v_mul_f32_e32 v167, v167, v169
	v_mul_f32_e32 v193, v193, v169
	v_mul_f32_e32 v194, v194, v171
	v_mul_f32_e32 v195, v195, v171
	v_mul_f32_e32 v196, v196, v173
	v_mul_f32_e32 v197, v197, v173
	v_mul_f32_e32 v198, v198, v175
	v_mul_f32_e32 v199, v199, v175
	v_mul_f32_e32 v136, v136, v168
	v_mul_f32_e32 v144, v144, v168
	v_mul_f32_e32 v137, v137, v170
	v_mul_f32_e32 v145, v145, v170
	v_mul_f32_e32 v138, v138, v172
	v_mul_f32_e32 v146, v146, v172
	v_mul_f32_e32 v139, v139, v174
	v_mul_f32_e32 v147, v147, v174
	v_add_f32_e32 v136, v136, v167
	v_add_f32_e32 v144, v144, v193
	v_add_f32_e32 v137, v137, v194
	v_add_f32_e32 v145, v145, v195
	v_add_f32_e32 v138, v138, v196
	v_add_f32_e32 v146, v146, v197
	v_add_f32_e32 v139, v139, v198
	v_add_f32_e32 v147, v147, v199
	v_mul_f32_e32 v136, v160, v136
	v_mul_f32_e32 v137, v161, v137
	v_mul_f32_e32 v138, v162, v138
	v_mul_f32_e32 v139, v163, v139
	v_mul_f32_e32 v144, v160, v144
	v_mul_f32_e32 v145, v161, v145
	v_mul_f32_e32 v146, v162, v146
	v_mul_f32_e32 v147, v163, v147
	v_mul_f32_e32 v140, v140, v160
	v_mul_f32_e32 v141, v141, v161
	v_mul_f32_e32 v142, v142, v162
	v_mul_f32_e32 v143, v143, v163
	v_mul_f32_e32 v148, v148, v160
	v_mul_f32_e32 v149, v149, v161
	v_mul_f32_e32 v150, v150, v162
	v_mul_f32_e32 v151, v151, v163
	v_cvt_pk_bf16_f32 v200, v136, v137
	v_cvt_pk_bf16_f32 v201, v138, v139
	v_cvt_pk_bf16_f32 v202, v140, v141
	v_cvt_pk_bf16_f32 v203, v142, v143
	v_cvt_pk_bf16_f32 v204, v144, v145
	v_cvt_pk_bf16_f32 v205, v146, v147
	v_cvt_pk_bf16_f32 v206, v148, v149
	v_cvt_pk_bf16_f32 v207, v150, v151
	v_mov_b32_dpp v208, v200 quad_perm:[1,0,3,2] row_mask:0xf bank_mask:0xf bound_ctrl:1
	v_mov_b32_dpp v209, v201 quad_perm:[1,0,3,2] row_mask:0xf bank_mask:0xf bound_ctrl:1
	v_mov_b32_dpp v210, v202 quad_perm:[1,0,3,2] row_mask:0xf bank_mask:0xf bound_ctrl:1
	v_mov_b32_dpp v211, v203 quad_perm:[1,0,3,2] row_mask:0xf bank_mask:0xf bound_ctrl:1
	v_mov_b32_dpp v212, v204 quad_perm:[1,0,3,2] row_mask:0xf bank_mask:0xf bound_ctrl:1
	v_mov_b32_dpp v213, v205 quad_perm:[1,0,3,2] row_mask:0xf bank_mask:0xf bound_ctrl:1
; __device__ __forceinline__ void store_rm4(u16* dst, size_t ld, int row0, int c, float v0, float v1, float v2, float v3, bool odd) {
;   {
;     float s = odd ? v0 : v1, r = dpp_swap1(s);
;     float lo = odd ? r : v0, hi = odd ? v1 : r;
;     *(unsigned*)(dst + (size_t)(row0 + (odd ? 1 : 0)) * ld + (c - (odd ? 1 : 0))) = pack2(lo, hi);
;   }
;   {
;     float s = odd ? v2 : v3, r = dpp_swap1(s);
;     float lo = odd ? r : v2, hi = odd ? v3 : r;
;     *(unsigned*)(dst + (size_t)(row0 + 2 + (odd ? 1 : 0)) * ld + (c - (odd ? 1 : 0))) = pack2(lo, hi);
;   }
; }
;   __device__ __forceinline__ void operator()(f32x4 (&acc)[2][2][4][2], int brow, int bcol, int wr, int wc, int fr, int fq) const {
;     ...
;       for (int ch = 0; ch < 8; ++ch) {
;         const int ai = ch >> 2, m = ch & 3;
;         int row0 = brow + ai * 128 + wr * 64 + m * 16 + fq * 4;
;         if (ch + 1 < 8) {
;           int rown = brow + ((ch + 1) >> 2) * 128 + wr * 64 + ((ch + 1) & 3) * 16 + fq * 4;
; #pragma unroll
;           for (int j = 0; j < 4; ++j) csn[j] = rope[((rown + j) & posmask) * 8 + (fr & 7)];
;         }
;         __builtin_amdgcn_sched_barrier(0);
;         float4 r4 = rsq[ai][m];
;         float rr[4] = {r4.x * sc, r4.y * sc, r4.z * sc, r4.w * sc};
;         float va[2][4], vb[2][4];
; #pragma unroll
;         for (int j = 0; j < 4; ++j) {
;           float2 cs = csc[j];
; #pragma unroll
;           for (int bj = 0; bj < 2; ++bj) {
;             float v = acc[ai][bj][m][0][j];
;             float pr = dpp_f<0x128>(v);
;             float sg = (fr < 8) ? -pr : pr;
;             float vr = v * cs.x + sg * cs.y;
;             v = rot ? vr : v;
;             va[bj][j] = v * rr[j];
;             vb[bj][j] = acc[ai][bj][m][1][j] * rr[j];
;           }
;         }
; #pragma unroll
;         for (int bj = 0; bj < 2; ++bj) {
;           int c = cbase + bj * 128 + wc * 32 + fr;
;           store_rm4(dst, 512, row0, c, va[bj][0], va[bj][1], va[bj][2], va[bj][3], fr & 1);
;           store_rm4(dst, 512, row0, c + 16, vb[bj][0], vb[bj][1], vb[bj][2], vb[bj][3], fr & 1);
;         }
	v_mov_b32_dpp v214, v206 quad_perm:[1,0,3,2] row_mask:0xf bank_mask:0xf bound_ctrl:1
	v_mov_b32_dpp v215, v207 quad_perm:[1,0,3,2] row_mask:0xf bank_mask:0xf bound_ctrl:1
	v_perm_b32 v200, v208, v200, v190
	v_perm_b32 v201, v209, v201, v190
	v_perm_b32 v202, v210, v202, v190
	v_perm_b32 v203, v211, v203, v190
	v_perm_b32 v204, v212, v204, v190
	v_perm_b32 v205, v213, v205, v190
	v_perm_b32 v206, v214, v206, v190
	v_perm_b32 v207, v215, v207, v190
	global_store_dword v184, v200, s[0:1]
	global_store_dword v184, v201, s[4:5]
	global_store_dword v184, v202, s[0:1] offset:128
	global_store_dword v184, v203, s[4:5] offset:128
	global_store_dword v184, v204, s[6:7]
	global_store_dword v184, v205, s[98:99]
	global_store_dword v184, v206, s[6:7] offset:128
	global_store_dword v184, v207, s[98:99] offset:128
	v_add_u32_e32 v217, 32, v186
	v_and_b32_e32 v217, s8, v217
	v_lshl_or_b32 v217, v217, 6, v188
	global_load_dwordx2 v[168:169], v217, s[42:43]
	v_add_u32_e32 v217, 33, v186
	v_and_b32_e32 v217, s8, v217
	v_lshl_or_b32 v217, v217, 6, v188
	global_load_dwordx2 v[170:171], v217, s[42:43]
	v_add_u32_e32 v217, 34, v186
	v_and_b32_e32 v217, s8, v217
	v_lshl_or_b32 v217, v217, 6, v188
	global_load_dwordx2 v[172:173], v217, s[42:43]
	v_add_u32_e32 v217, 35, v186
	v_and_b32_e32 v217, s8, v217
	v_lshl_or_b32 v217, v217, 6, v188
	global_load_dwordx2 v[174:175], v217, s[42:43]
	v_mul_f32_e32 v160, v152, v164
	v_mul_f32_e32 v161, v153, v164
	v_mul_f32_e32 v162, v154, v164
	v_mul_f32_e32 v163, v155, v164
	s_waitcnt vmcnt(12)
	v_mov_b32_dpp v167, v116 row_ror:8 row_mask:0xf bank_mask:0xf bound_ctrl:1
	v_mov_b32_dpp v193, v124 row_ror:8 row_mask:0xf bank_mask:0xf bound_ctrl:1
	v_mov_b32_dpp v194, v117 row_ror:8 row_mask:0xf bank_mask:0xf bound_ctrl:1
	v_mov_b32_dpp v195, v125 row_ror:8 row_mask:0xf bank_mask:0xf bound_ctrl:1
	v_mov_b32_dpp v196, v118 row_ror:8 row_mask:0xf bank_mask:0xf bound_ctrl:1
	v_mov_b32_dpp v197, v126 row_ror:8 row_mask:0xf bank_mask:0xf bound_ctrl:1
	v_mov_b32_dpp v198, v119 row_ror:8 row_mask:0xf bank_mask:0xf bound_ctrl:1
	v_mov_b32_dpp v199, v127 row_ror:8 row_mask:0xf bank_mask:0xf bound_ctrl:1
	v_cndmask_b32_e64 v167, v167, -v167, s[100:101]
	v_cndmask_b32_e64 v193, v193, -v193, s[100:101]
	v_cndmask_b32_e64 v194, v194, -v194, s[100:101]
	v_cndmask_b32_e64 v195, v195, -v195, s[100:101]
	v_cndmask_b32_e64 v196, v196, -v196, s[100:101]
	v_cndmask_b32_e64 v197, v197, -v197, s[100:101]
	v_cndmask_b32_e64 v198, v198, -v198, s[100:101]
	v_cndmask_b32_e64 v199, v199, -v199, s[100:101]
	v_mul_f32_e32 v167, v167, v177
	v_mul_f32_e32 v193, v193, v177
	v_mul_f32_e32 v194, v194, v179
	v_mul_f32_e32 v195, v195, v179
	v_mul_f32_e32 v196, v196, v181
	v_mul_f32_e32 v197, v197, v181
	v_mul_f32_e32 v198, v198, v183
	v_mul_f32_e32 v199, v199, v183
	v_mul_f32_e32 v116, v116, v176
	v_mul_f32_e32 v124, v124, v176
	v_mul_f32_e32 v117, v117, v178
	v_mul_f32_e32 v125, v125, v178
	v_mul_f32_e32 v118, v118, v180
	v_mul_f32_e32 v126, v126, v180
	v_mul_f32_e32 v119, v119, v182
	v_mul_f32_e32 v127, v127, v182
	v_add_f32_e32 v116, v116, v167
	v_add_f32_e32 v124, v124, v193
	v_add_f32_e32 v117, v117, v194
	v_add_f32_e32 v125, v125, v195
	v_add_f32_e32 v118, v118, v196
	v_add_f32_e32 v126, v126, v197
	v_add_f32_e32 v119, v119, v198
	v_add_f32_e32 v127, v127, v199
	v_mul_f32_e32 v116, v160, v116
	v_mul_f32_e32 v117, v161, v117
	v_mul_f32_e32 v118, v162, v118
	v_mul_f32_e32 v119, v163, v119
	v_mul_f32_e32 v124, v160, v124
	v_mul_f32_e32 v125, v161, v125
	v_mul_f32_e32 v126, v162, v126
	v_mul_f32_e32 v127, v163, v127
	v_mul_f32_e32 v120, v120, v160
	v_mul_f32_e32 v121, v121, v161
	v_mul_f32_e32 v122, v122, v162
	v_mul_f32_e32 v123, v123, v163
	v_mul_f32_e32 v128, v128, v160
	v_mul_f32_e32 v129, v129, v161
	v_mul_f32_e32 v130, v130, v162
	v_mul_f32_e32 v131, v131, v163
	v_cvt_pk_bf16_f32 v200, v116, v117
	v_cvt_pk_bf16_f32 v201, v118, v119
	v_cvt_pk_bf16_f32 v202, v120, v121
	v_cvt_pk_bf16_f32 v203, v122, v123
	v_cvt_pk_bf16_f32 v204, v124, v125
	v_cvt_pk_bf16_f32 v205, v126, v127
	v_cvt_pk_bf16_f32 v206, v128, v129
	v_cvt_pk_bf16_f32 v207, v130, v131
	v_mov_b32_dpp v208, v200 quad_perm:[1,0,3,2] row_mask:0xf bank_mask:0xf bound_ctrl:1
	v_mov_b32_dpp v209, v201 quad_perm:[1,0,3,2] row_mask:0xf bank_mask:0xf bound_ctrl:1
	v_mov_b32_dpp v210, v202 quad_perm:[1,0,3,2] row_mask:0xf bank_mask:0xf bound_ctrl:1
	v_mov_b32_dpp v211, v203 quad_perm:[1,0,3,2] row_mask:0xf bank_mask:0xf bound_ctrl:1
	v_mov_b32_dpp v212, v204 quad_perm:[1,0,3,2] row_mask:0xf bank_mask:0xf bound_ctrl:1
	v_mov_b32_dpp v213, v205 quad_perm:[1,0,3,2] row_mask:0xf bank_mask:0xf bound_ctrl:1
	v_mov_b32_dpp v214, v206 quad_perm:[1,0,3,2] row_mask:0xf bank_mask:0xf bound_ctrl:1
	v_mov_b32_dpp v215, v207 quad_perm:[1,0,3,2] row_mask:0xf bank_mask:0xf bound_ctrl:1
	v_perm_b32 v200, v208, v200, v190
	v_perm_b32 v201, v209, v201, v190
	v_perm_b32 v202, v210, v202, v190
	v_perm_b32 v203, v211, v203, v190
	v_perm_b32 v204, v212, v204, v190
	v_perm_b32 v205, v213, v205, v190
	v_perm_b32 v206, v214, v206, v190
	v_perm_b32 v207, v215, v207, v190
	global_store_dword v184, v200, s[0:1] offset:32
	global_store_dword v184, v201, s[4:5] offset:32
	global_store_dword v184, v202, s[0:1] offset:160
	global_store_dword v184, v203, s[4:5] offset:160
	global_store_dword v184, v204, s[6:7] offset:32
	global_store_dword v184, v205, s[98:99] offset:32
	global_store_dword v184, v206, s[6:7] offset:160
	global_store_dword v184, v207, s[98:99] offset:160
	v_add_u32_e32 v217, 48, v186
	v_and_b32_e32 v217, s8, v217
	v_lshl_or_b32 v217, v217, 6, v188
	global_load_dwordx2 v[176:177], v217, s[42:43]
	v_add_u32_e32 v217, 49, v186
	v_and_b32_e32 v217, s8, v217
	v_lshl_or_b32 v217, v217, 6, v188
	global_load_dwordx2 v[178:179], v217, s[42:43]
	v_add_u32_e32 v217, 50, v186
	v_and_b32_e32 v217, s8, v217
	v_lshl_or_b32 v217, v217, 6, v188
	global_load_dwordx2 v[180:181], v217, s[42:43]
	v_add_u32_e32 v217, 51, v186
	v_and_b32_e32 v217, s8, v217
	v_lshl_or_b32 v217, v217, 6, v188
	global_load_dwordx2 v[182:183], v217, s[42:43]
	v_mul_f32_e32 v160, v132, v164
	v_mul_f32_e32 v161, v133, v164
	v_mul_f32_e32 v162, v134, v164
	v_mul_f32_e32 v163, v135, v164
	s_waitcnt vmcnt(12)
; __device__ __forceinline__ void store_rm4(u16* dst, size_t ld, int row0, int c, float v0, float v1, float v2, float v3, bool odd) {
;   {
;     float s = odd ? v0 : v1, r = dpp_swap1(s);
;     float lo = odd ? r : v0, hi = odd ? v1 : r;
;     *(unsigned*)(dst + (size_t)(row0 + (odd ? 1 : 0)) * ld + (c - (odd ? 1 : 0))) = pack2(lo, hi);
;   }
;   {
;     float s = odd ? v2 : v3, r = dpp_swap1(s);
;     float lo = odd ? r : v2, hi = odd ? v3 : r;
;     *(unsigned*)(dst + (size_t)(row0 + 2 + (odd ? 1 : 0)) * ld + (c - (odd ? 1 : 0))) = pack2(lo, hi);
;   }
; }
;   __device__ __forceinline__ void operator()(f32x4 (&acc)[2][2][4][2], int brow, int bcol, int wr, int wc, int fr, int fq) const {
;     ...
;       for (int ch = 0; ch < 8; ++ch) {
;         const int ai = ch >> 2, m = ch & 3;
;         int row0 = brow + ai * 128 + wr * 64 + m * 16 + fq * 4;
;         if (ch + 1 < 8) {
;           int rown = brow + ((ch + 1) >> 2) * 128 + wr * 64 + ((ch + 1) & 3) * 16 + fq * 4;
; #pragma unroll
;           for (int j = 0; j < 4; ++j) csn[j] = rope[((rown + j) & posmask) * 8 + (fr & 7)];
;         }
;         __builtin_amdgcn_sched_barrier(0);
;         float4 r4 = rsq[ai][m];
;         float rr[4] = {r4.x * sc, r4.y * sc, r4.z * sc, r4.w * sc};
;         float va[2][4], vb[2][4];
; #pragma unroll
;         for (int j = 0; j < 4; ++j) {
;           float2 cs = csc[j];
; #pragma unroll
;           for (int bj = 0; bj < 2; ++bj) {
;             float v = acc[ai][bj][m][0][j];
;             float pr = dpp_f<0x128>(v);
;             float sg = (fr < 8) ? -pr : pr;
;             float vr = v * cs.x + sg * cs.y;
;             v = rot ? vr : v;
;             va[bj][j] = v * rr[j];
;             vb[bj][j] = acc[ai][bj][m][1][j] * rr[j];
;           }
;         }
; #pragma unroll
;         for (int bj = 0; bj < 2; ++bj) {
;           int c = cbase + bj * 128 + wc * 32 + fr;
;           store_rm4(dst, 512, row0, c, va[bj][0], va[bj][1], va[bj][2], va[bj][3], fr & 1);
;           store_rm4(dst, 512, row0, c + 16, vb[bj][0], vb[bj][1], vb[bj][2], vb[bj][3], fr & 1);
;         }
	v_mov_b32_dpp v167, v96 row_ror:8 row_mask:0xf bank_mask:0xf bound_ctrl:1
	v_mov_b32_dpp v193, v104 row_ror:8 row_mask:0xf bank_mask:0xf bound_ctrl:1
	v_mov_b32_dpp v194, v97 row_ror:8 row_mask:0xf bank_mask:0xf bound_ctrl:1
	v_mov_b32_dpp v195, v105 row_ror:8 row_mask:0xf bank_mask:0xf bound_ctrl:1
	v_mov_b32_dpp v196, v98 row_ror:8 row_mask:0xf bank_mask:0xf bound_ctrl:1
	v_mov_b32_dpp v197, v106 row_ror:8 row_mask:0xf bank_mask:0xf bound_ctrl:1
	v_mov_b32_dpp v198, v99 row_ror:8 row_mask:0xf bank_mask:0xf bound_ctrl:1
	v_mov_b32_dpp v199, v107 row_ror:8 row_mask:0xf bank_mask:0xf bound_ctrl:1
	v_cndmask_b32_e64 v167, v167, -v167, s[100:101]
	v_cndmask_b32_e64 v193, v193, -v193, s[100:101]
	v_cndmask_b32_e64 v194, v194, -v194, s[100:101]
	v_cndmask_b32_e64 v195, v195, -v195, s[100:101]
	v_cndmask_b32_e64 v196, v196, -v196, s[100:101]
	v_cndmask_b32_e64 v197, v197, -v197, s[100:101]
	v_cndmask_b32_e64 v198, v198, -v198, s[100:101]
	v_cndmask_b32_e64 v199, v199, -v199, s[100:101]
	v_mul_f32_e32 v167, v167, v169
	v_mul_f32_e32 v193, v193, v169
	v_mul_f32_e32 v194, v194, v171
	v_mul_f32_e32 v195, v195, v171
	v_mul_f32_e32 v196, v196, v173
	v_mul_f32_e32 v197, v197, v173
	v_mul_f32_e32 v198, v198, v175
	v_mul_f32_e32 v199, v199, v175
	v_mul_f32_e32 v96, v96, v168
	v_mul_f32_e32 v104, v104, v168
	v_mul_f32_e32 v97, v97, v170
	v_mul_f32_e32 v105, v105, v170
	v_mul_f32_e32 v98, v98, v172
	v_mul_f32_e32 v106, v106, v172
	v_mul_f32_e32 v99, v99, v174
	v_mul_f32_e32 v107, v107, v174
	v_add_f32_e32 v96, v96, v167
	v_add_f32_e32 v104, v104, v193
	v_add_f32_e32 v97, v97, v194
	v_add_f32_e32 v105, v105, v195
	v_add_f32_e32 v98, v98, v196
	v_add_f32_e32 v106, v106, v197
	v_add_f32_e32 v99, v99, v198
	v_add_f32_e32 v107, v107, v199
	v_mul_f32_e32 v96, v160, v96
	v_mul_f32_e32 v97, v161, v97
	v_mul_f32_e32 v98, v162, v98
	v_mul_f32_e32 v99, v163, v99
	v_mul_f32_e32 v104, v160, v104
	v_mul_f32_e32 v105, v161, v105
	v_mul_f32_e32 v106, v162, v106
	v_mul_f32_e32 v107, v163, v107
	v_mul_f32_e32 v100, v100, v160
	v_mul_f32_e32 v101, v101, v161
	v_mul_f32_e32 v102, v102, v162
	v_mul_f32_e32 v103, v103, v163
	v_mul_f32_e32 v108, v108, v160
	v_mul_f32_e32 v109, v109, v161
	v_mul_f32_e32 v110, v110, v162
	v_mul_f32_e32 v111, v111, v163
	v_cvt_pk_bf16_f32 v200, v96, v97
	v_cvt_pk_bf16_f32 v201, v98, v99
	v_cvt_pk_bf16_f32 v202, v100, v101
	v_cvt_pk_bf16_f32 v203, v102, v103
	v_cvt_pk_bf16_f32 v204, v104, v105
	v_cvt_pk_bf16_f32 v205, v106, v107
	v_cvt_pk_bf16_f32 v206, v108, v109
	v_cvt_pk_bf16_f32 v207, v110, v111
	v_mov_b32_dpp v208, v200 quad_perm:[1,0,3,2] row_mask:0xf bank_mask:0xf bound_ctrl:1
	v_mov_b32_dpp v209, v201 quad_perm:[1,0,3,2] row_mask:0xf bank_mask:0xf bound_ctrl:1
	v_mov_b32_dpp v210, v202 quad_perm:[1,0,3,2] row_mask:0xf bank_mask:0xf bound_ctrl:1
	v_mov_b32_dpp v211, v203 quad_perm:[1,0,3,2] row_mask:0xf bank_mask:0xf bound_ctrl:1
	v_mov_b32_dpp v212, v204 quad_perm:[1,0,3,2] row_mask:0xf bank_mask:0xf bound_ctrl:1
	v_mov_b32_dpp v213, v205 quad_perm:[1,0,3,2] row_mask:0xf bank_mask:0xf bound_ctrl:1
	v_mov_b32_dpp v214, v206 quad_perm:[1,0,3,2] row_mask:0xf bank_mask:0xf bound_ctrl:1
	v_mov_b32_dpp v215, v207 quad_perm:[1,0,3,2] row_mask:0xf bank_mask:0xf bound_ctrl:1
	v_perm_b32 v200, v208, v200, v190
	v_perm_b32 v201, v209, v201, v190
	v_perm_b32 v202, v210, v202, v190
	v_perm_b32 v203, v211, v203, v190
	v_perm_b32 v204, v212, v204, v190
	v_perm_b32 v205, v213, v205, v190
	v_perm_b32 v206, v214, v206, v190
	v_perm_b32 v207, v215, v207, v190
	global_store_dword v184, v200, s[0:1] offset:64
	global_store_dword v184, v201, s[4:5] offset:64
	global_store_dword v184, v202, s[0:1] offset:192
	global_store_dword v184, v203, s[4:5] offset:192
	global_store_dword v184, v204, s[6:7] offset:64
	global_store_dword v184, v205, s[98:99] offset:64
	global_store_dword v184, v206, s[6:7] offset:192
	global_store_dword v184, v207, s[98:99] offset:192
	v_add_u32_e32 v217, 0x80, v186
	v_and_b32_e32 v217, s8, v217
	v_lshl_or_b32 v217, v217, 6, v188
	global_load_dwordx2 v[168:169], v217, s[42:43]
	v_add_u32_e32 v217, 0x81, v186
	v_and_b32_e32 v217, s8, v217
	v_lshl_or_b32 v217, v217, 6, v188
	global_load_dwordx2 v[170:171], v217, s[42:43]
	v_add_u32_e32 v217, 0x82, v186
	v_and_b32_e32 v217, s8, v217
	v_lshl_or_b32 v217, v217, 6, v188
	global_load_dwordx2 v[172:173], v217, s[42:43]
	v_add_u32_e32 v217, 0x83, v186
	v_and_b32_e32 v217, s8, v217
	v_lshl_or_b32 v217, v217, 6, v188
	global_load_dwordx2 v[174:175], v217, s[42:43]
	v_mul_f32_e32 v160, v112, v164
	v_mul_f32_e32 v161, v113, v164
	v_mul_f32_e32 v162, v114, v164
	v_mul_f32_e32 v163, v115, v164
	s_waitcnt vmcnt(12)
; __device__ __forceinline__ void store_rm4(u16* dst, size_t ld, int row0, int c, float v0, float v1, float v2, float v3, bool odd) {
;   {
;     float s = odd ? v0 : v1, r = dpp_swap1(s);
;     float lo = odd ? r : v0, hi = odd ? v1 : r;
;     *(unsigned*)(dst + (size_t)(row0 + (odd ? 1 : 0)) * ld + (c - (odd ? 1 : 0))) = pack2(lo, hi);
;   }
;   {
;     float s = odd ? v2 : v3, r = dpp_swap1(s);
;     float lo = odd ? r : v2, hi = odd ? v3 : r;
;     *(unsigned*)(dst + (size_t)(row0 + 2 + (odd ? 1 : 0)) * ld + (c - (odd ? 1 : 0))) = pack2(lo, hi);
;   }
; }
;   __device__ __forceinline__ void operator()(f32x4 (&acc)[2][2][4][2], int brow, int bcol, int wr, int wc, int fr, int fq) const {
;     ...
;       for (int ch = 0; ch < 8; ++ch) {
;         const int ai = ch >> 2, m = ch & 3;
;         int row0 = brow + ai * 128 + wr * 64 + m * 16 + fq * 4;
;         if (ch + 1 < 8) {
;           int rown = brow + ((ch + 1) >> 2) * 128 + wr * 64 + ((ch + 1) & 3) * 16 + fq * 4;
; #pragma unroll
;           for (int j = 0; j < 4; ++j) csn[j] = rope[((rown + j) & posmask) * 8 + (fr & 7)];
;         }
;         __builtin_amdgcn_sched_barrier(0);
;         float4 r4 = rsq[ai][m];
;         float rr[4] = {r4.x * sc, r4.y * sc, r4.z * sc, r4.w * sc};
;         float va[2][4], vb[2][4];
; #pragma unroll
;         for (int j = 0; j < 4; ++j) {
;           float2 cs = csc[j];
; #pragma unroll
;           for (int bj = 0; bj < 2; ++bj) {
;             float v = acc[ai][bj][m][0][j];
;             float pr = dpp_f<0x128>(v);
;             float sg = (fr < 8) ? -pr : pr;
;             float vr = v * cs.x + sg * cs.y;
;             v = rot ? vr : v;
;             va[bj][j] = v * rr[j];
;             vb[bj][j] = acc[ai][bj][m][1][j] * rr[j];
;           }
;         }
; #pragma unroll
;         for (int bj = 0; bj < 2; ++bj) {
;           int c = cbase + bj * 128 + wc * 32 + fr;
;           store_rm4(dst, 512, row0, c, va[bj][0], va[bj][1], va[bj][2], va[bj][3], fr & 1);
;           store_rm4(dst, 512, row0, c + 16, vb[bj][0], vb[bj][1], vb[bj][2], vb[bj][3], fr & 1);
;         }
	v_mov_b32_dpp v167, v76 row_ror:8 row_mask:0xf bank_mask:0xf bound_ctrl:1
	v_mov_b32_dpp v193, v84 row_ror:8 row_mask:0xf bank_mask:0xf bound_ctrl:1
	v_mov_b32_dpp v194, v77 row_ror:8 row_mask:0xf bank_mask:0xf bound_ctrl:1
	v_mov_b32_dpp v195, v85 row_ror:8 row_mask:0xf bank_mask:0xf bound_ctrl:1
	v_mov_b32_dpp v196, v78 row_ror:8 row_mask:0xf bank_mask:0xf bound_ctrl:1
	v_mov_b32_dpp v197, v86 row_ror:8 row_mask:0xf bank_mask:0xf bound_ctrl:1
	v_mov_b32_dpp v198, v79 row_ror:8 row_mask:0xf bank_mask:0xf bound_ctrl:1
	v_mov_b32_dpp v199, v87 row_ror:8 row_mask:0xf bank_mask:0xf bound_ctrl:1
	v_cndmask_b32_e64 v167, v167, -v167, s[100:101]
	v_cndmask_b32_e64 v193, v193, -v193, s[100:101]
	v_cndmask_b32_e64 v194, v194, -v194, s[100:101]
	v_cndmask_b32_e64 v195, v195, -v195, s[100:101]
	v_cndmask_b32_e64 v196, v196, -v196, s[100:101]
	v_cndmask_b32_e64 v197, v197, -v197, s[100:101]
	v_cndmask_b32_e64 v198, v198, -v198, s[100:101]
	v_cndmask_b32_e64 v199, v199, -v199, s[100:101]
	v_mul_f32_e32 v167, v167, v177
	v_mul_f32_e32 v193, v193, v177
	v_mul_f32_e32 v194, v194, v179
	v_mul_f32_e32 v195, v195, v179
	v_mul_f32_e32 v196, v196, v181
	v_mul_f32_e32 v197, v197, v181
	v_mul_f32_e32 v198, v198, v183
	v_mul_f32_e32 v199, v199, v183
	v_mul_f32_e32 v76, v76, v176
	v_mul_f32_e32 v84, v84, v176
	v_mul_f32_e32 v77, v77, v178
	v_mul_f32_e32 v85, v85, v178
	v_mul_f32_e32 v78, v78, v180
	v_mul_f32_e32 v86, v86, v180
	v_mul_f32_e32 v79, v79, v182
	v_mul_f32_e32 v87, v87, v182
	v_add_f32_e32 v76, v76, v167
	v_add_f32_e32 v84, v84, v193
	v_add_f32_e32 v77, v77, v194
	v_add_f32_e32 v85, v85, v195
	v_add_f32_e32 v78, v78, v196
	v_add_f32_e32 v86, v86, v197
	v_add_f32_e32 v79, v79, v198
	v_add_f32_e32 v87, v87, v199
	v_mul_f32_e32 v76, v160, v76
	v_mul_f32_e32 v77, v161, v77
	v_mul_f32_e32 v78, v162, v78
	v_mul_f32_e32 v79, v163, v79
	v_mul_f32_e32 v84, v160, v84
	v_mul_f32_e32 v85, v161, v85
	v_mul_f32_e32 v86, v162, v86
	v_mul_f32_e32 v87, v163, v87
	v_mul_f32_e32 v80, v80, v160
	v_mul_f32_e32 v81, v81, v161
	v_mul_f32_e32 v82, v82, v162
	v_mul_f32_e32 v83, v83, v163
	v_mul_f32_e32 v88, v88, v160
	v_mul_f32_e32 v89, v89, v161
	v_mul_f32_e32 v90, v90, v162
	v_mul_f32_e32 v91, v91, v163
	v_cvt_pk_bf16_f32 v200, v76, v77
	v_cvt_pk_bf16_f32 v201, v78, v79
	v_cvt_pk_bf16_f32 v202, v80, v81
	v_cvt_pk_bf16_f32 v203, v82, v83
	v_cvt_pk_bf16_f32 v204, v84, v85
	v_cvt_pk_bf16_f32 v205, v86, v87
	v_cvt_pk_bf16_f32 v206, v88, v89
	v_cvt_pk_bf16_f32 v207, v90, v91
	v_mov_b32_dpp v208, v200 quad_perm:[1,0,3,2] row_mask:0xf bank_mask:0xf bound_ctrl:1
	v_mov_b32_dpp v209, v201 quad_perm:[1,0,3,2] row_mask:0xf bank_mask:0xf bound_ctrl:1
	v_mov_b32_dpp v210, v202 quad_perm:[1,0,3,2] row_mask:0xf bank_mask:0xf bound_ctrl:1
	v_mov_b32_dpp v211, v203 quad_perm:[1,0,3,2] row_mask:0xf bank_mask:0xf bound_ctrl:1
	v_mov_b32_dpp v212, v204 quad_perm:[1,0,3,2] row_mask:0xf bank_mask:0xf bound_ctrl:1
	v_mov_b32_dpp v213, v205 quad_perm:[1,0,3,2] row_mask:0xf bank_mask:0xf bound_ctrl:1
	v_mov_b32_dpp v214, v206 quad_perm:[1,0,3,2] row_mask:0xf bank_mask:0xf bound_ctrl:1
	v_mov_b32_dpp v215, v207 quad_perm:[1,0,3,2] row_mask:0xf bank_mask:0xf bound_ctrl:1
	v_perm_b32 v200, v208, v200, v190
	v_perm_b32 v201, v209, v201, v190
	v_perm_b32 v202, v210, v202, v190
	v_perm_b32 v203, v211, v203, v190
	v_perm_b32 v204, v212, v204, v190
	v_perm_b32 v205, v213, v205, v190
	v_perm_b32 v206, v214, v206, v190
	v_perm_b32 v207, v215, v207, v190
	global_store_dword v184, v200, s[0:1] offset:96
	global_store_dword v184, v201, s[4:5] offset:96
	global_store_dword v184, v202, s[0:1] offset:224
	global_store_dword v184, v203, s[4:5] offset:224
	global_store_dword v184, v204, s[6:7] offset:96
	global_store_dword v184, v205, s[98:99] offset:96
	global_store_dword v184, v206, s[6:7] offset:224
	global_store_dword v184, v207, s[98:99] offset:224
	v_add_u32_e32 v217, 0x90, v186
	v_and_b32_e32 v217, s8, v217
	v_lshl_or_b32 v217, v217, 6, v188
	global_load_dwordx2 v[176:177], v217, s[42:43]
	v_add_u32_e32 v217, 0x91, v186
	v_and_b32_e32 v217, s8, v217
	v_lshl_or_b32 v217, v217, 6, v188
	global_load_dwordx2 v[178:179], v217, s[42:43]
	v_add_u32_e32 v217, 0x92, v186
	v_and_b32_e32 v217, s8, v217
	v_lshl_or_b32 v217, v217, 6, v188
	global_load_dwordx2 v[180:181], v217, s[42:43]
	v_add_u32_e32 v217, 0x93, v186
	v_and_b32_e32 v217, s8, v217
	v_lshl_or_b32 v217, v217, 6, v188
	global_load_dwordx2 v[182:183], v217, s[42:43]
	v_mul_f32_e32 v160, v92, v164
	v_mul_f32_e32 v161, v93, v164
	v_mul_f32_e32 v162, v94, v164
	v_mul_f32_e32 v163, v95, v164
	s_waitcnt vmcnt(12)
; __device__ __forceinline__ void store_rm4(u16* dst, size_t ld, int row0, int c, float v0, float v1, float v2, float v3, bool odd) {
;   {
;     float s = odd ? v0 : v1, r = dpp_swap1(s);
;     float lo = odd ? r : v0, hi = odd ? v1 : r;
;     *(unsigned*)(dst + (size_t)(row0 + (odd ? 1 : 0)) * ld + (c - (odd ? 1 : 0))) = pack2(lo, hi);
;   }
;   {
;     float s = odd ? v2 : v3, r = dpp_swap1(s);
;     float lo = odd ? r : v2, hi = odd ? v3 : r;
;     *(unsigned*)(dst + (size_t)(row0 + 2 + (odd ? 1 : 0)) * ld + (c - (odd ? 1 : 0))) = pack2(lo, hi);
;   }
; }
;   __device__ __forceinline__ void operator()(f32x4 (&acc)[2][2][4][2], int brow, int bcol, int wr, int wc, int fr, int fq) const {
;     ...
;       for (int ch = 0; ch < 8; ++ch) {
;         const int ai = ch >> 2, m = ch & 3;
;         int row0 = brow + ai * 128 + wr * 64 + m * 16 + fq * 4;
;         if (ch + 1 < 8) {
;           int rown = brow + ((ch + 1) >> 2) * 128 + wr * 64 + ((ch + 1) & 3) * 16 + fq * 4;
; #pragma unroll
;           for (int j = 0; j < 4; ++j) csn[j] = rope[((rown + j) & posmask) * 8 + (fr & 7)];
;         }
;         __builtin_amdgcn_sched_barrier(0);
;         float4 r4 = rsq[ai][m];
;         float rr[4] = {r4.x * sc, r4.y * sc, r4.z * sc, r4.w * sc};
;         float va[2][4], vb[2][4];
; #pragma unroll
;         for (int j = 0; j < 4; ++j) {
;           float2 cs = csc[j];
; #pragma unroll
;           for (int bj = 0; bj < 2; ++bj) {
;             float v = acc[ai][bj][m][0][j];
;             float pr = dpp_f<0x128>(v);
;             float sg = (fr < 8) ? -pr : pr;
;             float vr = v * cs.x + sg * cs.y;
;             v = rot ? vr : v;
;             va[bj][j] = v * rr[j];
;             vb[bj][j] = acc[ai][bj][m][1][j] * rr[j];
;           }
;         }
; #pragma unroll
;         for (int bj = 0; bj < 2; ++bj) {
;           int c = cbase + bj * 128 + wc * 32 + fr;
;           store_rm4(dst, 512, row0, c, va[bj][0], va[bj][1], va[bj][2], va[bj][3], fr & 1);
;           store_rm4(dst, 512, row0, c + 16, vb[bj][0], vb[bj][1], vb[bj][2], vb[bj][3], fr & 1);
;         }
	v_mov_b32_dpp v167, v56 row_ror:8 row_mask:0xf bank_mask:0xf bound_ctrl:1
	v_mov_b32_dpp v193, v64 row_ror:8 row_mask:0xf bank_mask:0xf bound_ctrl:1
	v_mov_b32_dpp v194, v57 row_ror:8 row_mask:0xf bank_mask:0xf bound_ctrl:1
	v_mov_b32_dpp v195, v65 row_ror:8 row_mask:0xf bank_mask:0xf bound_ctrl:1
	v_mov_b32_dpp v196, v58 row_ror:8 row_mask:0xf bank_mask:0xf bound_ctrl:1
	v_mov_b32_dpp v197, v66 row_ror:8 row_mask:0xf bank_mask:0xf bound_ctrl:1
	v_mov_b32_dpp v198, v59 row_ror:8 row_mask:0xf bank_mask:0xf bound_ctrl:1
	v_mov_b32_dpp v199, v67 row_ror:8 row_mask:0xf bank_mask:0xf bound_ctrl:1
	v_cndmask_b32_e64 v167, v167, -v167, s[100:101]
	v_cndmask_b32_e64 v193, v193, -v193, s[100:101]
	v_cndmask_b32_e64 v194, v194, -v194, s[100:101]
	v_cndmask_b32_e64 v195, v195, -v195, s[100:101]
	v_cndmask_b32_e64 v196, v196, -v196, s[100:101]
	v_cndmask_b32_e64 v197, v197, -v197, s[100:101]
	v_cndmask_b32_e64 v198, v198, -v198, s[100:101]
	v_cndmask_b32_e64 v199, v199, -v199, s[100:101]
	v_mul_f32_e32 v167, v167, v169
	v_mul_f32_e32 v193, v193, v169
	v_mul_f32_e32 v194, v194, v171
	v_mul_f32_e32 v195, v195, v171
	v_mul_f32_e32 v196, v196, v173
	v_mul_f32_e32 v197, v197, v173
	v_mul_f32_e32 v198, v198, v175
	v_mul_f32_e32 v199, v199, v175
	v_mul_f32_e32 v56, v56, v168
	v_mul_f32_e32 v64, v64, v168
	v_mul_f32_e32 v57, v57, v170
	v_mul_f32_e32 v65, v65, v170
	v_mul_f32_e32 v58, v58, v172
	v_mul_f32_e32 v66, v66, v172
	v_mul_f32_e32 v59, v59, v174
	v_mul_f32_e32 v67, v67, v174
	v_add_f32_e32 v56, v56, v167
	v_add_f32_e32 v64, v64, v193
	v_add_f32_e32 v57, v57, v194
	v_add_f32_e32 v65, v65, v195
	v_add_f32_e32 v58, v58, v196
	v_add_f32_e32 v66, v66, v197
	v_add_f32_e32 v59, v59, v198
	v_add_f32_e32 v67, v67, v199
	v_mul_f32_e32 v56, v160, v56
	v_mul_f32_e32 v57, v161, v57
	v_mul_f32_e32 v58, v162, v58
	v_mul_f32_e32 v59, v163, v59
	v_mul_f32_e32 v64, v160, v64
	v_mul_f32_e32 v65, v161, v65
	v_mul_f32_e32 v66, v162, v66
	v_mul_f32_e32 v67, v163, v67
	v_mul_f32_e32 v60, v60, v160
	v_mul_f32_e32 v61, v61, v161
	v_mul_f32_e32 v62, v62, v162
	v_mul_f32_e32 v63, v63, v163
	v_mul_f32_e32 v68, v68, v160
	v_mul_f32_e32 v69, v69, v161
	v_mul_f32_e32 v70, v70, v162
	v_mul_f32_e32 v71, v71, v163
	v_cvt_pk_bf16_f32 v200, v56, v57
	v_cvt_pk_bf16_f32 v201, v58, v59
	v_cvt_pk_bf16_f32 v202, v60, v61
	v_cvt_pk_bf16_f32 v203, v62, v63
	v_cvt_pk_bf16_f32 v204, v64, v65
	v_cvt_pk_bf16_f32 v205, v66, v67
	v_cvt_pk_bf16_f32 v206, v68, v69
	v_cvt_pk_bf16_f32 v207, v70, v71
	v_mov_b32_dpp v208, v200 quad_perm:[1,0,3,2] row_mask:0xf bank_mask:0xf bound_ctrl:1
	v_mov_b32_dpp v209, v201 quad_perm:[1,0,3,2] row_mask:0xf bank_mask:0xf bound_ctrl:1
	v_mov_b32_dpp v210, v202 quad_perm:[1,0,3,2] row_mask:0xf bank_mask:0xf bound_ctrl:1
	v_mov_b32_dpp v211, v203 quad_perm:[1,0,3,2] row_mask:0xf bank_mask:0xf bound_ctrl:1
	v_mov_b32_dpp v212, v204 quad_perm:[1,0,3,2] row_mask:0xf bank_mask:0xf bound_ctrl:1
	v_mov_b32_dpp v213, v205 quad_perm:[1,0,3,2] row_mask:0xf bank_mask:0xf bound_ctrl:1
	v_mov_b32_dpp v214, v206 quad_perm:[1,0,3,2] row_mask:0xf bank_mask:0xf bound_ctrl:1
	v_mov_b32_dpp v215, v207 quad_perm:[1,0,3,2] row_mask:0xf bank_mask:0xf bound_ctrl:1
	v_perm_b32 v200, v208, v200, v190
	v_perm_b32 v201, v209, v201, v190
	v_perm_b32 v202, v210, v202, v190
	v_perm_b32 v203, v211, v203, v190
	v_perm_b32 v204, v212, v204, v190
	v_perm_b32 v205, v213, v205, v190
	v_perm_b32 v206, v214, v206, v190
	v_perm_b32 v207, v215, v207, v190
	global_store_dword v184, v200, s[0:1] offset:1024
	global_store_dword v184, v201, s[4:5] offset:1024
	global_store_dword v184, v202, s[0:1] offset:1152
	global_store_dword v184, v203, s[4:5] offset:1152
	global_store_dword v184, v204, s[6:7] offset:1024
	global_store_dword v184, v205, s[98:99] offset:1024
	global_store_dword v184, v206, s[6:7] offset:1152
	global_store_dword v184, v207, s[98:99] offset:1152
	v_add_u32_e32 v217, 0xa0, v186
	v_and_b32_e32 v217, s8, v217
	v_lshl_or_b32 v217, v217, 6, v188
	global_load_dwordx2 v[168:169], v217, s[42:43]
	v_add_u32_e32 v217, 0xa1, v186
	v_and_b32_e32 v217, s8, v217
	v_lshl_or_b32 v217, v217, 6, v188
	global_load_dwordx2 v[170:171], v217, s[42:43]
	v_add_u32_e32 v217, 0xa2, v186
	v_and_b32_e32 v217, s8, v217
	v_lshl_or_b32 v217, v217, 6, v188
	global_load_dwordx2 v[172:173], v217, s[42:43]
	v_add_u32_e32 v217, 0xa3, v186
	v_and_b32_e32 v217, s8, v217
	v_lshl_or_b32 v217, v217, 6, v188
	global_load_dwordx2 v[174:175], v217, s[42:43]
	v_mul_f32_e32 v160, v72, v164
	v_mul_f32_e32 v161, v73, v164
	v_mul_f32_e32 v162, v74, v164
	v_mul_f32_e32 v163, v75, v164
	s_waitcnt vmcnt(12)
; __device__ __forceinline__ void store_rm4(u16* dst, size_t ld, int row0, int c, float v0, float v1, float v2, float v3, bool odd) {
;   {
;     float s = odd ? v0 : v1, r = dpp_swap1(s);
;     float lo = odd ? r : v0, hi = odd ? v1 : r;
;     *(unsigned*)(dst + (size_t)(row0 + (odd ? 1 : 0)) * ld + (c - (odd ? 1 : 0))) = pack2(lo, hi);
;   }
;   {
;     float s = odd ? v2 : v3, r = dpp_swap1(s);
;     float lo = odd ? r : v2, hi = odd ? v3 : r;
;     *(unsigned*)(dst + (size_t)(row0 + 2 + (odd ? 1 : 0)) * ld + (c - (odd ? 1 : 0))) = pack2(lo, hi);
;   }
; }
;   __device__ __forceinline__ void operator()(f32x4 (&acc)[2][2][4][2], int brow, int bcol, int wr, int wc, int fr, int fq) const {
;     ...
;       for (int ch = 0; ch < 8; ++ch) {
;         const int ai = ch >> 2, m = ch & 3;
;         int row0 = brow + ai * 128 + wr * 64 + m * 16 + fq * 4;
;         if (ch + 1 < 8) {
;           int rown = brow + ((ch + 1) >> 2) * 128 + wr * 64 + ((ch + 1) & 3) * 16 + fq * 4;
; #pragma unroll
;           for (int j = 0; j < 4; ++j) csn[j] = rope[((rown + j) & posmask) * 8 + (fr & 7)];
;         }
;         __builtin_amdgcn_sched_barrier(0);
;         float4 r4 = rsq[ai][m];
;         float rr[4] = {r4.x * sc, r4.y * sc, r4.z * sc, r4.w * sc};
;         float va[2][4], vb[2][4];
; #pragma unroll
;         for (int j = 0; j < 4; ++j) {
;           float2 cs = csc[j];
; #pragma unroll
;           for (int bj = 0; bj < 2; ++bj) {
;             float v = acc[ai][bj][m][0][j];
;             float pr = dpp_f<0x128>(v);
;             float sg = (fr < 8) ? -pr : pr;
;             float vr = v * cs.x + sg * cs.y;
;             v = rot ? vr : v;
;             va[bj][j] = v * rr[j];
;             vb[bj][j] = acc[ai][bj][m][1][j] * rr[j];
;           }
;         }
; #pragma unroll
;         for (int bj = 0; bj < 2; ++bj) {
;           int c = cbase + bj * 128 + wc * 32 + fr;
;           store_rm4(dst, 512, row0, c, va[bj][0], va[bj][1], va[bj][2], va[bj][3], fr & 1);
;           store_rm4(dst, 512, row0, c + 16, vb[bj][0], vb[bj][1], vb[bj][2], vb[bj][3], fr & 1);
;         }
	v_mov_b32_dpp v167, v36 row_ror:8 row_mask:0xf bank_mask:0xf bound_ctrl:1
	v_mov_b32_dpp v193, v44 row_ror:8 row_mask:0xf bank_mask:0xf bound_ctrl:1
	v_mov_b32_dpp v194, v37 row_ror:8 row_mask:0xf bank_mask:0xf bound_ctrl:1
	v_mov_b32_dpp v195, v45 row_ror:8 row_mask:0xf bank_mask:0xf bound_ctrl:1
	v_mov_b32_dpp v196, v38 row_ror:8 row_mask:0xf bank_mask:0xf bound_ctrl:1
	v_mov_b32_dpp v197, v46 row_ror:8 row_mask:0xf bank_mask:0xf bound_ctrl:1
	v_mov_b32_dpp v198, v39 row_ror:8 row_mask:0xf bank_mask:0xf bound_ctrl:1
	v_mov_b32_dpp v199, v47 row_ror:8 row_mask:0xf bank_mask:0xf bound_ctrl:1
	v_cndmask_b32_e64 v167, v167, -v167, s[100:101]
	v_cndmask_b32_e64 v193, v193, -v193, s[100:101]
	v_cndmask_b32_e64 v194, v194, -v194, s[100:101]
	v_cndmask_b32_e64 v195, v195, -v195, s[100:101]
	v_cndmask_b32_e64 v196, v196, -v196, s[100:101]
	v_cndmask_b32_e64 v197, v197, -v197, s[100:101]
	v_cndmask_b32_e64 v198, v198, -v198, s[100:101]
	v_cndmask_b32_e64 v199, v199, -v199, s[100:101]
	v_mul_f32_e32 v167, v167, v177
	v_mul_f32_e32 v193, v193, v177
	v_mul_f32_e32 v194, v194, v179
	v_mul_f32_e32 v195, v195, v179
	v_mul_f32_e32 v196, v196, v181
	v_mul_f32_e32 v197, v197, v181
	v_mul_f32_e32 v198, v198, v183
	v_mul_f32_e32 v199, v199, v183
	v_mul_f32_e32 v36, v36, v176
	v_mul_f32_e32 v44, v44, v176
	v_mul_f32_e32 v37, v37, v178
	v_mul_f32_e32 v45, v45, v178
	v_mul_f32_e32 v38, v38, v180
	v_mul_f32_e32 v46, v46, v180
	v_mul_f32_e32 v39, v39, v182
	v_mul_f32_e32 v47, v47, v182
	v_add_f32_e32 v36, v36, v167
	v_add_f32_e32 v44, v44, v193
	v_add_f32_e32 v37, v37, v194
	v_add_f32_e32 v45, v45, v195
	v_add_f32_e32 v38, v38, v196
	v_add_f32_e32 v46, v46, v197
	v_add_f32_e32 v39, v39, v198
	v_add_f32_e32 v47, v47, v199
	v_mul_f32_e32 v36, v160, v36
	v_mul_f32_e32 v37, v161, v37
	v_mul_f32_e32 v38, v162, v38
	v_mul_f32_e32 v39, v163, v39
	v_mul_f32_e32 v44, v160, v44
	v_mul_f32_e32 v45, v161, v45
	v_mul_f32_e32 v46, v162, v46
	v_mul_f32_e32 v47, v163, v47
	v_mul_f32_e32 v40, v40, v160
	v_mul_f32_e32 v41, v41, v161
	v_mul_f32_e32 v42, v42, v162
	v_mul_f32_e32 v43, v43, v163
	v_mul_f32_e32 v48, v48, v160
	v_mul_f32_e32 v49, v49, v161
	v_mul_f32_e32 v50, v50, v162
	v_mul_f32_e32 v51, v51, v163
	v_cvt_pk_bf16_f32 v200, v36, v37
	v_cvt_pk_bf16_f32 v201, v38, v39
	v_cvt_pk_bf16_f32 v202, v40, v41
	v_cvt_pk_bf16_f32 v203, v42, v43
	v_cvt_pk_bf16_f32 v204, v44, v45
	v_cvt_pk_bf16_f32 v205, v46, v47
	v_cvt_pk_bf16_f32 v206, v48, v49
	v_cvt_pk_bf16_f32 v207, v50, v51
	v_mov_b32_dpp v208, v200 quad_perm:[1,0,3,2] row_mask:0xf bank_mask:0xf bound_ctrl:1
	v_mov_b32_dpp v209, v201 quad_perm:[1,0,3,2] row_mask:0xf bank_mask:0xf bound_ctrl:1
	v_mov_b32_dpp v210, v202 quad_perm:[1,0,3,2] row_mask:0xf bank_mask:0xf bound_ctrl:1
	v_mov_b32_dpp v211, v203 quad_perm:[1,0,3,2] row_mask:0xf bank_mask:0xf bound_ctrl:1
	v_mov_b32_dpp v212, v204 quad_perm:[1,0,3,2] row_mask:0xf bank_mask:0xf bound_ctrl:1
	v_mov_b32_dpp v213, v205 quad_perm:[1,0,3,2] row_mask:0xf bank_mask:0xf bound_ctrl:1
	v_mov_b32_dpp v214, v206 quad_perm:[1,0,3,2] row_mask:0xf bank_mask:0xf bound_ctrl:1
	v_mov_b32_dpp v215, v207 quad_perm:[1,0,3,2] row_mask:0xf bank_mask:0xf bound_ctrl:1
	v_perm_b32 v200, v208, v200, v190
	v_perm_b32 v201, v209, v201, v190
	v_perm_b32 v202, v210, v202, v190
	v_perm_b32 v203, v211, v203, v190
	v_perm_b32 v204, v212, v204, v190
	v_perm_b32 v205, v213, v205, v190
	v_perm_b32 v206, v214, v206, v190
	v_perm_b32 v207, v215, v207, v190
	global_store_dword v184, v200, s[0:1] offset:1056
	global_store_dword v184, v201, s[4:5] offset:1056
	global_store_dword v184, v202, s[0:1] offset:1184
	global_store_dword v184, v203, s[4:5] offset:1184
	global_store_dword v184, v204, s[6:7] offset:1056
	global_store_dword v184, v205, s[98:99] offset:1056
	global_store_dword v184, v206, s[6:7] offset:1184
	global_store_dword v184, v207, s[98:99] offset:1184
	v_add_u32_e32 v217, 0xb0, v186
	v_and_b32_e32 v217, s8, v217
	v_lshl_or_b32 v217, v217, 6, v188
	global_load_dwordx2 v[176:177], v217, s[42:43]
	v_add_u32_e32 v217, 0xb1, v186
	v_and_b32_e32 v217, s8, v217
	v_lshl_or_b32 v217, v217, 6, v188
	global_load_dwordx2 v[178:179], v217, s[42:43]
	v_add_u32_e32 v217, 0xb2, v186
	v_and_b32_e32 v217, s8, v217
	v_lshl_or_b32 v217, v217, 6, v188
	global_load_dwordx2 v[180:181], v217, s[42:43]
	v_add_u32_e32 v217, 0xb3, v186
	v_and_b32_e32 v217, s8, v217
	v_lshl_or_b32 v217, v217, 6, v188
	global_load_dwordx2 v[182:183], v217, s[42:43]
	v_mul_f32_e32 v160, v52, v164
	v_mul_f32_e32 v161, v53, v164
	v_mul_f32_e32 v162, v54, v164
	v_mul_f32_e32 v163, v55, v164
	s_waitcnt vmcnt(12)
; __device__ __forceinline__ void store_rm4(u16* dst, size_t ld, int row0, int c, float v0, float v1, float v2, float v3, bool odd) {
;   {
;     float s = odd ? v0 : v1, r = dpp_swap1(s);
;     float lo = odd ? r : v0, hi = odd ? v1 : r;
;     *(unsigned*)(dst + (size_t)(row0 + (odd ? 1 : 0)) * ld + (c - (odd ? 1 : 0))) = pack2(lo, hi);
;   }
;   {
;     float s = odd ? v2 : v3, r = dpp_swap1(s);
;     float lo = odd ? r : v2, hi = odd ? v3 : r;
;     *(unsigned*)(dst + (size_t)(row0 + 2 + (odd ? 1 : 0)) * ld + (c - (odd ? 1 : 0))) = pack2(lo, hi);
;   }
; }
;   __device__ __forceinline__ void operator()(f32x4 (&acc)[2][2][4][2], int brow, int bcol, int wr, int wc, int fr, int fq) const {
;     ...
;       for (int ch = 0; ch < 8; ++ch) {
;         const int ai = ch >> 2, m = ch & 3;
;         int row0 = brow + ai * 128 + wr * 64 + m * 16 + fq * 4;
;         if (ch + 1 < 8) {
;           int rown = brow + ((ch + 1) >> 2) * 128 + wr * 64 + ((ch + 1) & 3) * 16 + fq * 4;
; #pragma unroll
;           for (int j = 0; j < 4; ++j) csn[j] = rope[((rown + j) & posmask) * 8 + (fr & 7)];
;         }
;         __builtin_amdgcn_sched_barrier(0);
;         float4 r4 = rsq[ai][m];
;         float rr[4] = {r4.x * sc, r4.y * sc, r4.z * sc, r4.w * sc};
;         float va[2][4], vb[2][4];
; #pragma unroll
;         for (int j = 0; j < 4; ++j) {
;           float2 cs = csc[j];
; #pragma unroll
;           for (int bj = 0; bj < 2; ++bj) {
;             float v = acc[ai][bj][m][0][j];
;             float pr = dpp_f<0x128>(v);
;             float sg = (fr < 8) ? -pr : pr;
;             float vr = v * cs.x + sg * cs.y;
;             v = rot ? vr : v;
;             va[bj][j] = v * rr[j];
;             vb[bj][j] = acc[ai][bj][m][1][j] * rr[j];
;           }
;         }
; #pragma unroll
;         for (int bj = 0; bj < 2; ++bj) {
;           int c = cbase + bj * 128 + wc * 32 + fr;
;           store_rm4(dst, 512, row0, c, va[bj][0], va[bj][1], va[bj][2], va[bj][3], fr & 1);
;           store_rm4(dst, 512, row0, c + 16, vb[bj][0], vb[bj][1], vb[bj][2], vb[bj][3], fr & 1);
;         }
	v_mov_b32_dpp v167, v16 row_ror:8 row_mask:0xf bank_mask:0xf bound_ctrl:1
	v_mov_b32_dpp v193, v24 row_ror:8 row_mask:0xf bank_mask:0xf bound_ctrl:1
	v_mov_b32_dpp v194, v17 row_ror:8 row_mask:0xf bank_mask:0xf bound_ctrl:1
	v_mov_b32_dpp v195, v25 row_ror:8 row_mask:0xf bank_mask:0xf bound_ctrl:1
	v_mov_b32_dpp v196, v18 row_ror:8 row_mask:0xf bank_mask:0xf bound_ctrl:1
	v_mov_b32_dpp v197, v26 row_ror:8 row_mask:0xf bank_mask:0xf bound_ctrl:1
	v_mov_b32_dpp v198, v19 row_ror:8 row_mask:0xf bank_mask:0xf bound_ctrl:1
	v_mov_b32_dpp v199, v27 row_ror:8 row_mask:0xf bank_mask:0xf bound_ctrl:1
	v_cndmask_b32_e64 v167, v167, -v167, s[100:101]
	v_cndmask_b32_e64 v193, v193, -v193, s[100:101]
	v_cndmask_b32_e64 v194, v194, -v194, s[100:101]
	v_cndmask_b32_e64 v195, v195, -v195, s[100:101]
	v_cndmask_b32_e64 v196, v196, -v196, s[100:101]
	v_cndmask_b32_e64 v197, v197, -v197, s[100:101]
	v_cndmask_b32_e64 v198, v198, -v198, s[100:101]
	v_cndmask_b32_e64 v199, v199, -v199, s[100:101]
	v_mul_f32_e32 v167, v167, v169
	v_mul_f32_e32 v193, v193, v169
	v_mul_f32_e32 v194, v194, v171
	v_mul_f32_e32 v195, v195, v171
	v_mul_f32_e32 v196, v196, v173
	v_mul_f32_e32 v197, v197, v173
	v_mul_f32_e32 v198, v198, v175
	v_mul_f32_e32 v199, v199, v175
	v_mul_f32_e32 v16, v16, v168
	v_mul_f32_e32 v24, v24, v168
	v_mul_f32_e32 v17, v17, v170
	v_mul_f32_e32 v25, v25, v170
	v_mul_f32_e32 v18, v18, v172
	v_mul_f32_e32 v26, v26, v172
	v_mul_f32_e32 v19, v19, v174
	v_mul_f32_e32 v27, v27, v174
	v_add_f32_e32 v16, v16, v167
	v_add_f32_e32 v24, v24, v193
	v_add_f32_e32 v17, v17, v194
	v_add_f32_e32 v25, v25, v195
	v_add_f32_e32 v18, v18, v196
	v_add_f32_e32 v26, v26, v197
	v_add_f32_e32 v19, v19, v198
	v_add_f32_e32 v27, v27, v199
	v_mul_f32_e32 v16, v160, v16
	v_mul_f32_e32 v17, v161, v17
	v_mul_f32_e32 v18, v162, v18
	v_mul_f32_e32 v19, v163, v19
	v_mul_f32_e32 v24, v160, v24
	v_mul_f32_e32 v25, v161, v25
	v_mul_f32_e32 v26, v162, v26
	v_mul_f32_e32 v27, v163, v27
	v_mul_f32_e32 v20, v20, v160
	v_mul_f32_e32 v21, v21, v161
	v_mul_f32_e32 v22, v22, v162
	v_mul_f32_e32 v23, v23, v163
	v_mul_f32_e32 v28, v28, v160
	v_mul_f32_e32 v29, v29, v161
	v_mul_f32_e32 v30, v30, v162
	v_mul_f32_e32 v31, v31, v163
	v_cvt_pk_bf16_f32 v200, v16, v17
	v_cvt_pk_bf16_f32 v201, v18, v19
	v_cvt_pk_bf16_f32 v202, v20, v21
	v_cvt_pk_bf16_f32 v203, v22, v23
	v_cvt_pk_bf16_f32 v204, v24, v25
	v_cvt_pk_bf16_f32 v205, v26, v27
	v_cvt_pk_bf16_f32 v206, v28, v29
	v_cvt_pk_bf16_f32 v207, v30, v31
	v_mov_b32_dpp v208, v200 quad_perm:[1,0,3,2] row_mask:0xf bank_mask:0xf bound_ctrl:1
	v_mov_b32_dpp v209, v201 quad_perm:[1,0,3,2] row_mask:0xf bank_mask:0xf bound_ctrl:1
	v_mov_b32_dpp v210, v202 quad_perm:[1,0,3,2] row_mask:0xf bank_mask:0xf bound_ctrl:1
	v_mov_b32_dpp v211, v203 quad_perm:[1,0,3,2] row_mask:0xf bank_mask:0xf bound_ctrl:1
	v_mov_b32_dpp v212, v204 quad_perm:[1,0,3,2] row_mask:0xf bank_mask:0xf bound_ctrl:1
	v_mov_b32_dpp v213, v205 quad_perm:[1,0,3,2] row_mask:0xf bank_mask:0xf bound_ctrl:1
	v_mov_b32_dpp v214, v206 quad_perm:[1,0,3,2] row_mask:0xf bank_mask:0xf bound_ctrl:1
	v_mov_b32_dpp v215, v207 quad_perm:[1,0,3,2] row_mask:0xf bank_mask:0xf bound_ctrl:1
	v_perm_b32 v200, v208, v200, v190
	v_perm_b32 v201, v209, v201, v190
	v_perm_b32 v202, v210, v202, v190
	v_perm_b32 v203, v211, v203, v190
	v_perm_b32 v204, v212, v204, v190
	v_perm_b32 v205, v213, v205, v190
	v_perm_b32 v206, v214, v206, v190
	v_perm_b32 v207, v215, v207, v190
	global_store_dword v184, v200, s[0:1] offset:1088
	global_store_dword v184, v201, s[4:5] offset:1088
	global_store_dword v184, v202, s[0:1] offset:1216
	global_store_dword v184, v203, s[4:5] offset:1216
	global_store_dword v184, v204, s[6:7] offset:1088
	global_store_dword v184, v205, s[98:99] offset:1088
	global_store_dword v184, v206, s[6:7] offset:1216
	global_store_dword v184, v207, s[98:99] offset:1216
	v_mul_f32_e32 v160, v32, v164
	v_mul_f32_e32 v161, v33, v164
	v_mul_f32_e32 v162, v34, v164
	v_mul_f32_e32 v163, v35, v164
	s_waitcnt vmcnt(8)
	v_mov_b32_dpp v167, v0 row_ror:8 row_mask:0xf bank_mask:0xf bound_ctrl:1
	v_mov_b32_dpp v193, v8 row_ror:8 row_mask:0xf bank_mask:0xf bound_ctrl:1
	v_mov_b32_dpp v194, v1 row_ror:8 row_mask:0xf bank_mask:0xf bound_ctrl:1
	v_mov_b32_dpp v195, v9 row_ror:8 row_mask:0xf bank_mask:0xf bound_ctrl:1
	v_mov_b32_dpp v196, v2 row_ror:8 row_mask:0xf bank_mask:0xf bound_ctrl:1
	v_mov_b32_dpp v197, v10 row_ror:8 row_mask:0xf bank_mask:0xf bound_ctrl:1
	v_mov_b32_dpp v198, v3 row_ror:8 row_mask:0xf bank_mask:0xf bound_ctrl:1
	v_mov_b32_dpp v199, v11 row_ror:8 row_mask:0xf bank_mask:0xf bound_ctrl:1
	v_cndmask_b32_e64 v167, v167, -v167, s[100:101]
	v_cndmask_b32_e64 v193, v193, -v193, s[100:101]
	v_cndmask_b32_e64 v194, v194, -v194, s[100:101]
	v_cndmask_b32_e64 v195, v195, -v195, s[100:101]
	v_cndmask_b32_e64 v196, v196, -v196, s[100:101]
	v_cndmask_b32_e64 v197, v197, -v197, s[100:101]
	v_cndmask_b32_e64 v198, v198, -v198, s[100:101]
	v_cndmask_b32_e64 v199, v199, -v199, s[100:101]
	v_mul_f32_e32 v167, v167, v177
	v_mul_f32_e32 v193, v193, v177
	v_mul_f32_e32 v194, v194, v179
	v_mul_f32_e32 v195, v195, v179
	v_mul_f32_e32 v196, v196, v181
	v_mul_f32_e32 v197, v197, v181
	v_mul_f32_e32 v198, v198, v183
	v_mul_f32_e32 v199, v199, v183
	v_mul_f32_e32 v0, v0, v176
	v_mul_f32_e32 v8, v8, v176
	v_mul_f32_e32 v1, v1, v178
	v_mul_f32_e32 v9, v9, v178
	v_mul_f32_e32 v2, v2, v180
	v_mul_f32_e32 v10, v10, v180
	v_mul_f32_e32 v3, v3, v182
	v_mul_f32_e32 v11, v11, v182
	v_add_f32_e32 v0, v0, v167
	v_add_f32_e32 v8, v8, v193
	v_add_f32_e32 v1, v1, v194
	v_add_f32_e32 v9, v9, v195
	v_add_f32_e32 v2, v2, v196
	v_add_f32_e32 v10, v10, v197
; __device__ __forceinline__ void store_rm4(u16* dst, size_t ld, int row0, int c, float v0, float v1, float v2, float v3, bool odd) {
;   {
;     float s = odd ? v0 : v1, r = dpp_swap1(s);
;     float lo = odd ? r : v0, hi = odd ? v1 : r;
;     *(unsigned*)(dst + (size_t)(row0 + (odd ? 1 : 0)) * ld + (c - (odd ? 1 : 0))) = pack2(lo, hi);
;   }
;   {
;     float s = odd ? v2 : v3, r = dpp_swap1(s);
;     float lo = odd ? r : v2, hi = odd ? v3 : r;
;     *(unsigned*)(dst + (size_t)(row0 + 2 + (odd ? 1 : 0)) * ld + (c - (odd ? 1 : 0))) = pack2(lo, hi);
;   }
;   __device__ __forceinline__ void operator()(f32x4 (&acc)[2][2][4][2], int brow, int bcol, int wr, int wc, int fr, int fq) const {
;     ...
;         for (int j = 0; j < 4; ++j) {
;           float2 cs = csc[j];
; #pragma unroll
;           for (int bj = 0; bj < 2; ++bj) {
;             float v = acc[ai][bj][m][0][j];
;             float pr = dpp_f<0x128>(v);
;             float sg = (fr < 8) ? -pr : pr;
;             float vr = v * cs.x + sg * cs.y;
;             v = rot ? vr : v;
;             va[bj][j] = v * rr[j];
;             vb[bj][j] = acc[ai][bj][m][1][j] * rr[j];
;           }
;         }
; #pragma unroll
;         for (int bj = 0; bj < 2; ++bj) {
;           int c = cbase + bj * 128 + wc * 32 + fr;
;           store_rm4(dst, 512, row0, c, va[bj][0], va[bj][1], va[bj][2], va[bj][3], fr & 1);
;           store_rm4(dst, 512, row0, c + 16, vb[bj][0], vb[bj][1], vb[bj][2], vb[bj][3], fr & 1);
;         }
;         __builtin_amdgcn_sched_barrier(0);
; #pragma unroll
;         for (int j = 0; j < 4; ++j) csc[j] = csn[j];
	v_add_f32_e32 v3, v3, v198
	v_add_f32_e32 v11, v11, v199
	v_mul_f32_e32 v0, v160, v0
	v_mul_f32_e32 v1, v161, v1
	v_mul_f32_e32 v2, v162, v2
	v_mul_f32_e32 v3, v163, v3
	v_mul_f32_e32 v8, v160, v8
	v_mul_f32_e32 v9, v161, v9
	v_mul_f32_e32 v10, v162, v10
	v_mul_f32_e32 v11, v163, v11
	v_mul_f32_e32 v4, v4, v160
	v_mul_f32_e32 v5, v5, v161
	v_mul_f32_e32 v6, v6, v162
	v_mul_f32_e32 v7, v7, v163
	v_mul_f32_e32 v12, v12, v160
	v_mul_f32_e32 v13, v13, v161
	v_mul_f32_e32 v14, v14, v162
	v_mul_f32_e32 v15, v15, v163
	v_cvt_pk_bf16_f32 v200, v0, v1
	v_cvt_pk_bf16_f32 v201, v2, v3
	v_cvt_pk_bf16_f32 v202, v4, v5
	v_cvt_pk_bf16_f32 v203, v6, v7
	v_cvt_pk_bf16_f32 v204, v8, v9
	v_cvt_pk_bf16_f32 v205, v10, v11
	v_cvt_pk_bf16_f32 v206, v12, v13
	v_cvt_pk_bf16_f32 v207, v14, v15
	v_mov_b32_dpp v208, v200 quad_perm:[1,0,3,2] row_mask:0xf bank_mask:0xf bound_ctrl:1
	v_mov_b32_dpp v209, v201 quad_perm:[1,0,3,2] row_mask:0xf bank_mask:0xf bound_ctrl:1
	v_mov_b32_dpp v210, v202 quad_perm:[1,0,3,2] row_mask:0xf bank_mask:0xf bound_ctrl:1
	v_mov_b32_dpp v211, v203 quad_perm:[1,0,3,2] row_mask:0xf bank_mask:0xf bound_ctrl:1
	v_mov_b32_dpp v212, v204 quad_perm:[1,0,3,2] row_mask:0xf bank_mask:0xf bound_ctrl:1
	v_mov_b32_dpp v213, v205 quad_perm:[1,0,3,2] row_mask:0xf bank_mask:0xf bound_ctrl:1
	v_mov_b32_dpp v214, v206 quad_perm:[1,0,3,2] row_mask:0xf bank_mask:0xf bound_ctrl:1
	v_mov_b32_dpp v215, v207 quad_perm:[1,0,3,2] row_mask:0xf bank_mask:0xf bound_ctrl:1
	v_perm_b32 v200, v208, v200, v190
	v_perm_b32 v201, v209, v201, v190
	v_perm_b32 v202, v210, v202, v190
	v_perm_b32 v203, v211, v203, v190
	v_perm_b32 v204, v212, v204, v190
	v_perm_b32 v205, v213, v205, v190
	v_perm_b32 v206, v214, v206, v190
	v_perm_b32 v207, v215, v207, v190
	global_store_dword v184, v200, s[0:1] offset:1120
	global_store_dword v184, v201, s[4:5] offset:1120
	global_store_dword v184, v202, s[0:1] offset:1248
	global_store_dword v184, v203, s[4:5] offset:1248
	global_store_dword v184, v204, s[6:7] offset:1120
	global_store_dword v184, v205, s[98:99] offset:1120
	global_store_dword v184, v206, s[6:7] offset:1248
	global_store_dword v184, v207, s[98:99] offset:1248
	s_branch .LBB0_130
.Lmy_rope_norot:
	s_waitcnt vmcnt(0)
	v_mul_f32_e32 v160, v156, v164
	v_mul_f32_e32 v161, v157, v164
	v_mul_f32_e32 v162, v158, v164
	v_mul_f32_e32 v163, v159, v164
	v_mul_f32_e32 v136, v160, v136
	v_mul_f32_e32 v137, v161, v137
	v_mul_f32_e32 v138, v162, v138
	v_mul_f32_e32 v139, v163, v139
	v_mul_f32_e32 v144, v160, v144
	v_mul_f32_e32 v145, v161, v145
	v_mul_f32_e32 v146, v162, v146
	v_mul_f32_e32 v147, v163, v147
	v_mul_f32_e32 v140, v140, v160
	v_mul_f32_e32 v141, v141, v161
	v_mul_f32_e32 v142, v142, v162
	v_mul_f32_e32 v143, v143, v163
	v_mul_f32_e32 v148, v148, v160
	v_mul_f32_e32 v149, v149, v161
	v_mul_f32_e32 v150, v150, v162
	v_mul_f32_e32 v151, v151, v163
	v_cvt_pk_bf16_f32 v200, v136, v137
	v_cvt_pk_bf16_f32 v201, v138, v139
	v_cvt_pk_bf16_f32 v202, v140, v141
	v_cvt_pk_bf16_f32 v203, v142, v143
	v_cvt_pk_bf16_f32 v204, v144, v145
	v_cvt_pk_bf16_f32 v205, v146, v147
	v_cvt_pk_bf16_f32 v206, v148, v149
	v_cvt_pk_bf16_f32 v207, v150, v151
	v_mov_b32_dpp v208, v200 quad_perm:[1,0,3,2] row_mask:0xf bank_mask:0xf bound_ctrl:1
	v_mov_b32_dpp v209, v201 quad_perm:[1,0,3,2] row_mask:0xf bank_mask:0xf bound_ctrl:1
	v_mov_b32_dpp v210, v202 quad_perm:[1,0,3,2] row_mask:0xf bank_mask:0xf bound_ctrl:1
	v_mov_b32_dpp v211, v203 quad_perm:[1,0,3,2] row_mask:0xf bank_mask:0xf bound_ctrl:1
	v_mov_b32_dpp v212, v204 quad_perm:[1,0,3,2] row_mask:0xf bank_mask:0xf bound_ctrl:1
	v_mov_b32_dpp v213, v205 quad_perm:[1,0,3,2] row_mask:0xf bank_mask:0xf bound_ctrl:1
	v_mov_b32_dpp v214, v206 quad_perm:[1,0,3,2] row_mask:0xf bank_mask:0xf bound_ctrl:1
	v_mov_b32_dpp v215, v207 quad_perm:[1,0,3,2] row_mask:0xf bank_mask:0xf bound_ctrl:1
	v_perm_b32 v200, v208, v200, v190
	v_perm_b32 v201, v209, v201, v190
	v_perm_b32 v202, v210, v202, v190
	v_perm_b32 v203, v211, v203, v190
	v_perm_b32 v204, v212, v204, v190
	v_perm_b32 v205, v213, v205, v190
	v_perm_b32 v206, v214, v206, v190
	v_perm_b32 v207, v215, v207, v190
	global_store_dword v184, v200, s[0:1]
	global_store_dword v184, v201, s[4:5]
	global_store_dword v184, v202, s[0:1] offset:128
	global_store_dword v184, v203, s[4:5] offset:128
	global_store_dword v184, v204, s[6:7]
	global_store_dword v184, v205, s[98:99]
	global_store_dword v184, v206, s[6:7] offset:128
	global_store_dword v184, v207, s[98:99] offset:128
	v_mul_f32_e32 v160, v152, v164
	v_mul_f32_e32 v161, v153, v164
	v_mul_f32_e32 v162, v154, v164
	v_mul_f32_e32 v163, v155, v164
	v_mul_f32_e32 v116, v160, v116
	v_mul_f32_e32 v117, v161, v117
	v_mul_f32_e32 v118, v162, v118
	v_mul_f32_e32 v119, v163, v119
	v_mul_f32_e32 v124, v160, v124
	v_mul_f32_e32 v125, v161, v125
	v_mul_f32_e32 v126, v162, v126
	v_mul_f32_e32 v127, v163, v127
	v_mul_f32_e32 v120, v120, v160
	v_mul_f32_e32 v121, v121, v161
	v_mul_f32_e32 v122, v122, v162
	v_mul_f32_e32 v123, v123, v163
	v_mul_f32_e32 v128, v128, v160
	v_mul_f32_e32 v129, v129, v161
	v_mul_f32_e32 v130, v130, v162
	v_mul_f32_e32 v131, v131, v163
	v_cvt_pk_bf16_f32 v200, v116, v117
	v_cvt_pk_bf16_f32 v201, v118, v119
	v_cvt_pk_bf16_f32 v202, v120, v121
	v_cvt_pk_bf16_f32 v203, v122, v123
	v_cvt_pk_bf16_f32 v204, v124, v125
	v_cvt_pk_bf16_f32 v205, v126, v127
	v_cvt_pk_bf16_f32 v206, v128, v129
	v_cvt_pk_bf16_f32 v207, v130, v131
	v_mov_b32_dpp v208, v200 quad_perm:[1,0,3,2] row_mask:0xf bank_mask:0xf bound_ctrl:1
	v_mov_b32_dpp v209, v201 quad_perm:[1,0,3,2] row_mask:0xf bank_mask:0xf bound_ctrl:1
	v_mov_b32_dpp v210, v202 quad_perm:[1,0,3,2] row_mask:0xf bank_mask:0xf bound_ctrl:1
; __device__ __forceinline__ void store_rm4(u16* dst, size_t ld, int row0, int c, float v0, float v1, float v2, float v3, bool odd) {
;   {
;     float s = odd ? v0 : v1, r = dpp_swap1(s);
;     float lo = odd ? r : v0, hi = odd ? v1 : r;
;     *(unsigned*)(dst + (size_t)(row0 + (odd ? 1 : 0)) * ld + (c - (odd ? 1 : 0))) = pack2(lo, hi);
;   }
;   {
;     float s = odd ? v2 : v3, r = dpp_swap1(s);
;     float lo = odd ? r : v2, hi = odd ? v3 : r;
;     *(unsigned*)(dst + (size_t)(row0 + 2 + (odd ? 1 : 0)) * ld + (c - (odd ? 1 : 0))) = pack2(lo, hi);
;   }
;   __device__ __forceinline__ void operator()(f32x4 (&acc)[2][2][4][2], int brow, int bcol, int wr, int wc, int fr, int fq) const {
;     ...
;         float4 r4 = rsq[ai][m];
;         float rr[4] = {r4.x * sc, r4.y * sc, r4.z * sc, r4.w * sc};
;         float va[2][4], vb[2][4];
; #pragma unroll
;         for (int j = 0; j < 4; ++j) {
;           float2 cs = csc[j];
; #pragma unroll
;           for (int bj = 0; bj < 2; ++bj) {
;             float v = acc[ai][bj][m][0][j];
;             float pr = dpp_f<0x128>(v);
;             float sg = (fr < 8) ? -pr : pr;
;             float vr = v * cs.x + sg * cs.y;
;             v = rot ? vr : v;
;             va[bj][j] = v * rr[j];
;             vb[bj][j] = acc[ai][bj][m][1][j] * rr[j];
;           }
;         }
; #pragma unroll
;         for (int bj = 0; bj < 2; ++bj) {
;           int c = cbase + bj * 128 + wc * 32 + fr;
;           store_rm4(dst, 512, row0, c, va[bj][0], va[bj][1], va[bj][2], va[bj][3], fr & 1);
;           store_rm4(dst, 512, row0, c + 16, vb[bj][0], vb[bj][1], vb[bj][2], vb[bj][3], fr & 1);
;         }
;         __builtin_amdgcn_sched_barrier(0);
; #pragma unroll
;         for (int j = 0; j < 4; ++j) csc[j] = csn[j];
	v_mov_b32_dpp v211, v203 quad_perm:[1,0,3,2] row_mask:0xf bank_mask:0xf bound_ctrl:1
	v_mov_b32_dpp v212, v204 quad_perm:[1,0,3,2] row_mask:0xf bank_mask:0xf bound_ctrl:1
	v_mov_b32_dpp v213, v205 quad_perm:[1,0,3,2] row_mask:0xf bank_mask:0xf bound_ctrl:1
	v_mov_b32_dpp v214, v206 quad_perm:[1,0,3,2] row_mask:0xf bank_mask:0xf bound_ctrl:1
	v_mov_b32_dpp v215, v207 quad_perm:[1,0,3,2] row_mask:0xf bank_mask:0xf bound_ctrl:1
	v_perm_b32 v200, v208, v200, v190
	v_perm_b32 v201, v209, v201, v190
	v_perm_b32 v202, v210, v202, v190
	v_perm_b32 v203, v211, v203, v190
	v_perm_b32 v204, v212, v204, v190
	v_perm_b32 v205, v213, v205, v190
	v_perm_b32 v206, v214, v206, v190
	v_perm_b32 v207, v215, v207, v190
	global_store_dword v184, v200, s[0:1] offset:32
	global_store_dword v184, v201, s[4:5] offset:32
	global_store_dword v184, v202, s[0:1] offset:160
	global_store_dword v184, v203, s[4:5] offset:160
	global_store_dword v184, v204, s[6:7] offset:32
	global_store_dword v184, v205, s[98:99] offset:32
	global_store_dword v184, v206, s[6:7] offset:160
	global_store_dword v184, v207, s[98:99] offset:160
	v_mul_f32_e32 v160, v132, v164
	v_mul_f32_e32 v161, v133, v164
	v_mul_f32_e32 v162, v134, v164
	v_mul_f32_e32 v163, v135, v164
	v_mul_f32_e32 v96, v160, v96
	v_mul_f32_e32 v97, v161, v97
	v_mul_f32_e32 v98, v162, v98
	v_mul_f32_e32 v99, v163, v99
	v_mul_f32_e32 v104, v160, v104
	v_mul_f32_e32 v105, v161, v105
	v_mul_f32_e32 v106, v162, v106
	v_mul_f32_e32 v107, v163, v107
	v_mul_f32_e32 v100, v100, v160
	v_mul_f32_e32 v101, v101, v161
	v_mul_f32_e32 v102, v102, v162
	v_mul_f32_e32 v103, v103, v163
	v_mul_f32_e32 v108, v108, v160
	v_mul_f32_e32 v109, v109, v161
	v_mul_f32_e32 v110, v110, v162
	v_mul_f32_e32 v111, v111, v163
	v_cvt_pk_bf16_f32 v200, v96, v97
	v_cvt_pk_bf16_f32 v201, v98, v99
	v_cvt_pk_bf16_f32 v202, v100, v101
	v_cvt_pk_bf16_f32 v203, v102, v103
	v_cvt_pk_bf16_f32 v204, v104, v105
	v_cvt_pk_bf16_f32 v205, v106, v107
	v_cvt_pk_bf16_f32 v206, v108, v109
	v_cvt_pk_bf16_f32 v207, v110, v111
	v_mov_b32_dpp v208, v200 quad_perm:[1,0,3,2] row_mask:0xf bank_mask:0xf bound_ctrl:1
	v_mov_b32_dpp v209, v201 quad_perm:[1,0,3,2] row_mask:0xf bank_mask:0xf bound_ctrl:1
	v_mov_b32_dpp v210, v202 quad_perm:[1,0,3,2] row_mask:0xf bank_mask:0xf bound_ctrl:1
	v_mov_b32_dpp v211, v203 quad_perm:[1,0,3,2] row_mask:0xf bank_mask:0xf bound_ctrl:1
	v_mov_b32_dpp v212, v204 quad_perm:[1,0,3,2] row_mask:0xf bank_mask:0xf bound_ctrl:1
	v_mov_b32_dpp v213, v205 quad_perm:[1,0,3,2] row_mask:0xf bank_mask:0xf bound_ctrl:1
	v_mov_b32_dpp v214, v206 quad_perm:[1,0,3,2] row_mask:0xf bank_mask:0xf bound_ctrl:1
	v_mov_b32_dpp v215, v207 quad_perm:[1,0,3,2] row_mask:0xf bank_mask:0xf bound_ctrl:1
	v_perm_b32 v200, v208, v200, v190
	v_perm_b32 v201, v209, v201, v190
	v_perm_b32 v202, v210, v202, v190
	v_perm_b32 v203, v211, v203, v190
	v_perm_b32 v204, v212, v204, v190
	v_perm_b32 v205, v213, v205, v190
	v_perm_b32 v206, v214, v206, v190
	v_perm_b32 v207, v215, v207, v190
	global_store_dword v184, v200, s[0:1] offset:64
	global_store_dword v184, v201, s[4:5] offset:64
	global_store_dword v184, v202, s[0:1] offset:192
	global_store_dword v184, v203, s[4:5] offset:192
	global_store_dword v184, v204, s[6:7] offset:64
	global_store_dword v184, v205, s[98:99] offset:64
	global_store_dword v184, v206, s[6:7] offset:192
	global_store_dword v184, v207, s[98:99] offset:192
	v_mul_f32_e32 v160, v112, v164
	v_mul_f32_e32 v161, v113, v164
	v_mul_f32_e32 v162, v114, v164
	v_mul_f32_e32 v163, v115, v164
	v_mul_f32_e32 v76, v160, v76
	v_mul_f32_e32 v77, v161, v77
	v_mul_f32_e32 v78, v162, v78
	v_mul_f32_e32 v79, v163, v79
	v_mul_f32_e32 v84, v160, v84
	v_mul_f32_e32 v85, v161, v85
	v_mul_f32_e32 v86, v162, v86
	v_mul_f32_e32 v87, v163, v87
	v_mul_f32_e32 v80, v80, v160
	v_mul_f32_e32 v81, v81, v161
	v_mul_f32_e32 v82, v82, v162
	v_mul_f32_e32 v83, v83, v163
	v_mul_f32_e32 v88, v88, v160
	v_mul_f32_e32 v89, v89, v161
	v_mul_f32_e32 v90, v90, v162
	v_mul_f32_e32 v91, v91, v163
	v_cvt_pk_bf16_f32 v200, v76, v77
	v_cvt_pk_bf16_f32 v201, v78, v79
	v_cvt_pk_bf16_f32 v202, v80, v81
	v_cvt_pk_bf16_f32 v203, v82, v83
	v_cvt_pk_bf16_f32 v204, v84, v85
	v_cvt_pk_bf16_f32 v205, v86, v87
	v_cvt_pk_bf16_f32 v206, v88, v89
	v_cvt_pk_bf16_f32 v207, v90, v91
	v_mov_b32_dpp v208, v200 quad_perm:[1,0,3,2] row_mask:0xf bank_mask:0xf bound_ctrl:1
	v_mov_b32_dpp v209, v201 quad_perm:[1,0,3,2] row_mask:0xf bank_mask:0xf bound_ctrl:1
	v_mov_b32_dpp v210, v202 quad_perm:[1,0,3,2] row_mask:0xf bank_mask:0xf bound_ctrl:1
	v_mov_b32_dpp v211, v203 quad_perm:[1,0,3,2] row_mask:0xf bank_mask:0xf bound_ctrl:1
	v_mov_b32_dpp v212, v204 quad_perm:[1,0,3,2] row_mask:0xf bank_mask:0xf bound_ctrl:1
	v_mov_b32_dpp v213, v205 quad_perm:[1,0,3,2] row_mask:0xf bank_mask:0xf bound_ctrl:1
	v_mov_b32_dpp v214, v206 quad_perm:[1,0,3,2] row_mask:0xf bank_mask:0xf bound_ctrl:1
	v_mov_b32_dpp v215, v207 quad_perm:[1,0,3,2] row_mask:0xf bank_mask:0xf bound_ctrl:1
	v_perm_b32 v200, v208, v200, v190
	v_perm_b32 v201, v209, v201, v190
	v_perm_b32 v202, v210, v202, v190
	v_perm_b32 v203, v211, v203, v190
	v_perm_b32 v204, v212, v204, v190
	v_perm_b32 v205, v213, v205, v190
	v_perm_b32 v206, v214, v206, v190
	v_perm_b32 v207, v215, v207, v190
	global_store_dword v184, v200, s[0:1] offset:96
	global_store_dword v184, v201, s[4:5] offset:96
	global_store_dword v184, v202, s[0:1] offset:224
	global_store_dword v184, v203, s[4:5] offset:224
	global_store_dword v184, v204, s[6:7] offset:96
	global_store_dword v184, v205, s[98:99] offset:96
	global_store_dword v184, v206, s[6:7] offset:224
	global_store_dword v184, v207, s[98:99] offset:224
; __device__ __forceinline__ void store_rm4(u16* dst, size_t ld, int row0, int c, float v0, float v1, float v2, float v3, bool odd) {
;   {
;     float s = odd ? v0 : v1, r = dpp_swap1(s);
;     float lo = odd ? r : v0, hi = odd ? v1 : r;
;     *(unsigned*)(dst + (size_t)(row0 + (odd ? 1 : 0)) * ld + (c - (odd ? 1 : 0))) = pack2(lo, hi);
;   }
;   {
;     float s = odd ? v2 : v3, r = dpp_swap1(s);
;     float lo = odd ? r : v2, hi = odd ? v3 : r;
;     *(unsigned*)(dst + (size_t)(row0 + 2 + (odd ? 1 : 0)) * ld + (c - (odd ? 1 : 0))) = pack2(lo, hi);
;   }
;   __device__ __forceinline__ void operator()(f32x4 (&acc)[2][2][4][2], int brow, int bcol, int wr, int wc, int fr, int fq) const {
;     ...
;         float4 r4 = rsq[ai][m];
;         float rr[4] = {r4.x * sc, r4.y * sc, r4.z * sc, r4.w * sc};
;         float va[2][4], vb[2][4];
; #pragma unroll
;         for (int j = 0; j < 4; ++j) {
;           float2 cs = csc[j];
; #pragma unroll
;           for (int bj = 0; bj < 2; ++bj) {
;             float v = acc[ai][bj][m][0][j];
;             float pr = dpp_f<0x128>(v);
;             float sg = (fr < 8) ? -pr : pr;
;             float vr = v * cs.x + sg * cs.y;
;             v = rot ? vr : v;
;             va[bj][j] = v * rr[j];
;             vb[bj][j] = acc[ai][bj][m][1][j] * rr[j];
;           }
;         }
; #pragma unroll
;         for (int bj = 0; bj < 2; ++bj) {
;           int c = cbase + bj * 128 + wc * 32 + fr;
;           store_rm4(dst, 512, row0, c, va[bj][0], va[bj][1], va[bj][2], va[bj][3], fr & 1);
;           store_rm4(dst, 512, row0, c + 16, vb[bj][0], vb[bj][1], vb[bj][2], vb[bj][3], fr & 1);
;         }
;         __builtin_amdgcn_sched_barrier(0);
; #pragma unroll
;         for (int j = 0; j < 4; ++j) csc[j] = csn[j];
	v_mul_f32_e32 v160, v92, v164
	v_mul_f32_e32 v161, v93, v164
	v_mul_f32_e32 v162, v94, v164
	v_mul_f32_e32 v163, v95, v164
	v_mul_f32_e32 v56, v160, v56
	v_mul_f32_e32 v57, v161, v57
	v_mul_f32_e32 v58, v162, v58
	v_mul_f32_e32 v59, v163, v59
	v_mul_f32_e32 v64, v160, v64
	v_mul_f32_e32 v65, v161, v65
	v_mul_f32_e32 v66, v162, v66
	v_mul_f32_e32 v67, v163, v67
	v_mul_f32_e32 v60, v60, v160
	v_mul_f32_e32 v61, v61, v161
	v_mul_f32_e32 v62, v62, v162
	v_mul_f32_e32 v63, v63, v163
	v_mul_f32_e32 v68, v68, v160
	v_mul_f32_e32 v69, v69, v161
	v_mul_f32_e32 v70, v70, v162
	v_mul_f32_e32 v71, v71, v163
	v_cvt_pk_bf16_f32 v200, v56, v57
	v_cvt_pk_bf16_f32 v201, v58, v59
	v_cvt_pk_bf16_f32 v202, v60, v61
	v_cvt_pk_bf16_f32 v203, v62, v63
	v_cvt_pk_bf16_f32 v204, v64, v65
	v_cvt_pk_bf16_f32 v205, v66, v67
	v_cvt_pk_bf16_f32 v206, v68, v69
	v_cvt_pk_bf16_f32 v207, v70, v71
	v_mov_b32_dpp v208, v200 quad_perm:[1,0,3,2] row_mask:0xf bank_mask:0xf bound_ctrl:1
	v_mov_b32_dpp v209, v201 quad_perm:[1,0,3,2] row_mask:0xf bank_mask:0xf bound_ctrl:1
	v_mov_b32_dpp v210, v202 quad_perm:[1,0,3,2] row_mask:0xf bank_mask:0xf bound_ctrl:1
	v_mov_b32_dpp v211, v203 quad_perm:[1,0,3,2] row_mask:0xf bank_mask:0xf bound_ctrl:1
	v_mov_b32_dpp v212, v204 quad_perm:[1,0,3,2] row_mask:0xf bank_mask:0xf bound_ctrl:1
	v_mov_b32_dpp v213, v205 quad_perm:[1,0,3,2] row_mask:0xf bank_mask:0xf bound_ctrl:1
	v_mov_b32_dpp v214, v206 quad_perm:[1,0,3,2] row_mask:0xf bank_mask:0xf bound_ctrl:1
	v_mov_b32_dpp v215, v207 quad_perm:[1,0,3,2] row_mask:0xf bank_mask:0xf bound_ctrl:1
	v_perm_b32 v200, v208, v200, v190
	v_perm_b32 v201, v209, v201, v190
	v_perm_b32 v202, v210, v202, v190
	v_perm_b32 v203, v211, v203, v190
	v_perm_b32 v204, v212, v204, v190
	v_perm_b32 v205, v213, v205, v190
	v_perm_b32 v206, v214, v206, v190
	v_perm_b32 v207, v215, v207, v190
	global_store_dword v184, v200, s[0:1] offset:1024
	global_store_dword v184, v201, s[4:5] offset:1024
	global_store_dword v184, v202, s[0:1] offset:1152
	global_store_dword v184, v203, s[4:5] offset:1152
	global_store_dword v184, v204, s[6:7] offset:1024
	global_store_dword v184, v205, s[98:99] offset:1024
	global_store_dword v184, v206, s[6:7] offset:1152
	global_store_dword v184, v207, s[98:99] offset:1152
	v_mul_f32_e32 v160, v72, v164
	v_mul_f32_e32 v161, v73, v164
	v_mul_f32_e32 v162, v74, v164
	v_mul_f32_e32 v163, v75, v164
	v_mul_f32_e32 v36, v160, v36
	v_mul_f32_e32 v37, v161, v37
	v_mul_f32_e32 v38, v162, v38
	v_mul_f32_e32 v39, v163, v39
	v_mul_f32_e32 v44, v160, v44
	v_mul_f32_e32 v45, v161, v45
	v_mul_f32_e32 v46, v162, v46
	v_mul_f32_e32 v47, v163, v47
	v_mul_f32_e32 v40, v40, v160
	v_mul_f32_e32 v41, v41, v161
	v_mul_f32_e32 v42, v42, v162
	v_mul_f32_e32 v43, v43, v163
	v_mul_f32_e32 v48, v48, v160
	v_mul_f32_e32 v49, v49, v161
	v_mul_f32_e32 v50, v50, v162
	v_mul_f32_e32 v51, v51, v163
	v_cvt_pk_bf16_f32 v200, v36, v37
	v_cvt_pk_bf16_f32 v201, v38, v39
	v_cvt_pk_bf16_f32 v202, v40, v41
	v_cvt_pk_bf16_f32 v203, v42, v43
	v_cvt_pk_bf16_f32 v204, v44, v45
	v_cvt_pk_bf16_f32 v205, v46, v47
	v_cvt_pk_bf16_f32 v206, v48, v49
	v_cvt_pk_bf16_f32 v207, v50, v51
	v_mov_b32_dpp v208, v200 quad_perm:[1,0,3,2] row_mask:0xf bank_mask:0xf bound_ctrl:1
	v_mov_b32_dpp v209, v201 quad_perm:[1,0,3,2] row_mask:0xf bank_mask:0xf bound_ctrl:1
	v_mov_b32_dpp v210, v202 quad_perm:[1,0,3,2] row_mask:0xf bank_mask:0xf bound_ctrl:1
	v_mov_b32_dpp v211, v203 quad_perm:[1,0,3,2] row_mask:0xf bank_mask:0xf bound_ctrl:1
	v_mov_b32_dpp v212, v204 quad_perm:[1,0,3,2] row_mask:0xf bank_mask:0xf bound_ctrl:1
	v_mov_b32_dpp v213, v205 quad_perm:[1,0,3,2] row_mask:0xf bank_mask:0xf bound_ctrl:1
	v_mov_b32_dpp v214, v206 quad_perm:[1,0,3,2] row_mask:0xf bank_mask:0xf bound_ctrl:1
	v_mov_b32_dpp v215, v207 quad_perm:[1,0,3,2] row_mask:0xf bank_mask:0xf bound_ctrl:1
	v_perm_b32 v200, v208, v200, v190
	v_perm_b32 v201, v209, v201, v190
	v_perm_b32 v202, v210, v202, v190
	v_perm_b32 v203, v211, v203, v190
	v_perm_b32 v204, v212, v204, v190
	v_perm_b32 v205, v213, v205, v190
	v_perm_b32 v206, v214, v206, v190
	v_perm_b32 v207, v215, v207, v190
	global_store_dword v184, v200, s[0:1] offset:1056
	global_store_dword v184, v201, s[4:5] offset:1056
	global_store_dword v184, v202, s[0:1] offset:1184
	global_store_dword v184, v203, s[4:5] offset:1184
	global_store_dword v184, v204, s[6:7] offset:1056
	global_store_dword v184, v205, s[98:99] offset:1056
	global_store_dword v184, v206, s[6:7] offset:1184
	global_store_dword v184, v207, s[98:99] offset:1184
; __device__ __forceinline__ void store_rm4(u16* dst, size_t ld, int row0, int c, float v0, float v1, float v2, float v3, bool odd) {
;   {
;     float s = odd ? v0 : v1, r = dpp_swap1(s);
;     float lo = odd ? r : v0, hi = odd ? v1 : r;
;     *(unsigned*)(dst + (size_t)(row0 + (odd ? 1 : 0)) * ld + (c - (odd ? 1 : 0))) = pack2(lo, hi);
;   }
;   {
;     float s = odd ? v2 : v3, r = dpp_swap1(s);
;     float lo = odd ? r : v2, hi = odd ? v3 : r;
;     *(unsigned*)(dst + (size_t)(row0 + 2 + (odd ? 1 : 0)) * ld + (c - (odd ? 1 : 0))) = pack2(lo, hi);
;   }
;   __device__ __forceinline__ void operator()(f32x4 (&acc)[2][2][4][2], int brow, int bcol, int wr, int wc, int fr, int fq) const {
;     ...
;         float4 r4 = rsq[ai][m];
;         float rr[4] = {r4.x * sc, r4.y * sc, r4.z * sc, r4.w * sc};
;         float va[2][4], vb[2][4];
; #pragma unroll
;         for (int j = 0; j < 4; ++j) {
;           float2 cs = csc[j];
; #pragma unroll
;           for (int bj = 0; bj < 2; ++bj) {
;             float v = acc[ai][bj][m][0][j];
;             float pr = dpp_f<0x128>(v);
;             float sg = (fr < 8) ? -pr : pr;
;             float vr = v * cs.x + sg * cs.y;
;             v = rot ? vr : v;
;             va[bj][j] = v * rr[j];
;             vb[bj][j] = acc[ai][bj][m][1][j] * rr[j];
;           }
;         }
; #pragma unroll
;         for (int bj = 0; bj < 2; ++bj) {
;           int c = cbase + bj * 128 + wc * 32 + fr;
;           store_rm4(dst, 512, row0, c, va[bj][0], va[bj][1], va[bj][2], va[bj][3], fr & 1);
;           store_rm4(dst, 512, row0, c + 16, vb[bj][0], vb[bj][1], vb[bj][2], vb[bj][3], fr & 1);
;         }
;         __builtin_amdgcn_sched_barrier(0);
; #pragma unroll
;         for (int j = 0; j < 4; ++j) csc[j] = csn[j];
	v_mul_f32_e32 v160, v52, v164
	v_mul_f32_e32 v161, v53, v164
	v_mul_f32_e32 v162, v54, v164
	v_mul_f32_e32 v163, v55, v164
	v_mul_f32_e32 v16, v160, v16
	v_mul_f32_e32 v17, v161, v17
	v_mul_f32_e32 v18, v162, v18
	v_mul_f32_e32 v19, v163, v19
	v_mul_f32_e32 v24, v160, v24
	v_mul_f32_e32 v25, v161, v25
	v_mul_f32_e32 v26, v162, v26
	v_mul_f32_e32 v27, v163, v27
	v_mul_f32_e32 v20, v20, v160
	v_mul_f32_e32 v21, v21, v161
	v_mul_f32_e32 v22, v22, v162
	v_mul_f32_e32 v23, v23, v163
	v_mul_f32_e32 v28, v28, v160
	v_mul_f32_e32 v29, v29, v161
	v_mul_f32_e32 v30, v30, v162
	v_mul_f32_e32 v31, v31, v163
	v_cvt_pk_bf16_f32 v200, v16, v17
	v_cvt_pk_bf16_f32 v201, v18, v19
	v_cvt_pk_bf16_f32 v202, v20, v21
	v_cvt_pk_bf16_f32 v203, v22, v23
	v_cvt_pk_bf16_f32 v204, v24, v25
	v_cvt_pk_bf16_f32 v205, v26, v27
	v_cvt_pk_bf16_f32 v206, v28, v29
	v_cvt_pk_bf16_f32 v207, v30, v31
	v_mov_b32_dpp v208, v200 quad_perm:[1,0,3,2] row_mask:0xf bank_mask:0xf bound_ctrl:1
	v_mov_b32_dpp v209, v201 quad_perm:[1,0,3,2] row_mask:0xf bank_mask:0xf bound_ctrl:1
	v_mov_b32_dpp v210, v202 quad_perm:[1,0,3,2] row_mask:0xf bank_mask:0xf bound_ctrl:1
	v_mov_b32_dpp v211, v203 quad_perm:[1,0,3,2] row_mask:0xf bank_mask:0xf bound_ctrl:1
	v_mov_b32_dpp v212, v204 quad_perm:[1,0,3,2] row_mask:0xf bank_mask:0xf bound_ctrl:1
	v_mov_b32_dpp v213, v205 quad_perm:[1,0,3,2] row_mask:0xf bank_mask:0xf bound_ctrl:1
	v_mov_b32_dpp v214, v206 quad_perm:[1,0,3,2] row_mask:0xf bank_mask:0xf bound_ctrl:1
	v_mov_b32_dpp v215, v207 quad_perm:[1,0,3,2] row_mask:0xf bank_mask:0xf bound_ctrl:1
	v_perm_b32 v200, v208, v200, v190
	v_perm_b32 v201, v209, v201, v190
	v_perm_b32 v202, v210, v202, v190
	v_perm_b32 v203, v211, v203, v190
	v_perm_b32 v204, v212, v204, v190
	v_perm_b32 v205, v213, v205, v190
	v_perm_b32 v206, v214, v206, v190
	v_perm_b32 v207, v215, v207, v190
	global_store_dword v184, v200, s[0:1] offset:1088
	global_store_dword v184, v201, s[4:5] offset:1088
	global_store_dword v184, v202, s[0:1] offset:1216
	global_store_dword v184, v203, s[4:5] offset:1216
	global_store_dword v184, v204, s[6:7] offset:1088
	global_store_dword v184, v205, s[98:99] offset:1088
	global_store_dword v184, v206, s[6:7] offset:1216
	global_store_dword v184, v207, s[98:99] offset:1216
	v_mul_f32_e32 v160, v32, v164
	v_mul_f32_e32 v161, v33, v164
	v_mul_f32_e32 v162, v34, v164
	v_mul_f32_e32 v163, v35, v164
	v_mul_f32_e32 v0, v160, v0
	v_mul_f32_e32 v1, v161, v1
	v_mul_f32_e32 v2, v162, v2
	v_mul_f32_e32 v3, v163, v3
	v_mul_f32_e32 v8, v160, v8
	v_mul_f32_e32 v9, v161, v9
	v_mul_f32_e32 v10, v162, v10
	v_mul_f32_e32 v11, v163, v11
	v_mul_f32_e32 v4, v4, v160
	v_mul_f32_e32 v5, v5, v161
	v_mul_f32_e32 v6, v6, v162
	v_mul_f32_e32 v7, v7, v163
	v_mul_f32_e32 v12, v12, v160
	v_mul_f32_e32 v13, v13, v161
	v_mul_f32_e32 v14, v14, v162
	v_mul_f32_e32 v15, v15, v163
	v_cvt_pk_bf16_f32 v200, v0, v1
	v_cvt_pk_bf16_f32 v201, v2, v3
	v_cvt_pk_bf16_f32 v202, v4, v5
	v_cvt_pk_bf16_f32 v203, v6, v7
	v_cvt_pk_bf16_f32 v204, v8, v9
	v_cvt_pk_bf16_f32 v205, v10, v11
	v_cvt_pk_bf16_f32 v206, v12, v13
	v_cvt_pk_bf16_f32 v207, v14, v15
	v_mov_b32_dpp v208, v200 quad_perm:[1,0,3,2] row_mask:0xf bank_mask:0xf bound_ctrl:1
	v_mov_b32_dpp v209, v201 quad_perm:[1,0,3,2] row_mask:0xf bank_mask:0xf bound_ctrl:1
	v_mov_b32_dpp v210, v202 quad_perm:[1,0,3,2] row_mask:0xf bank_mask:0xf bound_ctrl:1
	v_mov_b32_dpp v211, v203 quad_perm:[1,0,3,2] row_mask:0xf bank_mask:0xf bound_ctrl:1
	v_mov_b32_dpp v212, v204 quad_perm:[1,0,3,2] row_mask:0xf bank_mask:0xf bound_ctrl:1
	v_mov_b32_dpp v213, v205 quad_perm:[1,0,3,2] row_mask:0xf bank_mask:0xf bound_ctrl:1
	v_mov_b32_dpp v214, v206 quad_perm:[1,0,3,2] row_mask:0xf bank_mask:0xf bound_ctrl:1
	v_mov_b32_dpp v215, v207 quad_perm:[1,0,3,2] row_mask:0xf bank_mask:0xf bound_ctrl:1
	v_perm_b32 v200, v208, v200, v190
	v_perm_b32 v201, v209, v201, v190
	v_perm_b32 v202, v210, v202, v190
	v_perm_b32 v203, v211, v203, v190
	v_perm_b32 v204, v212, v204, v190
	v_perm_b32 v205, v213, v205, v190
	v_perm_b32 v206, v214, v206, v190
	v_perm_b32 v207, v215, v207, v190
	global_store_dword v184, v200, s[0:1] offset:1120
	global_store_dword v184, v201, s[4:5] offset:1120
	global_store_dword v184, v202, s[0:1] offset:1248
	global_store_dword v184, v203, s[4:5] offset:1248
	global_store_dword v184, v204, s[6:7] offset:1120
	global_store_dword v184, v205, s[98:99] offset:1120
	global_store_dword v184, v206, s[6:7] offset:1248
	global_store_dword v184, v207, s[98:99] offset:1248
	s_branch .LBB0_130

; __device__ __forceinline__ KVB attn_load(int ks, const u16* __restrict__ kbase, const u16* __restrict__ vbase, int L16,
;                                          int r, int i0, int lane) {
;     ...
;   int cK, sK; attn_desc(ks, gk, r, i0, cK, sK);
;   int ia = sK + ek, ib = ia + 4;
;   ia = min(max(ia, 0), L16 - 1); ib = min(max(ib, 0), L16 - 1);
;   const u16* ka = kbase + (size_t)(cK + 16 * ia) * 512;
;   const u16* kb = kbase + (size_t)(cK + 16 * ib) * 512;
;   b.k0 = *(const bf16x8*)ka; b.k1 = *(const bf16x8*)(ka + 8);
;   b.k2 = *(const bf16x8*)kb; b.k3 = *(const bf16x8*)(kb + 8);
; template <int NT>
; __device__ void attn_unitN(const P& p, int u) {
;     ...
;   int lane = opaque_tid(p) & 63, q = lane & 15, quad = lane >> 4;
;   int rb = u % RS, h = (u / RS) & 7, span = u / (RS * 8);
;   int tb = span * 256;
;   int seq0, L;
;   if (tb < NT_P) { L = 4096; seq0 = tb & ~4095; } else { L = 8192; seq0 = NT_P + ((tb - NT_P) & ~8191); }
;   int L16 = L >> 4;
;   int i0 = (tb - seq0) >> 4;
;   int iq = i0 + q;
;   const u16* Qd = (const u16*)((const char*)p.out + OUT_QD);
;   const u16* Kd = (const u16*)((const char*)p.out + OUT_KD);
;   const u16* VdT = (const u16*)(p.ws + OFF_VDT);
;   extern __shared__ __attribute__((aligned(16))) u16 shm[];
;   bf16x8* qs = (bf16x8*)((char*)shm + __builtin_amdgcn_readfirstlane(opaque_tid(p) >> 6) * 8192) + lane;
;   f32x4 o[NT][4];
;   float mrun[NT], lrun[NT];
; #pragma unroll
;   for (int t = 0; t < NT; ++t) {
;     const u16* qp = Qd + (size_t)(seq0 + rb + RS * t + 16 * iq) * 512 + h * 64 + quad * 16;
;     qs[t * 128] = *(const bf16x8*)qp; qs[t * 128 + 64] = *(const bf16x8*)(qp + 8);
; #pragma unroll
;     for (int dt = 0; dt < 4; ++dt) o[t][dt] = f32x4{0.f, 0.f, 0.f, 0.f};
;     mrun[t] = -1e30f; lrun[t] = 0.f;
;   }
;   const u16* kbase = Kd + (size_t)seq0 * 512 + h * 64 + quad * 16;
;   const u16* vbase = VdT + (size_t)seq0 * 512 + (size_t)h * 16 * 64 * L16;
;   KVB bA = attn_load_e<NT>(0, kbase, vbase, L16, rb, i0, lane);
;   KVB bB = attn_load_e<NT>(1, kbase, vbase, L16, rb, i0, lane);
.LBB0_231:
	s_ashr_i32 s0, s3, 31
	s_lshr_b32 s1, s0, 30
	s_lshr_b32 s0, s0, 27
	s_add_i32 s1, s3, s1
	s_add_i32 s0, s3, s0
	s_and_b32 s4, s1, -4
	s_lshl_b32 s0, s0, 3
	s_sub_i32 s42, s3, s4
	s_bfe_u32 s8, s1, 0x30002
	s_and_b32 s1, s0, 0xffffff00
	s_cmpk_lt_i32 s3, 0x1000
	s_cselect_b32 s0, s31, 0x7fffe000
	v_mbcnt_lo_u32_b32 v224, -1, 0
	v_mbcnt_hi_u32_b32 v224, -1, v224
	s_cselect_b32 s10, 8, 9
	s_cselect_b32 s43, s40, 0x1ff
	s_cselect_b32 s44, 6, 7
	s_and_b32 s0, s1, s0
	v_mbcnt_lo_u32_b32 v0, -1, 0
	v_mbcnt_hi_u32_b32 v0, -1, v0
	s_sub_i32 s1, s1, s0
	v_add_u32_e32 v0, s33, v0
	s_ashr_i32 s46, s1, 4
	v_readfirstlane_b32 s1, v0
	v_and_b32_e32 v34, 15, v224
	s_lshl_b32 s1, s1, 7
	v_or_b32_e32 v225, s46, v34
	s_and_b32 s1, s1, 0xffffe000
	s_add_i32 s4, s0, s42
	s_add_i32 s1, s1, 16
	v_lshl_add_u32 v152, v225, 4, s4
	s_lshl_b32 s45, s8, 6
	s_lshl_b32 s11, s8, 15
	s_add_u32 s4, s26, s11
	v_and_b32_e32 v0, 48, v224
	v_add_u32_e32 v150, 4, v152
	v_add_u32_e32 v148, 8, v152
	v_add_u32_e32 v146, 12, v152
	s_addc_u32 s5, s27, 0
	v_lshlrev_b32_e32 v144, 3, v0
	v_ashrrev_i32_e32 v153, 31, v152
	v_ashrrev_i32_e32 v151, 31, v150
	v_ashrrev_i32_e32 v149, 31, v148
	v_ashrrev_i32_e32 v147, 31, v146
	v_lshl_add_u64 v[24:25], s[4:5], 0, v[144:145]
	v_lshrrev_b32_e32 v243, 8, v152
	v_and_b32_e32 v244, 15, v152
	v_lshlrev_b32_e32 v243, 18, v243
	v_lshl_or_b32 v243, v244, 11, v243
	v_bfe_u32 v244, v152, 6, 2
	v_lshl_or_b32 v243, v244, 9, v243
	v_bfe_u32 v244, v152, 4, 2
	v_lshl_or_b32 v0, v244, 5, v243
	v_mov_b32_e32 v1, 0
	v_lshrrev_b32_e32 v243, 8, v150
	v_and_b32_e32 v244, 15, v150
	v_lshlrev_b32_e32 v243, 18, v243
	v_lshl_or_b32 v243, v244, 11, v243
	v_bfe_u32 v244, v150, 6, 2
	v_lshl_or_b32 v243, v244, 9, v243
	v_bfe_u32 v244, v150, 4, 2
	v_lshl_or_b32 v8, v244, 5, v243
	v_mov_b32_e32 v9, 0
	v_lshrrev_b32_e32 v243, 8, v148
	v_and_b32_e32 v244, 15, v148
	v_lshlrev_b32_e32 v243, 18, v243
	v_lshl_or_b32 v243, v244, 11, v243
	v_bfe_u32 v244, v148, 6, 2
	v_lshl_or_b32 v243, v244, 9, v243
	v_bfe_u32 v244, v148, 4, 2
	v_lshl_or_b32 v16, v244, 5, v243
	v_mov_b32_e32 v17, 0
	v_lshrrev_b32_e32 v243, 8, v146
	v_and_b32_e32 v244, 15, v146
	v_lshlrev_b32_e32 v243, 18, v243
	v_lshl_or_b32 v243, v244, 11, v243
	v_bfe_u32 v244, v146, 6, 2
	v_lshl_or_b32 v243, v244, 9, v243
	v_bfe_u32 v244, v146, 4, 2
	v_lshl_or_b32 v26, v244, 5, v243
	v_mov_b32_e32 v27, 0
	v_lshl_add_u64 v[4:5], v[24:25], 0, v[0:1]
	v_lshl_add_u64 v[12:13], v[24:25], 0, v[8:9]
	v_lshl_add_u64 v[20:21], v[24:25], 0, v[16:17]
	v_lshl_add_u64 v[28:29], v[24:25], 0, v[26:27]
	global_load_dwordx4 v[0:3], v[4:5], off
	s_nop 0
	global_load_dwordx4 v[4:7], v[4:5], off offset:16
	s_nop 0
	global_load_dwordx4 v[8:11], v[12:13], off
	s_nop 0
	global_load_dwordx4 v[12:15], v[12:13], off offset:16
	s_nop 0
	global_load_dwordx4 v[16:19], v[20:21], off
	s_nop 0
	global_load_dwordx4 v[20:23], v[20:21], off offset:16
	s_nop 0
	global_load_dwordx4 v[24:27], v[28:29], off
	s_nop 0
	global_load_dwordx4 v[28:31], v[28:29], off offset:16
	v_and_b32_e32 v226, 63, v224
	v_lshl_add_u32 v228, v226, 4, s1
	s_ashr_i32 s1, s0, 31
	s_lshl_b64 s[0:1], s[0:1], 10
	s_add_u32 s4, s28, s0
	s_addc_u32 s5, s29, s1
	s_add_u32 s4, s4, s11
	s_addc_u32 s5, s5, 0
	s_add_u32 s0, s90, s0
	v_lshl_add_u64 v[154:155], s[4:5], 0, v[144:145]
	s_addc_u32 s1, s91, s1
	s_lshl_b32 s4, s8, 10
	s_lshl_b32 s4, s4, s10
	s_lshl_b32 s4, s4, 1
	s_add_u32 s0, s0, s4
	v_and_b32_e32 v227, 3, v224
	s_addc_u32 s1, s1, 0
	s_add_i32 s11, s46, -4
	v_or_b32_e32 v32, s11, v227
	v_max_i32_e32 v33, 0, v32
	v_max_i32_e32 v32, -4, v32
	v_min_i32_e32 v33, s43, v33
	v_add_u32_e32 v32, 4, v32
	v_bfe_u32 v239, v224, 2, 2
	v_min_u32_e32 v35, s43, v32
	v_lshlrev_b32_e32 v36, 4, v33
	v_or_b32_e32 v32, v36, v239
	v_lshrrev_b32_e32 v243, 8, v32
	v_and_b32_e32 v244, 15, v32
	v_lshlrev_b32_e32 v243, 18, v243
	v_lshl_or_b32 v243, v244, 11, v243
	v_bfe_u32 v244, v32, 6, 2
	v_lshl_or_b32 v243, v244, 9, v243
	v_bfe_u32 v244, v32, 4, 2
	v_lshl_or_b32 v144, v244, 5, v243
	v_bfe_u32 v238, v224, 4, 2
	v_lshl_add_u64 v[32:33], v[154:155], 0, v[144:145]
	s_ashr_i32 s4, s11, 2
	s_ashr_i32 s5, s4, 31
	v_lshlrev_b32_e32 v240, 3, v239
	v_lshlrev_b32_e32 v241, 3, v238
	s_movk_i32 s57, 0xff90
	s_add_i32 s47, s46, 0xffffff90
	s_add_i32 s56, s42, 4
	s_add_i32 s8, s42, 8
	s_add_i32 s10, s42, 12
	v_mov_b32_e32 v235, 0xf149f2ca
	s_mov_b32 s58, 4
	s_mov_b32 s59, 12
	s_waitcnt vmcnt(7)
	ds_write_b128 v228, v[0:3]
	s_waitcnt vmcnt(6)
	ds_write_b128 v228, v[4:7] offset:1024
	s_waitcnt vmcnt(5)
	ds_write_b128 v228, v[8:11] offset:2048
	s_waitcnt vmcnt(4)
	ds_write_b128 v228, v[12:15] offset:3072
	s_waitcnt vmcnt(3)
	ds_write_b128 v228, v[16:19] offset:4096
	s_waitcnt vmcnt(2)
	ds_write_b128 v228, v[20:23] offset:5120
	s_waitcnt vmcnt(1)
	ds_write_b128 v228, v[24:27] offset:6144
	s_waitcnt vmcnt(0)
; __device__ __forceinline__ KVB attn_load(int ks, const u16* __restrict__ kbase, const u16* __restrict__ vbase, int L16,
;                                          int r, int i0, int lane) {
;   KVB b;
;   const int quad = lane >> 4, l15 = lane & 15, gk = l15 >> 2, ek = l15 & 3;
;   int cK, sK; attn_desc(ks, gk, r, i0, cK, sK);
;   int ia = sK + ek, ib = ia + 4;
;   ia = min(max(ia, 0), L16 - 1); ib = min(max(ib, 0), L16 - 1);
;   const u16* ka = kbase + (size_t)(cK + 16 * ia) * 512;
;   const u16* kb = kbase + (size_t)(cK + 16 * ib) * 512;
;   b.k0 = *(const bf16x8*)ka; b.k1 = *(const bf16x8*)(ka + 8);
;   b.k2 = *(const bf16x8*)kb; b.k3 = *(const bf16x8*)(kb + 8);
;   int cV, sV; attn_desc(ks, quad, r, i0, cV, sV);
;   const u16* vp = vbase + ((ptrdiff_t)cV * (L16 >> 2) + (sV >> 2)) * 256 + l15 * 4;
;   {
;     union { struct { uint2 a, b; } p; bf16x8 v; } c0, c1, c2, c3;
;     c0.p.a = *(const uint2*)(vp);        c0.p.b = *(const uint2*)(vp + 256);
;     c1.p.a = *(const uint2*)(vp + 64);   c1.p.b = *(const uint2*)(vp + 64 + 256);
;     c2.p.a = *(const uint2*)(vp + 128);  c2.p.b = *(const uint2*)(vp + 128 + 256);
;     c3.p.a = *(const uint2*)(vp + 192);  c3.p.b = *(const uint2*)(vp + 192 + 256);
;     b.v0 = c0.v; b.v1 = c1.v; b.v2 = c2.v; b.v3 = c3.v;
;   }
;   return b;
; }
; template <int NT>
; __device__ void attn_unitN(const P& p, int u) {
;     ...
;   f32x4 o[NT][4];
;   float mrun[NT], lrun[NT];
; #pragma unroll
;   for (int t = 0; t < NT; ++t) {
;     const u16* qp = Qd + (size_t)(seq0 + rb + RS * t + 16 * iq) * 512 + h * 64 + quad * 16;
;     qs[t * 128] = *(const bf16x8*)qp; qs[t * 128 + 64] = *(const bf16x8*)(qp + 8);
; #pragma unroll
;     for (int dt = 0; dt < 4; ++dt) o[t][dt] = f32x4{0.f, 0.f, 0.f, 0.f};
;     mrun[t] = -1e30f; lrun[t] = 0.f;
;   }
;   const u16* kbase = Kd + (size_t)seq0 * 512 + h * 64 + quad * 16;
;   const u16* vbase = VdT + (size_t)seq0 * 512 + (size_t)h * 16 * 64 * L16;
;   KVB bA = attn_load_e<NT>(0, kbase, vbase, L16, rb, i0, lane);
;   KVB bB = attn_load_e<NT>(1, kbase, vbase, L16, rb, i0, lane);
	ds_write_b128 v228, v[28:31] offset:7168
	v_lshlrev_b32_e32 v2, 4, v35
	v_or_b32_e32 v0, v2, v239
	v_lshrrev_b32_e32 v243, 8, v0
	v_and_b32_e32 v244, 15, v0
	v_lshlrev_b32_e32 v243, 18, v243
	v_lshl_or_b32 v243, v244, 11, v243
	v_bfe_u32 v244, v0, 6, 2
	v_lshl_or_b32 v243, v244, 9, v243
	v_bfe_u32 v244, v0, 4, 2
	v_lshl_or_b32 v144, v244, 5, v243
	v_lshl_add_u64 v[0:1], v[154:155], 0, v[144:145]
	v_lshlrev_b32_e32 v144, s44, v238
	global_load_dwordx4 v[124:127], v[32:33], off
	global_load_dwordx4 v[120:123], v[32:33], off offset:16
	global_load_dwordx4 v[116:119], v[0:1], off
	global_load_dwordx4 v[112:115], v[0:1], off offset:16
	v_lshl_add_u64 v[0:1], s[4:5], 0, v[144:145]
	v_lshlrev_b64 v[0:1], 9, v[0:1]
	v_lshl_add_u64 v[0:1], s[0:1], 0, v[0:1]
	v_lshlrev_b32_e32 v144, 3, v34
	v_lshl_add_u64 v[0:1], v[0:1], 0, v[144:145]
	v_or_b32_e32 v3, 4, v239
	global_load_dwordx2 v[64:65], v[0:1], off
	global_load_dwordx2 v[68:69], v[0:1], off offset:128
	global_load_dwordx2 v[72:73], v[0:1], off offset:256
	global_load_dwordx2 v[76:77], v[0:1], off offset:384
	global_load_dwordx2 v[66:67], v[0:1], off offset:512
	global_load_dwordx2 v[70:71], v[0:1], off offset:640
	global_load_dwordx2 v[74:75], v[0:1], off offset:768
	global_load_dwordx2 v[78:79], v[0:1], off offset:896
	v_or_b32_e32 v0, v36, v3
	v_lshrrev_b32_e32 v243, 8, v0
	v_and_b32_e32 v244, 15, v0
	v_lshlrev_b32_e32 v243, 18, v243
	v_lshl_or_b32 v243, v244, 11, v243
	v_bfe_u32 v244, v0, 6, 2
	v_lshl_or_b32 v243, v244, 9, v243
	v_bfe_u32 v244, v0, 4, 2
	v_lshl_or_b32 v0, v244, 5, v243
	v_mov_b32_e32 v1, v145
	v_or_b32_e32 v2, v2, v3
	v_lshl_add_u64 v[0:1], v[154:155], 0, v[0:1]
	v_lshrrev_b32_e32 v243, 8, v2
	v_and_b32_e32 v244, 15, v2
	v_lshlrev_b32_e32 v243, 18, v243
	v_lshl_or_b32 v243, v244, 11, v243
	v_bfe_u32 v244, v2, 6, 2
	v_lshl_or_b32 v243, v244, 9, v243
	v_bfe_u32 v244, v2, 4, 2
	v_lshl_or_b32 v2, v244, 5, v243
	v_mov_b32_e32 v3, v145
	v_lshl_add_u64 v[2:3], v[154:155], 0, v[2:3]
	global_load_dwordx4 v[108:111], v[0:1], off
	global_load_dwordx4 v[104:107], v[0:1], off offset:16
	global_load_dwordx4 v[100:103], v[2:3], off
	global_load_dwordx4 v[96:99], v[2:3], off offset:16
	v_or_b32_e32 v0, 4, v238
	v_lshlrev_b32_e32 v0, s44, v0
	v_mov_b32_e32 v1, v145
	v_lshl_add_u64 v[0:1], s[4:5], 0, v[0:1]
	v_lshlrev_b64 v[0:1], 9, v[0:1]
	v_lshl_add_u64 v[0:1], s[0:1], 0, v[0:1]
	v_lshl_add_u64 v[0:1], v[0:1], 0, v[144:145]
	global_load_dwordx2 v[80:81], v[0:1], off
	global_load_dwordx2 v[84:85], v[0:1], off offset:128
	global_load_dwordx2 v[88:89], v[0:1], off offset:256
	global_load_dwordx2 v[92:93], v[0:1], off offset:384
	global_load_dwordx2 v[82:83], v[0:1], off offset:512
	global_load_dwordx2 v[86:87], v[0:1], off offset:640
	global_load_dwordx2 v[90:91], v[0:1], off offset:768
	global_load_dwordx2 v[94:95], v[0:1], off offset:896
	v_lshl_add_u64 v[158:159], s[0:1], 0, v[144:145]
	s_and_b32 s0, s42, 3
	v_and_or_b32 v229, v224, 12, s0
	v_lshl_or_b32 v230, v238, 2, s0
	s_add_i32 s0, s46, 0xfffffd80
	v_add_u32_e32 v231, s0, v240
	v_add_u32_e32 v232, s0, v241
	v_mov_b32_e32 v236, 0xf149f2ca
	v_mov_b32_e32 v237, 0xf149f2ca
	v_mov_b32_e32 v143, 0xf149f2ca
	s_mov_b32 s60, 0
	v_mov_b32_e32 v0, v145
	v_mov_b32_e32 v1, v145
	v_mov_b32_e32 v2, v145
	v_mov_b32_e32 v3, v145
	v_mov_b32_e32 v4, v145
	v_mov_b32_e32 v5, v145
	v_mov_b32_e32 v6, v145
	v_mov_b32_e32 v7, v145
	v_mov_b32_e32 v8, v145
	v_mov_b32_e32 v9, v145
	v_mov_b32_e32 v10, v145
	v_mov_b32_e32 v11, v145
	v_mov_b32_e32 v16, v145
	v_mov_b32_e32 v17, v145
	v_mov_b32_e32 v18, v145
	v_mov_b32_e32 v19, v145
	v_mov_b32_e32 v12, v145
	v_mov_b32_e32 v13, v145
	v_mov_b32_e32 v14, v145
	v_mov_b32_e32 v15, v145
	v_mov_b32_e32 v20, v145
	v_mov_b32_e32 v21, v145
	v_mov_b32_e32 v22, v145
	v_mov_b32_e32 v23, v145
	v_mov_b32_e32 v24, v145
	v_mov_b32_e32 v25, v145
	v_mov_b32_e32 v26, v145
	v_mov_b32_e32 v27, v145
	v_mov_b32_e32 v32, v145
	v_mov_b32_e32 v33, v145
	v_mov_b32_e32 v34, v145
	v_mov_b32_e32 v35, v145
	v_mov_b32_e32 v28, v145
	v_mov_b32_e32 v29, v145
	v_mov_b32_e32 v30, v145
	v_mov_b32_e32 v31, v145
	v_mov_b32_e32 v36, v145
	v_mov_b32_e32 v37, v145
	v_mov_b32_e32 v38, v145
	v_mov_b32_e32 v39, v145
	v_mov_b32_e32 v40, v145
	v_mov_b32_e32 v41, v145
	v_mov_b32_e32 v42, v145
	v_mov_b32_e32 v43, v145
	v_mov_b32_e32 v48, v145
	v_mov_b32_e32 v49, v145
	v_mov_b32_e32 v50, v145
	v_mov_b32_e32 v51, v145
	v_mov_b32_e32 v44, v145
	v_mov_b32_e32 v45, v145
	v_mov_b32_e32 v46, v145
	v_mov_b32_e32 v47, v145
	v_mov_b32_e32 v52, v145
	v_mov_b32_e32 v53, v145
	v_mov_b32_e32 v54, v145
	v_mov_b32_e32 v55, v145
	v_mov_b32_e32 v56, v145
	v_mov_b32_e32 v57, v145
	v_mov_b32_e32 v58, v145
	v_mov_b32_e32 v59, v145
	v_mov_b32_e32 v60, v145
	v_mov_b32_e32 v61, v145
	v_mov_b32_e32 v62, v145
	v_mov_b32_e32 v63, v145
	v_mov_b32_e32 v156, v145
	v_mov_b32_e32 v157, v145
	v_mov_b32_e32 v160, v145
	v_mov_b32_e32 v161, v145

; __device__ __forceinline__ KVB attn_load(int ks, const u16* __restrict__ kbase, const u16* __restrict__ vbase, int L16,
;                                          int r, int i0, int lane) {
;     ...
;   int cK, sK; attn_desc(ks, gk, r, i0, cK, sK);
;   int ia = sK + ek, ib = ia + 4;
;   ia = min(max(ia, 0), L16 - 1); ib = min(max(ib, 0), L16 - 1);
;   const u16* ka = kbase + (size_t)(cK + 16 * ia) * 512;
;   const u16* kb = kbase + (size_t)(cK + 16 * ib) * 512;
;   b.k0 = *(const bf16x8*)ka; b.k1 = *(const bf16x8*)(ka + 8);
;   b.k2 = *(const bf16x8*)kb; b.k3 = *(const bf16x8*)(kb + 8);
.LBB0_240:
	v_add_u32_e32 v64, v64, v227
	v_max_i32_e32 v66, 0, v64
	v_max_i32_e32 v64, -4, v64
	v_min_i32_e32 v66, s43, v66
	v_add_u32_e32 v64, 4, v64
	v_min_u32_e32 v64, s43, v64
	v_lshl_add_u32 v66, v66, 4, v65
	v_ashrrev_i32_e32 v67, 31, v66
	v_lshl_add_u32 v64, v64, 4, v65
	v_lshrrev_b32_e32 v243, 8, v66
	v_and_b32_e32 v244, 15, v66
	v_lshlrev_b32_e32 v243, 18, v243
	v_lshl_or_b32 v243, v244, 11, v243
	v_bfe_u32 v244, v66, 6, 2
	v_lshl_or_b32 v243, v244, 9, v243
	v_bfe_u32 v244, v66, 4, 2
	v_lshl_or_b32 v66, v244, 5, v243
	v_mov_b32_e32 v67, 0
	v_ashrrev_i32_e32 v65, 31, v64
	v_lshl_add_u64 v[66:67], v[154:155], 0, v[66:67]
	v_lshrrev_b32_e32 v243, 8, v64
	v_and_b32_e32 v244, 15, v64
	v_lshlrev_b32_e32 v243, 18, v243
	v_lshl_or_b32 v243, v244, 11, v243
	v_bfe_u32 v244, v64, 6, 2
	v_lshl_or_b32 v243, v244, 9, v243
	v_bfe_u32 v244, v64, 4, 2
	v_lshl_or_b32 v64, v244, 5, v243
	v_mov_b32_e32 v65, 0
	v_lshl_add_u64 v[64:65], v[154:155], 0, v[64:65]
	global_load_dwordx4 v[124:127], v[66:67], off
	global_load_dwordx4 v[120:123], v[66:67], off offset:16
	global_load_dwordx4 v[116:119], v[64:65], off
	global_load_dwordx4 v[112:115], v[64:65], off offset:16
	s_mov_b64 s[4:5], -1
	s_and_b64 vcc, exec, s[22:23]
	s_cbranch_vccz .LBB0_246
	s_and_b64 vcc, exec, s[20:21]
	s_cbranch_vccz .LBB0_243
	v_lshl_add_u32 v66, s62, 5, v232
	s_mov_b64 s[4:5], 0

; __device__ __forceinline__ KVB attn_load(int ks, const u16* __restrict__ kbase, const u16* __restrict__ vbase, int L16,
;                                          int r, int i0, int lane) {
;     ...
;   int cK, sK; attn_desc(ks, gk, r, i0, cK, sK);
;   int ia = sK + ek, ib = ia + 4;
;   ia = min(max(ia, 0), L16 - 1); ib = min(max(ib, 0), L16 - 1);
;   const u16* ka = kbase + (size_t)(cK + 16 * ia) * 512;
;   const u16* kb = kbase + (size_t)(cK + 16 * ib) * 512;
;   b.k0 = *(const bf16x8*)ka; b.k1 = *(const bf16x8*)(ka + 8);
;   b.k2 = *(const bf16x8*)kb; b.k3 = *(const bf16x8*)(kb + 8);
.LBB0_256:
	v_add_u32_e32 v80, v80, v227
	v_max_i32_e32 v82, 0, v80
	v_max_i32_e32 v80, -4, v80
	v_min_i32_e32 v82, s43, v82
	v_add_u32_e32 v80, 4, v80
	v_min_u32_e32 v80, s43, v80
	v_lshl_add_u32 v82, v82, 4, v81
	v_ashrrev_i32_e32 v83, 31, v82
	v_lshl_add_u32 v80, v80, 4, v81
	v_lshrrev_b32_e32 v243, 8, v82
	v_and_b32_e32 v244, 15, v82
	v_lshlrev_b32_e32 v243, 18, v243
	v_lshl_or_b32 v243, v244, 11, v243
	v_bfe_u32 v244, v82, 6, 2
	v_lshl_or_b32 v243, v244, 9, v243
	v_bfe_u32 v244, v82, 4, 2
	v_lshl_or_b32 v82, v244, 5, v243
	v_mov_b32_e32 v83, 0
	v_ashrrev_i32_e32 v81, 31, v80
	v_lshl_add_u64 v[82:83], v[154:155], 0, v[82:83]
	v_lshrrev_b32_e32 v243, 8, v80
	v_and_b32_e32 v244, 15, v80
	v_lshlrev_b32_e32 v243, 18, v243
	v_lshl_or_b32 v243, v244, 11, v243
	v_bfe_u32 v244, v80, 6, 2
	v_lshl_or_b32 v243, v244, 9, v243
	v_bfe_u32 v244, v80, 4, 2
	v_lshl_or_b32 v80, v244, 5, v243
	v_mov_b32_e32 v81, 0
	v_lshl_add_u64 v[80:81], v[154:155], 0, v[80:81]
	global_load_dwordx4 v[108:111], v[82:83], off
	global_load_dwordx4 v[104:107], v[82:83], off offset:16
	global_load_dwordx4 v[100:103], v[80:81], off
	global_load_dwordx4 v[96:99], v[80:81], off offset:16
	s_mov_b64 s[0:1], -1
	s_and_b64 vcc, exec, s[22:23]
	s_cbranch_vccz .LBB0_262
	s_and_b64 vcc, exec, s[4:5]
	s_cbranch_vccz .LBB0_259
	v_lshl_add_u32 v82, s61, 5, v232
	s_mov_b64 s[0:1], 0

; __device__ __forceinline__ void attn_step(int ks, const KVB& b, int L16, int r, int i0, int iq, int lane,
;                                           const bf16x8* qs, f32x4 (&o)[4], float& mrun, float& lrun) {
;   asm volatile("" : "+v"(lane), "+v"(iq));
;   asm volatile("" : "+s"(r), "+s"(i0));
;   const int quad = lane >> 4;
;   bf16x8 qB0 = qs[0], qB1 = qs[64];
;   int cV, sV; attn_desc(ks, quad, r, i0, cV, sV);
;   int D = ks < 12 ? 4 : (ks < 18 ? 16 : 64);
;   f32x4 z = {0.f, 0.f, 0.f, 0.f};
;   f32x4 sa = __builtin_amdgcn_mfma_f32_16x16x32_bf16(b.k0, qB0, z, 0, 0, 0);
;   sa = __builtin_amdgcn_mfma_f32_16x16x32_bf16(b.k1, qB1, sa, 0, 0, 0);
;   f32x4 sb = __builtin_amdgcn_mfma_f32_16x16x32_bf16(b.k2, qB0, z, 0, 0, 0);
;   sb = __builtin_amdgcn_mfma_f32_16x16x32_bf16(b.k3, qB1, sb, 0, 0, 0);
;   int jlo = max(iq - D + (cV < r ? 1 : 0), 0) - sV;
;   int jhi = min(iq + D - (cV > r ? 1 : 0), L16 - 1) - sV;
;   const float NINF = -__builtin_inff();
;   float s8[8];
;   float mt = -1e30f;
; #pragma unroll
;   for (int j = 0; j < 8; ++j) {
;     float sv = j < 4 ? sa[j] : sb[j - 4];
;     sv = (j >= jlo && j <= jhi) ? sv : NINF;
;     s8[j] = sv;
;     mt = fmaxf(mt, sv);
;   }
;   mt = fmaxf(mt, __shfl_xor(mt, 16));
;   mt = fmaxf(mt, __shfl_xor(mt, 32));
;   float mnew = fmaxf(mrun, mt);
;   float alpha = __builtin_amdgcn_exp2f(mrun - mnew);
;   mrun = mnew;
;   float ps = 0.f;
;   float p8[8];
; #pragma unroll
;   for (int j = 0; j < 8; ++j) { p8[j] = __builtin_amdgcn_exp2f(s8[j] - mnew); ps += p8[j]; }
;   lrun = lrun * alpha + ps;
;   union { uint4 u; bf16x8 v; } pb;
;   pb.u = make_uint4(pack2(p8[0], p8[1]), pack2(p8[2], p8[3]), pack2(p8[4], p8[5]), pack2(p8[6], p8[7]));
; #pragma unroll
;   for (int dt = 0; dt < 4; ++dt) { o[dt][0] *= alpha; o[dt][1] *= alpha; o[dt][2] *= alpha; o[dt][3] *= alpha; }
;   o[0] = __builtin_amdgcn_mfma_f32_16x16x32_bf16(b.v0, pb.v, o[0], 0, 0, 0);
;   o[1] = __builtin_amdgcn_mfma_f32_16x16x32_bf16(b.v1, pb.v, o[1], 0, 0, 0);
;   o[2] = __builtin_amdgcn_mfma_f32_16x16x32_bf16(b.v2, pb.v, o[2], 0, 0, 0);
;   o[3] = __builtin_amdgcn_mfma_f32_16x16x32_bf16(b.v3, pb.v, o[3], 0, 0, 0);
; }
; template <int NT>
; __device__ void attn_unitN(const P& p, int u) {
;     ...
;   for (int kk = 0; kk < 5; ++kk) {
;     int e0 = 18 + NT * kk, ks = 18 + kk;
; #pragma unroll
;     for (int t = 0; t < NT; t += 2) {
.LBB0_267:
	v_mov_b32_e32 v136, v226
	v_mov_b32_e32 v137, v225
	s_mov_b32 s0, s42
	s_mov_b32 s1, s46
	ds_read_b128 v[128:131], v228
	ds_read_b128 v[132:135], v228 offset:1024
	s_waitcnt vmcnt(21) lgkmcnt(1)
	v_mfma_f32_16x16x32_bf16 v[116:119], v[116:119], v[128:131], 0
	v_ashrrev_i32_e32 v136, 4, v136
	s_sub_i32 s0, s1, 64
	v_add_u32_e32 v136, s11, v136
	v_mfma_f32_16x16x32_bf16 v[124:127], v[124:127], v[128:131], 0
	v_lshl_add_u32 v136, v136, 3, s0
	v_ashrrev_i32_e32 v192, 2, v180
	v_ashrrev_i32_e32 v193, 31, v192
	s_waitcnt vmcnt(20) lgkmcnt(0)
	v_mfma_f32_16x16x32_bf16 v[112:115], v[112:115], v[132:135], v[116:119]
	v_lshl_add_u64 v[128:129], s[4:5], 0, v[192:193]
	v_lshlrev_b64 v[128:129], 9, v[128:129]
	v_mov_b32_e32 v162, v225
	v_subrev_u32_e32 v116, 64, v137
	v_add_u32_e32 v117, 64, v137
	v_mfma_f32_16x16x32_bf16 v[120:123], v[120:123], v[132:135], v[124:127]
	v_max_i32_e32 v116, 0, v116
	v_min_i32_e32 v117, s43, v117
	v_sub_u32_e32 v116, v116, v136
	v_sub_u32_e32 v117, v117, v136
	v_cmp_lt_i32_e32 vcc, 0, v116
	v_cmp_gt_i32_e64 s[0:1], 0, v117
	s_or_b64 vcc, vcc, s[0:1]
	s_nop 0
	v_cndmask_b32_e32 v118, v120, v219, vcc
	v_cmp_lt_i32_e32 vcc, 1, v116
	v_cmp_gt_i32_e64 s[0:1], 1, v117
	s_or_b64 vcc, vcc, s[0:1]
	v_cndmask_b32_e32 v119, v121, v219, vcc
	v_cmp_lt_i32_e32 vcc, 2, v116
	v_cmp_gt_i32_e64 s[0:1], 2, v117
	s_or_b64 vcc, vcc, s[0:1]
	v_cndmask_b32_e32 v121, v122, v219, vcc
	v_cmp_lt_i32_e32 vcc, 3, v116
	v_cmp_gt_i32_e64 s[0:1], 3, v117
	s_or_b64 vcc, vcc, s[0:1]
	v_cndmask_b32_e32 v122, v123, v219, vcc
	v_cmp_lt_i32_e32 vcc, 4, v116
	v_cmp_gt_i32_e64 s[0:1], 4, v117
	s_or_b64 vcc, vcc, s[0:1]
	v_cndmask_b32_e32 v112, v112, v219, vcc
	v_cmp_lt_i32_e32 vcc, 5, v116
	v_cmp_gt_i32_e64 s[0:1], 5, v117
	s_or_b64 vcc, vcc, s[0:1]
	v_cndmask_b32_e32 v113, v113, v219, vcc
	v_cmp_lt_i32_e32 vcc, 6, v116
	v_cmp_gt_i32_e64 s[0:1], 6, v117
	s_or_b64 vcc, vcc, s[0:1]
	v_max3_f32 v120, v118, s41, v119
	v_cndmask_b32_e32 v114, v114, v219, vcc
	v_cmp_lt_i32_e32 vcc, 7, v116
	v_cmp_gt_i32_e64 s[0:1], 7, v117
	v_max3_f32 v120, v120, v121, v122
	s_or_b64 vcc, vcc, s[0:1]
	v_max3_f32 v120, v120, v112, v113
	v_cndmask_b32_e32 v115, v115, v219, vcc
	v_max3_f32 v116, v120, v114, v115
	ds_bpermute_b32 v117, v233, v116
	s_mov_b32 s0, s56
	s_mov_b32 s1, s46
	s_add_i32 s22, s11, 20
	v_add_u32_e32 v180, 32, v180
	s_waitcnt lgkmcnt(0)
	v_max_f32_e32 v117, v117, v117
	v_max_f32_e32 v116, v116, v117
	ds_bpermute_b32 v117, v234, v116
	s_waitcnt lgkmcnt(0)
	v_max3_f32 v182, v143, v116, v117
	v_sub_f32_e32 v112, v112, v182
	v_exp_f32_e32 v171, v112
	v_sub_f32_e32 v112, v113, v182
	v_exp_f32_e32 v173, v112
	v_sub_f32_e32 v112, v114, v182
	v_exp_f32_e32 v175, v112
	v_sub_f32_e32 v112, v115, v182
	v_exp_f32_e32 v177, v112
	v_max_i32_e32 v112, 0, v181
	v_max_i32_e32 v113, -4, v181
	v_sub_f32_e32 v117, v118, v182
	v_min_i32_e32 v112, s43, v112
	v_add_u32_e32 v113, 4, v113
	v_exp_f32_e32 v163, v117
	v_sub_f32_e32 v117, v119, v182
	v_min_u32_e32 v114, s43, v113
	v_lshlrev_b32_e32 v194, 4, v112
	v_exp_f32_e32 v165, v117
	v_sub_f32_e32 v117, v121, v182
	v_add_u32_e32 v144, s8, v194
	v_lshlrev_b32_e32 v195, 4, v114
	v_sub_f32_e32 v116, v143, v182
	v_exp_f32_e32 v167, v117
	v_sub_f32_e32 v117, v122, v182
	v_lshrrev_b32_e32 v243, 8, v144
	v_and_b32_e32 v244, 15, v144
	v_lshlrev_b32_e32 v243, 18, v243
	v_lshl_or_b32 v243, v244, 11, v243
	v_bfe_u32 v244, v144, 6, 2
	v_lshl_or_b32 v243, v244, 9, v243
	v_bfe_u32 v244, v144, 4, 2
	v_lshl_or_b32 v112, v244, 5, v243
	v_mov_b32_e32 v113, 0
	v_add_u32_e32 v144, s8, v195
	v_exp_f32_e32 v169, v117
	v_exp_f32_e32 v179, v116
	v_lshl_add_u64 v[116:117], v[154:155], 0, v[112:113]
	v_lshrrev_b32_e32 v243, 8, v144
	v_and_b32_e32 v244, 15, v144
	v_lshlrev_b32_e32 v243, 18, v243
	v_lshl_or_b32 v243, v244, 11, v243
	v_bfe_u32 v244, v144, 6, 2
	v_lshl_or_b32 v243, v244, 9, v243
	v_bfe_u32 v244, v144, 4, 2
	v_lshl_or_b32 v112, v244, 5, v243
	v_mov_b32_e32 v113, 0
	v_lshl_add_u64 v[124:125], v[154:155], 0, v[112:113]
	global_load_dwordx4 v[112:115], v[116:117], off
	s_nop 0
	global_load_dwordx4 v[116:119], v[116:117], off offset:16
	s_nop 0
	global_load_dwordx4 v[120:123], v[124:125], off
	s_nop 0
	global_load_dwordx4 v[124:127], v[124:125], off offset:16
	v_lshl_add_u64 v[142:143], v[158:159], 0, v[128:129]
	v_mov_b32_e32 v144, v226
	global_load_dwordx2 v[128:129], v[142:143], off
	global_load_dwordx2 v[130:131], v[142:143], off offset:512
	global_load_dwordx2 v[132:133], v[142:143], off offset:128
	global_load_dwordx2 v[134:135], v[142:143], off offset:640
	global_load_dwordx2 v[136:137], v[142:143], off offset:256
	global_load_dwordx2 v[138:139], v[142:143], off offset:768
	global_load_dwordx2 v[140:141], v[142:143], off offset:384
	s_nop 0
	global_load_dwordx2 v[142:143], v[142:143], off offset:896
	ds_read_b128 v[184:187], v228 offset:2048
	ds_read_b128 v[188:191], v228 offset:3072
	s_waitcnt vmcnt(21) lgkmcnt(1)
	v_mfma_f32_16x16x32_bf16 v[100:103], v[100:103], v[184:187], 0
	v_ashrrev_i32_e32 v144, 4, v144
	s_sub_i32 s0, s1, 64
	v_add_u32_e32 v144, s11, v144
	v_mfma_f32_16x16x32_bf16 v[108:111], v[108:111], v[184:187], 0
	v_lshl_add_u32 v144, v144, 3, s0
	v_add_u32_e32 v181, 32, v181
	s_waitcnt vmcnt(20) lgkmcnt(0)
; __device__ __forceinline__ void attn_step(int ks, const KVB& b, int L16, int r, int i0, int iq, int lane,
;                                           const bf16x8* qs, f32x4 (&o)[4], float& mrun, float& lrun) {
;   asm volatile("" : "+v"(lane), "+v"(iq));
;   asm volatile("" : "+s"(r), "+s"(i0));
;   const int quad = lane >> 4;
;   bf16x8 qB0 = qs[0], qB1 = qs[64];
;   int cV, sV; attn_desc(ks, quad, r, i0, cV, sV);
;   int D = ks < 12 ? 4 : (ks < 18 ? 16 : 64);
;   f32x4 z = {0.f, 0.f, 0.f, 0.f};
;   f32x4 sa = __builtin_amdgcn_mfma_f32_16x16x32_bf16(b.k0, qB0, z, 0, 0, 0);
;   sa = __builtin_amdgcn_mfma_f32_16x16x32_bf16(b.k1, qB1, sa, 0, 0, 0);
;   f32x4 sb = __builtin_amdgcn_mfma_f32_16x16x32_bf16(b.k2, qB0, z, 0, 0, 0);
;   sb = __builtin_amdgcn_mfma_f32_16x16x32_bf16(b.k3, qB1, sb, 0, 0, 0);
;   int jlo = max(iq - D + (cV < r ? 1 : 0), 0) - sV;
;   int jhi = min(iq + D - (cV > r ? 1 : 0), L16 - 1) - sV;
;   const float NINF = -__builtin_inff();
;   float s8[8];
;   float mt = -1e30f;
; #pragma unroll
;   for (int j = 0; j < 8; ++j) {
;     float sv = j < 4 ? sa[j] : sb[j - 4];
;     sv = (j >= jlo && j <= jhi) ? sv : NINF;
;     s8[j] = sv;
;     mt = fmaxf(mt, sv);
;   }
;   mt = fmaxf(mt, __shfl_xor(mt, 16));
;   mt = fmaxf(mt, __shfl_xor(mt, 32));
;   float mnew = fmaxf(mrun, mt);
;   float alpha = __builtin_amdgcn_exp2f(mrun - mnew);
;   mrun = mnew;
;   float ps = 0.f;
;   float p8[8];
; #pragma unroll
;   for (int j = 0; j < 8; ++j) { p8[j] = __builtin_amdgcn_exp2f(s8[j] - mnew); ps += p8[j]; }
;   lrun = lrun * alpha + ps;
;   union { uint4 u; bf16x8 v; } pb;
;   pb.u = make_uint4(pack2(p8[0], p8[1]), pack2(p8[2], p8[3]), pack2(p8[4], p8[5]), pack2(p8[6], p8[7]));
; #pragma unroll
;   for (int dt = 0; dt < 4; ++dt) { o[dt][0] *= alpha; o[dt][1] *= alpha; o[dt][2] *= alpha; o[dt][3] *= alpha; }
;   o[0] = __builtin_amdgcn_mfma_f32_16x16x32_bf16(b.v0, pb.v, o[0], 0, 0, 0);
;   o[1] = __builtin_amdgcn_mfma_f32_16x16x32_bf16(b.v1, pb.v, o[1], 0, 0, 0);
;   o[2] = __builtin_amdgcn_mfma_f32_16x16x32_bf16(b.v2, pb.v, o[2], 0, 0, 0);
;   o[3] = __builtin_amdgcn_mfma_f32_16x16x32_bf16(b.v3, pb.v, o[3], 0, 0, 0);
; }
; template <int NT>
; __device__ void attn_unitN(const P& p, int u) {
;     ...
;   for (int kk = 0; kk < 5; ++kk) {
;     int e0 = 18 + NT * kk, ks = 18 + kk;
; #pragma unroll
;     for (int t = 0; t < NT; t += 2) {
	v_mfma_f32_16x16x32_bf16 v[96:99], v[96:99], v[188:191], v[100:103]
	s_nop 2
	v_subrev_u32_e32 v100, 64, v162
	v_add_u32_e32 v101, 64, v162
	v_mfma_f32_16x16x32_bf16 v[104:107], v[104:107], v[188:191], v[108:111]
	v_max_i32_e32 v100, 0, v100
	v_min_i32_e32 v101, s43, v101
	v_sub_u32_e32 v100, v100, v144
	v_sub_u32_e32 v101, v101, v144
	v_cmp_lt_i32_e32 vcc, 0, v100
	v_cmp_gt_i32_e64 s[0:1], 0, v101
	s_or_b64 vcc, vcc, s[0:1]
	s_nop 0
	v_cndmask_b32_e32 v102, v104, v219, vcc
	v_cmp_lt_i32_e32 vcc, 1, v100
	v_cmp_gt_i32_e64 s[0:1], 1, v101
	s_or_b64 vcc, vcc, s[0:1]
	v_cndmask_b32_e32 v103, v105, v219, vcc
	v_cmp_lt_i32_e32 vcc, 2, v100
	v_cmp_gt_i32_e64 s[0:1], 2, v101
	s_or_b64 vcc, vcc, s[0:1]
	v_cndmask_b32_e32 v105, v106, v219, vcc
	v_cmp_lt_i32_e32 vcc, 3, v100
	v_cmp_gt_i32_e64 s[0:1], 3, v101
	s_or_b64 vcc, vcc, s[0:1]
	v_cndmask_b32_e32 v106, v107, v219, vcc
	v_cmp_lt_i32_e32 vcc, 4, v100
	v_cmp_gt_i32_e64 s[0:1], 4, v101
	s_or_b64 vcc, vcc, s[0:1]
	v_cndmask_b32_e32 v96, v96, v219, vcc
	v_cmp_lt_i32_e32 vcc, 5, v100
	v_cmp_gt_i32_e64 s[0:1], 5, v101
	s_or_b64 vcc, vcc, s[0:1]
	v_cndmask_b32_e32 v97, v97, v219, vcc
	v_cmp_lt_i32_e32 vcc, 6, v100
	v_cmp_gt_i32_e64 s[0:1], 6, v101
	s_or_b64 vcc, vcc, s[0:1]
	v_max3_f32 v104, v102, s41, v103
	v_cndmask_b32_e32 v98, v98, v219, vcc
	v_cmp_lt_i32_e32 vcc, 7, v100
	v_cmp_gt_i32_e64 s[0:1], 7, v101
	v_max3_f32 v104, v104, v105, v106
	s_or_b64 vcc, vcc, s[0:1]
	v_max3_f32 v104, v104, v96, v97
	v_cndmask_b32_e32 v99, v99, v219, vcc
	v_max3_f32 v100, v104, v98, v99
	ds_bpermute_b32 v101, v233, v100
	v_add_u32_e32 v144, s10, v194
	s_mov_b32 s0, s8
	s_mov_b32 s1, s46
	s_waitcnt lgkmcnt(0)
	v_max_f32_e32 v101, v101, v101
	v_max_f32_e32 v100, v100, v101
	ds_bpermute_b32 v101, v234, v100
	s_waitcnt lgkmcnt(0)
	v_max3_f32 v183, v237, v100, v101
	v_sub_f32_e32 v101, v102, v183
	v_exp_f32_e32 v162, v101
	v_sub_f32_e32 v101, v103, v183
	v_sub_f32_e32 v96, v96, v183
	v_exp_f32_e32 v164, v101
	v_sub_f32_e32 v101, v105, v183
	v_exp_f32_e32 v170, v96
	v_sub_f32_e32 v96, v97, v183
	v_exp_f32_e32 v166, v101
	v_sub_f32_e32 v101, v106, v183
	v_exp_f32_e32 v172, v96
	v_sub_f32_e32 v96, v98, v183
	v_exp_f32_e32 v168, v101
	v_exp_f32_e32 v174, v96
	v_sub_f32_e32 v96, v99, v183
	v_exp_f32_e32 v176, v96
	v_pk_add_f32 v[96:97], v[162:163], 0 op_sel_hi:[1,0]
	v_sub_f32_e32 v100, v237, v183
	v_pk_add_f32 v[96:97], v[164:165], v[96:97]
	v_exp_f32_e32 v178, v100
	v_pk_add_f32 v[96:97], v[166:167], v[96:97]
	v_cvt_pk_bf16_f32 v98, v171, v173
	v_pk_add_f32 v[96:97], v[168:169], v[96:97]
	v_cvt_pk_bf16_f32 v99, v175, v177
	v_pk_add_f32 v[96:97], v[170:171], v[96:97]
	v_pk_mul_f32 v[50:51], v[50:51], v[178:179] op_sel_hi:[1,0]
	v_pk_add_f32 v[96:97], v[172:173], v[96:97]
	v_pk_mul_f32 v[48:49], v[48:49], v[178:179] op_sel_hi:[1,0]
	v_pk_add_f32 v[96:97], v[174:175], v[96:97]
	v_pk_mul_f32 v[42:43], v[42:43], v[178:179] op_sel_hi:[1,0]
	v_pk_add_f32 v[100:101], v[176:177], v[96:97]
	v_mov_b32_e32 v96, v179
	v_pk_mul_f32 v[62:63], v[62:63], v[96:97] op_sel_hi:[1,0]
	v_pk_mul_f32 v[60:61], v[60:61], v[96:97] op_sel_hi:[1,0]
	v_pk_mul_f32 v[58:59], v[58:59], v[96:97] op_sel_hi:[1,0]
	v_pk_mul_f32 v[56:57], v[56:57], v[96:97] op_sel_hi:[1,0]
	v_pk_mul_f32 v[54:55], v[54:55], v[96:97] op_sel_hi:[1,0]
	v_pk_mul_f32 v[52:53], v[52:53], v[96:97] op_sel_hi:[1,0]
	v_pk_mul_f32 v[46:47], v[46:47], v[96:97] op_sel_hi:[1,0]
	v_pk_mul_f32 v[44:45], v[44:45], v[96:97] op_sel_hi:[1,0]
	v_cvt_pk_bf16_f32 v96, v163, v165
	v_cvt_pk_bf16_f32 v97, v167, v169
	v_pk_mul_f32 v[40:41], v[40:41], v[178:179] op_sel_hi:[1,0]
	v_pk_mul_f32 v[38:39], v[38:39], v[178:179] op_sel_hi:[1,0]
	v_mfma_f32_16x16x32_bf16 v[60:63], v[64:67], v[96:99], v[60:63]
	v_mul_f32_e64 v36, v36, v178
	v_mul_f32_e64 v37, v37, v178
	v_pk_mul_f32 v[30:31], v[30:31], v[178:179] op_sel_hi:[1,0]
	v_pk_mul_f32 v[28:29], v[28:29], v[178:179] op_sel_hi:[1,0]
	v_cvt_pk_bf16_f32 v64, v162, v164
	v_cvt_pk_bf16_f32 v65, v166, v168
	v_cvt_pk_bf16_f32 v66, v170, v172
	v_cvt_pk_bf16_f32 v67, v174, v176
	v_mfma_f32_16x16x32_bf16 v[56:59], v[68:71], v[96:99], v[56:59]
	v_fma_f32 v160, v160, v178, v100
	v_fma_f32 v161, v161, v179, v101
	v_mov_b32_e32 v162, v226
	v_mov_b32_e32 v164, v225
	s_waitcnt vmcnt(15)
	v_mfma_f32_16x16x32_bf16 v[48:51], v[80:83], v[64:67], v[48:51]
	v_mov_b32_e32 v237, v183
	s_waitcnt vmcnt(14)
	v_mfma_f32_16x16x32_bf16 v[40:43], v[84:87], v[64:67], v[40:43]
	s_waitcnt vmcnt(13)
	v_mfma_f32_16x16x32_bf16 v[36:39], v[88:91], v[64:67], v[36:39]
	s_waitcnt vmcnt(12)
	v_mfma_f32_16x16x32_bf16 v[28:31], v[92:95], v[64:67], v[28:31]
	v_lshrrev_b32_e32 v243, 8, v144
	v_and_b32_e32 v244, 15, v144
	v_lshlrev_b32_e32 v243, 18, v243
	v_lshl_or_b32 v243, v244, 11, v243
	v_bfe_u32 v244, v144, 6, 2
	v_lshl_or_b32 v243, v244, 9, v243
	v_bfe_u32 v244, v144, 4, 2
	v_lshl_or_b32 v64, v244, 5, v243
	v_mov_b32_e32 v65, 0
	v_add_u32_e32 v144, s10, v195
	v_lshl_add_u64 v[64:65], v[154:155], 0, v[64:65]
	v_lshrrev_b32_e32 v243, 8, v144
	v_and_b32_e32 v244, 15, v144
	v_lshlrev_b32_e32 v243, 18, v243
	v_lshl_or_b32 v243, v244, 11, v243
	v_bfe_u32 v244, v144, 6, 2
	v_lshl_or_b32 v243, v244, 9, v243
	v_bfe_u32 v244, v144, 4, 2
	v_lshl_or_b32 v66, v244, 5, v243
	v_mov_b32_e32 v67, 0
	v_mfma_f32_16x16x32_bf16 v[52:55], v[72:75], v[96:99], v[52:55]
	v_lshl_add_u64 v[66:67], v[154:155], 0, v[66:67]
	v_mov_b32_e32 v72, v226
	v_mfma_f32_16x16x32_bf16 v[44:47], v[76:79], v[96:99], v[44:47]
	global_load_dwordx4 v[96:99], v[64:65], off
	global_load_dwordx4 v[100:103], v[64:65], off offset:16
	global_load_dwordx4 v[104:107], v[66:67], off
	global_load_dwordx4 v[108:111], v[66:67], off offset:16
	v_lshl_add_u64 v[64:65], s[20:21], 0, v[192:193]
	v_lshlrev_b64 v[64:65], 9, v[64:65]
	v_lshl_add_u64 v[64:65], v[158:159], 0, v[64:65]
	v_mov_b32_e32 v76, v225
	global_load_dwordx2 v[80:81], v[64:65], off
	global_load_dwordx2 v[82:83], v[64:65], off offset:512
	global_load_dwordx2 v[84:85], v[64:65], off offset:128
	global_load_dwordx2 v[86:87], v[64:65], off offset:640
	global_load_dwordx2 v[88:89], v[64:65], off offset:256
	global_load_dwordx2 v[90:91], v[64:65], off offset:768
	global_load_dwordx2 v[92:93], v[64:65], off offset:384
	global_load_dwordx2 v[94:95], v[64:65], off offset:896
	ds_read_b128 v[64:67], v228 offset:4096
	ds_read_b128 v[68:71], v228 offset:5120
	v_ashrrev_i32_e32 v72, 4, v72
	s_sub_i32 s0, s1, 64
	v_add_u32_e32 v72, s11, v72
	v_lshl_add_u32 v77, v72, 3, s0
	s_waitcnt vmcnt(23) lgkmcnt(1)
; __device__ __forceinline__ void attn_step(int ks, const KVB& b, int L16, int r, int i0, int iq, int lane,
;                                           const bf16x8* qs, f32x4 (&o)[4], float& mrun, float& lrun) {
;   asm volatile("" : "+v"(lane), "+v"(iq));
;   asm volatile("" : "+s"(r), "+s"(i0));
;   const int quad = lane >> 4;
;   bf16x8 qB0 = qs[0], qB1 = qs[64];
;   int cV, sV; attn_desc(ks, quad, r, i0, cV, sV);
;   int D = ks < 12 ? 4 : (ks < 18 ? 16 : 64);
;   f32x4 z = {0.f, 0.f, 0.f, 0.f};
;   f32x4 sa = __builtin_amdgcn_mfma_f32_16x16x32_bf16(b.k0, qB0, z, 0, 0, 0);
;   sa = __builtin_amdgcn_mfma_f32_16x16x32_bf16(b.k1, qB1, sa, 0, 0, 0);
;   f32x4 sb = __builtin_amdgcn_mfma_f32_16x16x32_bf16(b.k2, qB0, z, 0, 0, 0);
;   sb = __builtin_amdgcn_mfma_f32_16x16x32_bf16(b.k3, qB1, sb, 0, 0, 0);
;   int jlo = max(iq - D + (cV < r ? 1 : 0), 0) - sV;
;   int jhi = min(iq + D - (cV > r ? 1 : 0), L16 - 1) - sV;
;   const float NINF = -__builtin_inff();
;   float s8[8];
;   float mt = -1e30f;
; #pragma unroll
;   for (int j = 0; j < 8; ++j) {
;     float sv = j < 4 ? sa[j] : sb[j - 4];
;     sv = (j >= jlo && j <= jhi) ? sv : NINF;
;     s8[j] = sv;
;     mt = fmaxf(mt, sv);
;   }
;   mt = fmaxf(mt, __shfl_xor(mt, 16));
;   mt = fmaxf(mt, __shfl_xor(mt, 32));
;   float mnew = fmaxf(mrun, mt);
;   float alpha = __builtin_amdgcn_exp2f(mrun - mnew);
;   mrun = mnew;
;   float ps = 0.f;
;   float p8[8];
; #pragma unroll
;   for (int j = 0; j < 8; ++j) { p8[j] = __builtin_amdgcn_exp2f(s8[j] - mnew); ps += p8[j]; }
;   lrun = lrun * alpha + ps;
;   union { uint4 u; bf16x8 v; } pb;
;   pb.u = make_uint4(pack2(p8[0], p8[1]), pack2(p8[2], p8[3]), pack2(p8[4], p8[5]), pack2(p8[6], p8[7]));
; #pragma unroll
;   for (int dt = 0; dt < 4; ++dt) { o[dt][0] *= alpha; o[dt][1] *= alpha; o[dt][2] *= alpha; o[dt][3] *= alpha; }
;   o[0] = __builtin_amdgcn_mfma_f32_16x16x32_bf16(b.v0, pb.v, o[0], 0, 0, 0);
;   o[1] = __builtin_amdgcn_mfma_f32_16x16x32_bf16(b.v1, pb.v, o[1], 0, 0, 0);
;   o[2] = __builtin_amdgcn_mfma_f32_16x16x32_bf16(b.v2, pb.v, o[2], 0, 0, 0);
;   o[3] = __builtin_amdgcn_mfma_f32_16x16x32_bf16(b.v3, pb.v, o[3], 0, 0, 0);
; }
; template <int NT>
; __device__ void attn_unitN(const P& p, int u) {
;     ...
;   for (int kk = 0; kk < 5; ++kk) {
;     int e0 = 18 + NT * kk, ks = 18 + kk;
; #pragma unroll
;     for (int t = 0; t < NT; t += 2) {
	v_mfma_f32_16x16x32_bf16 v[72:75], v[112:115], v[64:67], 0
	s_waitcnt vmcnt(21)
	v_mfma_f32_16x16x32_bf16 v[64:67], v[120:123], v[64:67], 0
	s_waitcnt lgkmcnt(0)
	v_mfma_f32_16x16x32_bf16 v[72:75], v[116:119], v[68:71], v[72:75]
	s_waitcnt vmcnt(20)
	v_mfma_f32_16x16x32_bf16 v[64:67], v[124:127], v[68:71], v[64:67]
	v_subrev_u32_e32 v68, 64, v76
	v_add_u32_e32 v69, 64, v76
	v_max_i32_e32 v68, 0, v68
	v_min_i32_e32 v69, s43, v69
	v_sub_u32_e32 v68, v68, v77
	v_sub_u32_e32 v69, v69, v77
	v_cmp_lt_i32_e32 vcc, 0, v68
	v_cmp_gt_i32_e64 s[0:1], 0, v69
	s_or_b64 vcc, vcc, s[0:1]
	v_cndmask_b32_e32 v70, v72, v219, vcc
	v_cmp_lt_i32_e32 vcc, 1, v68
	v_cmp_gt_i32_e64 s[0:1], 1, v69
	s_or_b64 vcc, vcc, s[0:1]
	v_cndmask_b32_e32 v71, v73, v219, vcc
	v_cmp_lt_i32_e32 vcc, 2, v68
	v_cmp_gt_i32_e64 s[0:1], 2, v69
	s_or_b64 vcc, vcc, s[0:1]
	v_cndmask_b32_e32 v73, v74, v219, vcc
	v_cmp_lt_i32_e32 vcc, 3, v68
	v_cmp_gt_i32_e64 s[0:1], 3, v69
	s_or_b64 vcc, vcc, s[0:1]
	v_cndmask_b32_e32 v74, v75, v219, vcc
	v_cmp_lt_i32_e32 vcc, 4, v68
	v_cmp_gt_i32_e64 s[0:1], 4, v69
	s_or_b64 vcc, vcc, s[0:1]
	v_cndmask_b32_e32 v64, v64, v219, vcc
	v_cmp_lt_i32_e32 vcc, 5, v68
	v_cmp_gt_i32_e64 s[0:1], 5, v69
	s_or_b64 vcc, vcc, s[0:1]
	v_cndmask_b32_e32 v65, v65, v219, vcc
	v_cmp_lt_i32_e32 vcc, 6, v68
	v_cmp_gt_i32_e64 s[0:1], 6, v69
	s_or_b64 vcc, vcc, s[0:1]
	v_max3_f32 v72, v70, s41, v71
	v_cndmask_b32_e32 v66, v66, v219, vcc
	v_cmp_lt_i32_e32 vcc, 7, v68
	v_cmp_gt_i32_e64 s[0:1], 7, v69
	v_max3_f32 v72, v72, v73, v74
	s_or_b64 vcc, vcc, s[0:1]
	v_max3_f32 v72, v72, v64, v65
	v_cndmask_b32_e32 v67, v67, v219, vcc
	v_max3_f32 v68, v72, v66, v67
	ds_bpermute_b32 v69, v233, v68
	s_min_i32 s0, s22, 35
	s_add_i32 s0, s0, -16
	s_ashr_i32 s1, s0, 31
	s_lshr_b32 s1, s1, 30
	s_waitcnt lgkmcnt(0)
	v_max_f32_e32 v69, v69, v69
	v_max_f32_e32 v68, v68, v69
	ds_bpermute_b32 v69, v234, v68
	s_add_i32 s1, s0, s1
	s_ashr_i32 s23, s1, 2
	s_and_b32 s1, s1, 0x3ffffffc
	s_sub_i32 s0, s0, s1
	s_waitcnt lgkmcnt(0)
	v_max3_f32 v144, v236, v68, v69
	s_lshl_b32 s0, s0, 2
	v_sub_f32_e32 v69, v70, v144
	v_sub_f32_e32 v64, v64, v144
	s_add_i32 s24, s23, 18
	s_add_i32 s0, s0, s42
	v_exp_f32_e32 v163, v69
	v_sub_f32_e32 v69, v71, v144
	v_exp_f32_e32 v171, v64
	v_sub_f32_e32 v64, v65, v144
	s_cmp_gt_u32 s23, 0xffffffed
	v_exp_f32_e32 v165, v69
	v_sub_f32_e32 v69, v73, v144
	v_exp_f32_e32 v173, v64
	v_sub_f32_e32 v64, v66, v144
	s_cselect_b64 vcc, -1, 0
	s_lshl_b32 s1, s24, 3
	v_exp_f32_e32 v167, v69
	v_sub_f32_e32 v69, v74, v144
	v_exp_f32_e32 v175, v64
	v_sub_f32_e32 v64, v67, v144
	s_add_i32 s1, s1, s47
	s_lshl_b32 s23, s24, 5
	v_exp_f32_e32 v169, v69
	v_exp_f32_e32 v177, v64
	v_add_u32_e32 v64, s23, v231
	v_mov_b32_e32 v69, s1
	v_cndmask_b32_e32 v64, v64, v69, vcc
	v_sub_f32_e32 v68, v236, v144
	v_add_u32_e32 v64, v64, v227
	v_exp_f32_e32 v179, v68
	v_mov_b32_e32 v68, s0
	v_max_i32_e32 v65, 0, v64
	v_max_i32_e32 v64, -4, v64
	v_cndmask_b32_e32 v66, v68, v229, vcc
	v_min_i32_e32 v65, s43, v65
	v_add_u32_e32 v64, 4, v64
	v_min_u32_e32 v67, s43, v64
	v_lshl_add_u32 v64, v65, 4, v66
	v_ashrrev_i32_e32 v65, 31, v64
	v_lshl_add_u32 v66, v67, 4, v66
	v_lshrrev_b32_e32 v243, 8, v64
	v_and_b32_e32 v244, 15, v64
	v_lshlrev_b32_e32 v243, 18, v243
	v_lshl_or_b32 v243, v244, 11, v243
	v_bfe_u32 v244, v64, 6, 2
	v_lshl_or_b32 v243, v244, 9, v243
	v_bfe_u32 v244, v64, 4, 2
	v_lshl_or_b32 v64, v244, 5, v243
	v_mov_b32_e32 v65, 0
	v_ashrrev_i32_e32 v67, 31, v66
	v_lshl_add_u64 v[64:65], v[154:155], 0, v[64:65]
	v_lshrrev_b32_e32 v243, 8, v66
	v_and_b32_e32 v244, 15, v66
	v_lshlrev_b32_e32 v243, 18, v243
	v_lshl_or_b32 v243, v244, 11, v243
	v_bfe_u32 v244, v66, 6, 2
	v_lshl_or_b32 v243, v244, 9, v243
	v_bfe_u32 v244, v66, 4, 2
	v_lshl_or_b32 v66, v244, 5, v243
	v_mov_b32_e32 v67, 0
	v_lshl_add_u64 v[66:67], v[154:155], 0, v[66:67]
	global_load_dwordx4 v[124:127], v[64:65], off
	global_load_dwordx4 v[120:123], v[64:65], off offset:16
	global_load_dwordx4 v[116:119], v[66:67], off
	global_load_dwordx4 v[112:115], v[66:67], off offset:16
	v_add_u32_e32 v65, s23, v232
	v_cndmask_b32_e32 v64, v68, v230, vcc
	v_cndmask_b32_e32 v66, v65, v69, vcc
	v_ashrrev_i32_e32 v65, 31, v64
	v_ashrrev_i32_e32 v66, 2, v66
	v_lshlrev_b64 v[64:65], s44, v[64:65]
	v_ashrrev_i32_e32 v67, 31, v66
	v_lshl_add_u64 v[64:65], v[64:65], 0, v[66:67]
	v_lshlrev_b64 v[64:65], 9, v[64:65]
	v_lshl_add_u64 v[78:79], v[158:159], 0, v[64:65]
	s_mov_b32 s0, s10
	s_mov_b32 s1, s46
	global_load_dwordx2 v[64:65], v[78:79], off
	global_load_dwordx2 v[66:67], v[78:79], off offset:512
	global_load_dwordx2 v[68:69], v[78:79], off offset:128
	global_load_dwordx2 v[70:71], v[78:79], off offset:640
	global_load_dwordx2 v[72:73], v[78:79], off offset:256
	global_load_dwordx2 v[74:75], v[78:79], off offset:768
	global_load_dwordx2 v[76:77], v[78:79], off offset:384
	s_nop 0
	global_load_dwordx2 v[78:79], v[78:79], off offset:896
	ds_read_b128 v[184:187], v228 offset:6144
	ds_read_b128 v[188:191], v228 offset:7168
	s_waitcnt vmcnt(23) lgkmcnt(1)
	v_mfma_f32_16x16x32_bf16 v[96:99], v[96:99], v[184:187], 0
	v_ashrrev_i32_e32 v162, 4, v162
	s_sub_i32 s0, s1, 64
	v_add_u32_e32 v162, s11, v162
	s_waitcnt vmcnt(22) lgkmcnt(0)
	v_mfma_f32_16x16x32_bf16 v[96:99], v[100:103], v[188:191], v[96:99]
	v_lshl_add_u32 v162, v162, 3, s0
	v_mov_b32_e32 v236, v144
	s_waitcnt vmcnt(21)
; __device__ __forceinline__ void attn_step(int ks, const KVB& b, int L16, int r, int i0, int iq, int lane,
;                                           const bf16x8* qs, f32x4 (&o)[4], float& mrun, float& lrun) {
;   asm volatile("" : "+v"(lane), "+v"(iq));
;   asm volatile("" : "+s"(r), "+s"(i0));
;   const int quad = lane >> 4;
;   bf16x8 qB0 = qs[0], qB1 = qs[64];
;   int cV, sV; attn_desc(ks, quad, r, i0, cV, sV);
;   int D = ks < 12 ? 4 : (ks < 18 ? 16 : 64);
;   f32x4 z = {0.f, 0.f, 0.f, 0.f};
;   f32x4 sa = __builtin_amdgcn_mfma_f32_16x16x32_bf16(b.k0, qB0, z, 0, 0, 0);
;   sa = __builtin_amdgcn_mfma_f32_16x16x32_bf16(b.k1, qB1, sa, 0, 0, 0);
;   f32x4 sb = __builtin_amdgcn_mfma_f32_16x16x32_bf16(b.k2, qB0, z, 0, 0, 0);
;   sb = __builtin_amdgcn_mfma_f32_16x16x32_bf16(b.k3, qB1, sb, 0, 0, 0);
;   int jlo = max(iq - D + (cV < r ? 1 : 0), 0) - sV;
;   int jhi = min(iq + D - (cV > r ? 1 : 0), L16 - 1) - sV;
;   const float NINF = -__builtin_inff();
;   float s8[8];
;   float mt = -1e30f;
; #pragma unroll
;   for (int j = 0; j < 8; ++j) {
;     float sv = j < 4 ? sa[j] : sb[j - 4];
;     sv = (j >= jlo && j <= jhi) ? sv : NINF;
;     s8[j] = sv;
;     mt = fmaxf(mt, sv);
;   }
;   mt = fmaxf(mt, __shfl_xor(mt, 16));
;   mt = fmaxf(mt, __shfl_xor(mt, 32));
;   float mnew = fmaxf(mrun, mt);
;   float alpha = __builtin_amdgcn_exp2f(mrun - mnew);
;   mrun = mnew;
;   float ps = 0.f;
;   float p8[8];
; #pragma unroll
;   for (int j = 0; j < 8; ++j) { p8[j] = __builtin_amdgcn_exp2f(s8[j] - mnew); ps += p8[j]; }
;   lrun = lrun * alpha + ps;
;   union { uint4 u; bf16x8 v; } pb;
;   pb.u = make_uint4(pack2(p8[0], p8[1]), pack2(p8[2], p8[3]), pack2(p8[4], p8[5]), pack2(p8[6], p8[7]));
; #pragma unroll
;   for (int dt = 0; dt < 4; ++dt) { o[dt][0] *= alpha; o[dt][1] *= alpha; o[dt][2] *= alpha; o[dt][3] *= alpha; }
;   o[0] = __builtin_amdgcn_mfma_f32_16x16x32_bf16(b.v0, pb.v, o[0], 0, 0, 0);
;   o[1] = __builtin_amdgcn_mfma_f32_16x16x32_bf16(b.v1, pb.v, o[1], 0, 0, 0);
;   o[2] = __builtin_amdgcn_mfma_f32_16x16x32_bf16(b.v2, pb.v, o[2], 0, 0, 0);
;   o[3] = __builtin_amdgcn_mfma_f32_16x16x32_bf16(b.v3, pb.v, o[3], 0, 0, 0);
; }
; template <int NT>
; __device__ void attn_unitN(const P& p, int u) {
;     ...
;   for (int kk = 0; kk < 5; ++kk) {
;     int e0 = 18 + NT * kk, ks = 18 + kk;
; #pragma unroll
;     for (int t = 0; t < NT; t += 2) {
	v_mfma_f32_16x16x32_bf16 v[100:103], v[104:107], v[184:187], 0
	v_subrev_u32_e32 v104, 64, v164
	v_add_u32_e32 v105, 64, v164
	v_max_i32_e32 v104, 0, v104
	v_min_i32_e32 v105, s43, v105
	v_sub_u32_e32 v104, v104, v162
	v_sub_u32_e32 v105, v105, v162
	v_cmp_lt_i32_e32 vcc, 0, v104
	v_cmp_gt_i32_e64 s[0:1], 0, v105
	s_or_b64 vcc, vcc, s[0:1]
	v_cndmask_b32_e32 v96, v96, v219, vcc
	v_cmp_lt_i32_e32 vcc, 1, v104
	v_cmp_gt_i32_e64 s[0:1], 1, v105
	s_or_b64 vcc, vcc, s[0:1]
	v_cndmask_b32_e32 v97, v97, v219, vcc
	v_cmp_lt_i32_e32 vcc, 2, v104
	v_cmp_gt_i32_e64 s[0:1], 2, v105
	s_or_b64 vcc, vcc, s[0:1]
	s_waitcnt vmcnt(20)
	v_mfma_f32_16x16x32_bf16 v[100:103], v[108:111], v[188:191], v[100:103]
	v_cndmask_b32_e32 v98, v98, v219, vcc
	v_cmp_lt_i32_e32 vcc, 3, v104
	v_cmp_gt_i32_e64 s[0:1], 3, v105
	s_or_b64 vcc, vcc, s[0:1]
	v_cndmask_b32_e32 v99, v99, v219, vcc
	v_cmp_lt_i32_e32 vcc, 4, v104
	v_cmp_gt_i32_e64 s[0:1], 4, v105
	s_or_b64 vcc, vcc, s[0:1]
	v_cndmask_b32_e32 v100, v100, v219, vcc
	v_cmp_lt_i32_e32 vcc, 5, v104
	v_cmp_gt_i32_e64 s[0:1], 5, v105
	s_or_b64 vcc, vcc, s[0:1]
	v_cndmask_b32_e32 v101, v101, v219, vcc
	v_cmp_lt_i32_e32 vcc, 6, v104
	v_cmp_gt_i32_e64 s[0:1], 6, v105
	s_or_b64 vcc, vcc, s[0:1]
	v_max3_f32 v106, v96, s41, v97
	v_cndmask_b32_e32 v102, v102, v219, vcc
	v_cmp_lt_i32_e32 vcc, 7, v104
	v_cmp_gt_i32_e64 s[0:1], 7, v105
	v_max3_f32 v106, v106, v98, v99
	s_or_b64 vcc, vcc, s[0:1]
	v_max3_f32 v106, v106, v100, v101
	v_cndmask_b32_e32 v103, v103, v219, vcc
	v_max3_f32 v104, v106, v102, v103
	ds_bpermute_b32 v105, v233, v104
	s_min_i32 s0, s22, 34
	s_add_i32 s0, s0, -15
	s_ashr_i32 s1, s0, 31
	s_lshr_b32 s1, s1, 30
	s_waitcnt lgkmcnt(0)
	v_max_f32_e32 v105, v105, v105
	v_max_f32_e32 v104, v104, v105
	ds_bpermute_b32 v105, v234, v104
	s_add_i32 s1, s0, s1
	s_ashr_i32 s22, s1, 2
	s_and_b32 s1, s1, 0x3ffffffc
	s_sub_i32 s0, s0, s1
	s_waitcnt lgkmcnt(0)
	v_max3_f32 v184, v235, v104, v105
	v_sub_f32_e32 v96, v96, v184
	v_exp_f32_e32 v162, v96
	v_sub_f32_e32 v96, v97, v184
	v_exp_f32_e32 v164, v96
	v_sub_f32_e32 v96, v98, v184
	v_exp_f32_e32 v166, v96
	v_sub_f32_e32 v96, v99, v184
	v_exp_f32_e32 v168, v96
	v_sub_f32_e32 v96, v100, v184
	v_exp_f32_e32 v170, v96
	v_sub_f32_e32 v96, v101, v184
	v_exp_f32_e32 v172, v96
	v_sub_f32_e32 v96, v102, v184
	v_exp_f32_e32 v174, v96
	v_sub_f32_e32 v96, v103, v184
	v_exp_f32_e32 v176, v96
	v_pk_add_f32 v[96:97], v[162:163], 0 op_sel_hi:[1,0]
	v_sub_f32_e32 v104, v235, v184
	v_pk_add_f32 v[96:97], v[164:165], v[96:97]
	v_exp_f32_e32 v178, v104
	v_pk_add_f32 v[96:97], v[166:167], v[96:97]
	s_lshl_b32 s0, s0, 2
	v_pk_add_f32 v[96:97], v[168:169], v[96:97]
	s_add_i32 s23, s22, 18
	v_pk_add_f32 v[96:97], v[170:171], v[96:97]
	s_add_i32 s0, s0, s42
	v_pk_add_f32 v[96:97], v[172:173], v[96:97]
	s_cmp_gt_u32 s22, 0xffffffed
	v_pk_add_f32 v[96:97], v[174:175], v[96:97]
	v_cvt_pk_bf16_f32 v98, v171, v173
	v_pk_add_f32 v[100:101], v[176:177], v[96:97]
	v_mov_b32_e32 v96, v179
	v_pk_mul_f32 v[34:35], v[34:35], v[96:97] op_sel_hi:[1,0]
	v_pk_mul_f32 v[32:33], v[32:33], v[96:97] op_sel_hi:[1,0]
	v_pk_mul_f32 v[26:27], v[26:27], v[96:97] op_sel_hi:[1,0]
	v_pk_mul_f32 v[24:25], v[24:25], v[96:97] op_sel_hi:[1,0]
	v_pk_mul_f32 v[22:23], v[22:23], v[96:97] op_sel_hi:[1,0]
	v_pk_mul_f32 v[20:21], v[20:21], v[96:97] op_sel_hi:[1,0]
	v_pk_mul_f32 v[14:15], v[14:15], v[96:97] op_sel_hi:[1,0]
	v_pk_mul_f32 v[12:13], v[12:13], v[96:97] op_sel_hi:[1,0]
	v_cvt_pk_bf16_f32 v96, v163, v165
	v_cvt_pk_bf16_f32 v97, v167, v169
	v_cvt_pk_bf16_f32 v99, v175, v177
	s_cselect_b64 vcc, -1, 0
	s_lshl_b32 s1, s23, 3
	v_mfma_f32_16x16x32_bf16 v[32:35], v[128:131], v[96:99], v[32:35]
	v_mul_f32_e64 v18, v18, v178
	v_mul_f32_e64 v19, v19, v178
	v_pk_mul_f32 v[16:17], v[16:17], v[178:179] op_sel_hi:[1,0]
	v_pk_mul_f32 v[10:11], v[10:11], v[178:179] op_sel_hi:[1,0]
	v_mfma_f32_16x16x32_bf16 v[24:27], v[132:135], v[96:99], v[24:27]
	v_mul_f32_e64 v8, v8, v178
	v_mul_f32_e64 v9, v9, v178
	s_add_i32 s1, s1, s47
	s_lshl_b32 s22, s23, 5
	v_mfma_f32_16x16x32_bf16 v[20:23], v[136:139], v[96:99], v[20:23]
	v_mul_f32_e64 v6, v6, v178
	v_mul_f32_e64 v7, v7, v178
	v_pk_mul_f32 v[4:5], v[4:5], v[178:179] op_sel_hi:[1,0]
	v_pk_mul_f32 v[2:3], v[2:3], v[178:179] op_sel_hi:[1,0]
	v_mfma_f32_16x16x32_bf16 v[12:15], v[140:143], v[96:99], v[12:15]
	v_cvt_pk_bf16_f32 v96, v162, v164
	v_cvt_pk_bf16_f32 v97, v166, v168
	v_cvt_pk_bf16_f32 v98, v170, v172
	v_cvt_pk_bf16_f32 v99, v174, v176
	v_pk_mul_f32 v[0:1], v[0:1], v[178:179] op_sel_hi:[1,0]
	v_pk_fma_f32 v[156:157], v[156:157], v[178:179], v[100:101]
	s_waitcnt vmcnt(18)
	v_mfma_f32_16x16x32_bf16 v[16:19], v[80:83], v[96:99], v[16:19]
	v_add_u32_e32 v80, s22, v231
	s_add_i32 s11, s11, 4
	s_cmp_lg_u32 s11, 20
	s_waitcnt vmcnt(16)
	v_mfma_f32_16x16x32_bf16 v[8:11], v[84:87], v[96:99], v[8:11]
	v_mov_b32_e32 v85, s1
	v_cndmask_b32_e32 v80, v80, v85, vcc
	v_add_u32_e32 v80, v80, v227
	v_mov_b32_e32 v84, s0
	v_max_i32_e32 v81, 0, v80
	v_max_i32_e32 v80, -4, v80
	v_cndmask_b32_e32 v82, v84, v229, vcc
	v_min_i32_e32 v81, s43, v81
	v_add_u32_e32 v80, 4, v80
	v_min_u32_e32 v83, s43, v80
	v_lshl_add_u32 v80, v81, 4, v82
	v_ashrrev_i32_e32 v81, 31, v80
	v_lshl_add_u32 v82, v83, 4, v82
	v_lshrrev_b32_e32 v243, 8, v80
	v_and_b32_e32 v244, 15, v80
	v_lshlrev_b32_e32 v243, 18, v243
	v_lshl_or_b32 v243, v244, 11, v243
	v_bfe_u32 v244, v80, 6, 2
	v_lshl_or_b32 v243, v244, 9, v243
	v_bfe_u32 v244, v80, 4, 2
	v_lshl_or_b32 v80, v244, 5, v243
	v_mov_b32_e32 v81, 0
	v_ashrrev_i32_e32 v83, 31, v82
	v_lshl_add_u64 v[80:81], v[154:155], 0, v[80:81]
	v_lshrrev_b32_e32 v243, 8, v82
	v_and_b32_e32 v244, 15, v82
	v_lshlrev_b32_e32 v243, 18, v243
	v_lshl_or_b32 v243, v244, 11, v243
	v_bfe_u32 v244, v82, 6, 2
	v_lshl_or_b32 v243, v244, 9, v243
	v_bfe_u32 v244, v82, 4, 2
	v_lshl_or_b32 v82, v244, 5, v243
	v_mov_b32_e32 v83, 0
	s_waitcnt vmcnt(14)
; __device__ __forceinline__ void attn_step(int ks, const KVB& b, int L16, int r, int i0, int iq, int lane,
;                                           const bf16x8* qs, f32x4 (&o)[4], float& mrun, float& lrun) {
;     ...
;   o[0] = __builtin_amdgcn_mfma_f32_16x16x32_bf16(b.v0, pb.v, o[0], 0, 0, 0);
;   o[1] = __builtin_amdgcn_mfma_f32_16x16x32_bf16(b.v1, pb.v, o[1], 0, 0, 0);
;   o[2] = __builtin_amdgcn_mfma_f32_16x16x32_bf16(b.v2, pb.v, o[2], 0, 0, 0);
;   o[3] = __builtin_amdgcn_mfma_f32_16x16x32_bf16(b.v3, pb.v, o[3], 0, 0, 0);
; template <int NT>
; __device__ void attn_unitN(const P& p, int u) {
;     ...
;       { int f = min(e0 + t + 2, EMAX) - 18;
;         bA = attn_load(18 + f / NT, kbase, vbase, L16, rb + RS * (f % NT), i0, lane); }
;       attn_step(ks, bB, L16, rb + RS * (t + 1), i0, iq, lane, qs + (t + 1) * 128, o[t + 1], mrun[t + 1], lrun[t + 1]);
;       { int f = min(e0 + t + 3, EMAX) - 18;
;         bB = attn_load(18 + f / NT, kbase, vbase, L16, rb + RS * (f % NT), i0, lane); }
;     }
	v_mfma_f32_16x16x32_bf16 v[4:7], v[88:91], v[96:99], v[4:7]
	v_lshl_add_u64 v[82:83], v[154:155], 0, v[82:83]
	v_mov_b32_e32 v235, v184
	v_mov_b32_e32 v143, v182
	s_waitcnt vmcnt(12)
	v_mfma_f32_16x16x32_bf16 v[0:3], v[92:95], v[96:99], v[0:3]
	global_load_dwordx4 v[108:111], v[80:81], off
	global_load_dwordx4 v[104:107], v[80:81], off offset:16
	global_load_dwordx4 v[100:103], v[82:83], off
	global_load_dwordx4 v[96:99], v[82:83], off offset:16
	v_add_u32_e32 v81, s22, v232
	v_cndmask_b32_e32 v80, v84, v230, vcc
	v_cndmask_b32_e32 v82, v81, v85, vcc
	v_ashrrev_i32_e32 v81, 31, v80
	v_ashrrev_i32_e32 v82, 2, v82
	v_lshlrev_b64 v[80:81], s44, v[80:81]
	v_ashrrev_i32_e32 v83, 31, v82
	v_lshl_add_u64 v[80:81], v[80:81], 0, v[82:83]
	v_lshlrev_b64 v[80:81], 9, v[80:81]
	v_lshl_add_u64 v[94:95], v[158:159], 0, v[80:81]
	global_load_dwordx2 v[80:81], v[94:95], off
	global_load_dwordx2 v[82:83], v[94:95], off offset:512
	global_load_dwordx2 v[84:85], v[94:95], off offset:128
	global_load_dwordx2 v[86:87], v[94:95], off offset:640
	global_load_dwordx2 v[88:89], v[94:95], off offset:256
	global_load_dwordx2 v[90:91], v[94:95], off offset:768
	global_load_dwordx2 v[92:93], v[94:95], off offset:384
	s_nop 0
	global_load_dwordx2 v[94:95], v[94:95], off offset:896
	s_cbranch_scc1 .LBB0_267
; template <int NT>
; __device__ void attn_unitN(const P& p, int u) {
;     ...
;   u16* omix = (u16*)(p.ws + OFF_OMIX);
; #pragma unroll
;   for (int t = 0; t < NT; ++t) {
;     float l = lrun[t];
;     l += __shfl_xor(l, 16);
;     l += __shfl_xor(l, 32);
;     float inv = 1.f / l;
;     u16* op = omix + (size_t)(seq0 + rb + RS * t + 16 * iq) * 1024 + h * 64 + quad * 4;
; #pragma unroll
;     for (int dt = 0; dt < 4; ++dt) {
;       uint2 w; w.x = pack2(o[t][dt][0] * inv, o[t][dt][1] * inv); w.y = pack2(o[t][dt][2] * inv, o[t][dt][3] * inv);
;       *(uint2*)(op + dt * 16) = w;
;     }
;   }
	s_waitcnt vmcnt(19)
	ds_bpermute_b32 v64, v233, v161
	s_lshl_b32 s0, s45, 1
	s_waitcnt vmcnt(18)
	v_lshrrev_b32_e32 v66, 1, v224
	s_add_u32 s0, s34, s0
	v_and_b32_e32 v144, 24, v66
	s_waitcnt lgkmcnt(0)
	v_add_f32_e32 v67, v161, v64
	s_waitcnt vmcnt(17)
	ds_bpermute_b32 v68, v234, v67
	s_addc_u32 s1, s35, 0
	v_lshlrev_b64 v[64:65], 11, v[152:153]
	s_add_i32 s3, s3, s30
	s_cmpk_lt_i32 s3, 0x2000
	s_waitcnt lgkmcnt(0)
	v_add_f32_e32 v68, v67, v68
	v_div_scale_f32 v69, s[4:5], v68, v68, 1.0
	s_waitcnt vmcnt(16)
	v_rcp_f32_e32 v70, v69
	v_div_scale_f32 v71, vcc, 1.0, v68, 1.0
	v_lshl_add_u64 v[66:67], s[0:1], 0, v[144:145]
	s_waitcnt vmcnt(15)
	v_fma_f32 v72, -v69, v70, 1.0
	v_fmac_f32_e32 v70, v72, v70
	v_mul_f32_e32 v72, v71, v70
	v_fma_f32 v73, -v69, v72, v71
	v_fmac_f32_e32 v72, v73, v70
	v_fma_f32 v69, -v69, v72, v71
	v_div_fmas_f32 v69, v69, v70, v72
	v_div_fixup_f32 v68, v69, v68, 1.0
	v_pk_mul_f32 v[56:57], v[56:57], v[68:69] op_sel_hi:[1,0]
	v_pk_mul_f32 v[58:59], v[58:59], v[68:69] op_sel_hi:[1,0]
	v_cvt_pk_bf16_f32 v56, v56, v57
	v_cvt_pk_bf16_f32 v57, v58, v59
	ds_bpermute_b32 v58, v233, v160
	v_lshl_add_u64 v[64:65], v[66:67], 0, v[64:65]
	global_store_dwordx2 v[64:65], v[56:57], off offset:32
	v_pk_mul_f32 v[52:53], v[52:53], v[68:69] op_sel_hi:[1,0]
	v_pk_mul_f32 v[54:55], v[54:55], v[68:69] op_sel_hi:[1,0]
	s_waitcnt lgkmcnt(0)
	v_add_f32_e32 v56, v160, v58
	ds_bpermute_b32 v57, v234, v56
	v_cvt_pk_bf16_f32 v52, v52, v53
	v_cvt_pk_bf16_f32 v53, v54, v55
	global_store_dwordx2 v[64:65], v[52:53], off offset:64
	v_pk_mul_f32 v[44:45], v[44:45], v[68:69] op_sel_hi:[1,0]
	s_waitcnt lgkmcnt(0)
	v_add_f32_e32 v52, v56, v57
	v_div_scale_f32 v53, s[0:1], v52, v52, 1.0
	v_rcp_f32_e32 v54, v53
	v_pk_mul_f32 v[46:47], v[46:47], v[68:69] op_sel_hi:[1,0]
	v_cvt_pk_bf16_f32 v44, v44, v45
	v_cvt_pk_bf16_f32 v45, v46, v47
	global_store_dwordx2 v[64:65], v[44:45], off offset:96
	v_fma_f32 v44, -v53, v54, 1.0
	v_fmac_f32_e32 v54, v44, v54
	v_div_scale_f32 v44, vcc, 1.0, v52, 1.0
	v_mul_f32_e32 v45, v44, v54
	v_fma_f32 v46, -v53, v45, v44
	v_fmac_f32_e32 v45, v46, v54
	v_fma_f32 v44, -v53, v45, v44
	v_div_fmas_f32 v44, v44, v54, v45
	v_div_fixup_f32 v44, v44, v52, 1.0
	v_pk_mul_f32 v[40:41], v[40:41], v[44:45] op_sel_hi:[1,0]
	v_pk_mul_f32 v[42:43], v[42:43], v[44:45] op_sel_hi:[1,0]
	v_cvt_pk_bf16_f32 v40, v40, v41
	v_cvt_pk_bf16_f32 v41, v42, v43
	ds_bpermute_b32 v42, v233, v157
	v_lshlrev_b64 v[46:47], 11, v[150:151]
	v_lshl_add_u64 v[46:47], v[66:67], 0, v[46:47]
	global_store_dwordx2 v[46:47], v[40:41], off offset:32
	v_pk_mul_f32 v[36:37], v[36:37], v[44:45] op_sel_hi:[1,0]
	s_waitcnt lgkmcnt(0)
	v_add_f32_e32 v40, v157, v42
	ds_bpermute_b32 v41, v234, v40
	v_pk_mul_f32 v[38:39], v[38:39], v[44:45] op_sel_hi:[1,0]
	v_cvt_pk_bf16_f32 v36, v36, v37
	v_cvt_pk_bf16_f32 v37, v38, v39
	global_store_dwordx2 v[46:47], v[36:37], off offset:64
	s_waitcnt lgkmcnt(0)
	v_add_f32_e32 v36, v40, v41
	v_div_scale_f32 v37, s[0:1], v36, v36, 1.0
	v_rcp_f32_e32 v38, v37
	v_pk_mul_f32 v[28:29], v[28:29], v[44:45] op_sel_hi:[1,0]
	v_pk_mul_f32 v[30:31], v[30:31], v[44:45] op_sel_hi:[1,0]
	v_cvt_pk_bf16_f32 v28, v28, v29
	v_cvt_pk_bf16_f32 v29, v30, v31
	global_store_dwordx2 v[46:47], v[28:29], off offset:96
	v_fma_f32 v28, -v37, v38, 1.0
	v_fmac_f32_e32 v38, v28, v38
	v_div_scale_f32 v28, vcc, 1.0, v36, 1.0
	v_mul_f32_e32 v29, v28, v38
	v_fma_f32 v30, -v37, v29, v28
	v_fmac_f32_e32 v29, v30, v38
	v_fma_f32 v28, -v37, v29, v28
	v_div_fmas_f32 v28, v28, v38, v29
	v_div_fixup_f32 v28, v28, v36, 1.0
	v_pk_mul_f32 v[24:25], v[24:25], v[28:29] op_sel_hi:[1,0]
	v_pk_mul_f32 v[26:27], v[26:27], v[28:29] op_sel_hi:[1,0]
	v_cvt_pk_bf16_f32 v24, v24, v25
	v_cvt_pk_bf16_f32 v25, v26, v27
	ds_bpermute_b32 v26, v233, v156
	v_lshlrev_b64 v[30:31], 11, v[148:149]
	v_lshl_add_u64 v[30:31], v[66:67], 0, v[30:31]
	global_store_dwordx2 v[30:31], v[24:25], off offset:32
	v_pk_mul_f32 v[20:21], v[20:21], v[28:29] op_sel_hi:[1,0]
	s_waitcnt lgkmcnt(0)
	v_add_f32_e32 v24, v156, v26
	ds_bpermute_b32 v25, v234, v24
	v_pk_mul_f32 v[22:23], v[22:23], v[28:29] op_sel_hi:[1,0]
	v_cvt_pk_bf16_f32 v20, v20, v21
	v_cvt_pk_bf16_f32 v21, v22, v23
	global_store_dwordx2 v[30:31], v[20:21], off offset:64
	s_waitcnt lgkmcnt(0)
	v_add_f32_e32 v20, v24, v25
	v_div_scale_f32 v21, s[0:1], v20, v20, 1.0
	v_rcp_f32_e32 v22, v21
	v_pk_mul_f32 v[12:13], v[12:13], v[28:29] op_sel_hi:[1,0]
	v_pk_mul_f32 v[14:15], v[14:15], v[28:29] op_sel_hi:[1,0]
	v_cvt_pk_bf16_f32 v12, v12, v13
	v_cvt_pk_bf16_f32 v13, v14, v15
	global_store_dwordx2 v[30:31], v[12:13], off offset:96
	v_fma_f32 v12, -v21, v22, 1.0
	v_fmac_f32_e32 v22, v12, v22
	v_div_scale_f32 v12, vcc, 1.0, v20, 1.0
	v_mul_f32_e32 v13, v12, v22
	v_fma_f32 v14, -v21, v13, v12
	v_fmac_f32_e32 v13, v14, v22
	v_fma_f32 v12, -v21, v13, v12
	v_div_fmas_f32 v12, v12, v22, v13
	v_div_fixup_f32 v12, v12, v20, 1.0
	v_pk_mul_f32 v[60:61], v[60:61], v[68:69] op_sel_hi:[1,0]
	v_pk_mul_f32 v[62:63], v[62:63], v[68:69] op_sel_hi:[1,0]
	v_pk_mul_f32 v[48:49], v[48:49], v[44:45] op_sel_hi:[1,0]
	v_pk_mul_f32 v[50:51], v[50:51], v[44:45] op_sel_hi:[1,0]
	v_pk_mul_f32 v[32:33], v[32:33], v[28:29] op_sel_hi:[1,0]
	v_pk_mul_f32 v[34:35], v[34:35], v[28:29] op_sel_hi:[1,0]
	v_lshlrev_b64 v[14:15], 11, v[146:147]
	v_pk_mul_f32 v[16:17], v[16:17], v[12:13] op_sel_hi:[1,0]
	v_pk_mul_f32 v[18:19], v[18:19], v[12:13] op_sel_hi:[1,0]
	v_pk_mul_f32 v[8:9], v[8:9], v[12:13] op_sel_hi:[1,0]
	v_pk_mul_f32 v[10:11], v[10:11], v[12:13] op_sel_hi:[1,0]
	v_pk_mul_f32 v[4:5], v[4:5], v[12:13] op_sel_hi:[1,0]
	v_pk_mul_f32 v[6:7], v[6:7], v[12:13] op_sel_hi:[1,0]
	v_pk_mul_f32 v[0:1], v[0:1], v[12:13] op_sel_hi:[1,0]
	v_pk_mul_f32 v[2:3], v[2:3], v[12:13] op_sel_hi:[1,0]
	v_cvt_pk_bf16_f32 v60, v60, v61
	v_cvt_pk_bf16_f32 v61, v62, v63
	v_cvt_pk_bf16_f32 v48, v48, v49
	v_cvt_pk_bf16_f32 v49, v50, v51
	v_cvt_pk_bf16_f32 v32, v32, v33
	v_cvt_pk_bf16_f32 v33, v34, v35
	v_lshl_add_u64 v[14:15], v[66:67], 0, v[14:15]
	v_cvt_pk_bf16_f32 v16, v16, v17
	v_cvt_pk_bf16_f32 v17, v18, v19
	v_cvt_pk_bf16_f32 v8, v8, v9
	v_cvt_pk_bf16_f32 v9, v10, v11
	v_cvt_pk_bf16_f32 v4, v4, v5
	v_cvt_pk_bf16_f32 v5, v6, v7
	v_cvt_pk_bf16_f32 v0, v0, v1
	v_cvt_pk_bf16_f32 v1, v2, v3
	global_store_dwordx2 v[64:65], v[60:61], off
	global_store_dwordx2 v[46:47], v[48:49], off
	global_store_dwordx2 v[30:31], v[32:33], off
	global_store_dwordx2 v[14:15], v[16:17], off
	global_store_dwordx2 v[14:15], v[8:9], off offset:32
	global_store_dwordx2 v[14:15], v[4:5], off offset:64
	global_store_dwordx2 v[14:15], v[0:1], off offset:96
	s_cbranch_scc1 .LBB0_231
